# v2 + s_setprio toggles removed from the 12 GEMM K-loops (partner wave load segment no longer starved)
# speedup vs baseline: 1.0084x; 1.0038x over previous
.LBB0_38:
	s_add_u32 s10, s8, 0x100
	s_addc_u32 s11, s9, 0
	s_add_i32 s48, 0, 0x10000
	s_cmp_eq_u32 s22, 40
	s_cselect_b32 s15, s1, s11
	s_cselect_b32 s14, s0, s10
	s_cselect_b32 s13, s37, s90
	s_cselect_b32 s12, s36, s21
	s_add_i32 s49, 0, 0x14000
	v_add_u32_e32 v154, s48, v143
	v_add_u32_e32 v158, s49, v143
	ds_read_b128 v[138:141], v154
	ds_read_b128 v[146:149], v154 offset:1024
	ds_read_b128 v[150:153], v154 offset:2048
	ds_read_b128 v[154:157], v154 offset:3072
	ds_read_b128 v[162:165], v158
	ds_read_b128 v[166:169], v158 offset:1024
	ds_read_b128 v[170:173], v158 offset:2048
	ds_read_b128 v[174:177], v158 offset:3072
	v_lshl_add_u64 v[158:159], s[8:9], 0, v[136:137]
	s_add_i32 m0, s29, 0xc000
	ds_read_b128 v[178:181], v145
	ds_read_b128 v[182:185], v145 offset:1024
	ds_read_b128 v[186:189], v145 offset:2048
	ds_read_b128 v[190:193], v145 offset:3072
	ds_read_b128 v[194:197], v145 offset:4096
	ds_read_b128 v[198:201], v145 offset:5120
	ds_read_b128 v[202:205], v145 offset:6144
	ds_read_b128 v[206:209], v145 offset:7168
	global_load_lds_dwordx4 v[158:159], off
	v_lshl_add_u64 v[158:159], s[8:9], 0, v[134:135]
	s_add_i32 m0, s29, 0xe000
	s_nop 0
	global_load_lds_dwordx4 v[158:159], off
	s_waitcnt vmcnt(8)
	s_waitcnt lgkmcnt(0)
	s_barrier
	s_waitcnt lgkmcnt(0)
	v_mfma_f32_16x16x32_bf16 v[124:127], v[138:141], v[178:181], v[124:127]
	v_mfma_f32_16x16x32_bf16 v[120:123], v[150:153], v[178:181], v[120:123]
	v_mfma_f32_16x16x32_bf16 v[108:111], v[138:141], v[186:189], v[108:111]
	v_mfma_f32_16x16x32_bf16 v[104:107], v[150:153], v[186:189], v[104:107]
	v_mfma_f32_16x16x32_bf16 v[92:95], v[138:141], v[194:197], v[92:95]
	v_mfma_f32_16x16x32_bf16 v[88:91], v[150:153], v[194:197], v[88:91]
	v_mfma_f32_16x16x32_bf16 v[76:79], v[138:141], v[202:205], v[76:79]
	v_mfma_f32_16x16x32_bf16 v[72:75], v[150:153], v[202:205], v[72:75]
	v_mfma_f32_16x16x32_bf16 v[124:127], v[146:149], v[182:185], v[124:127]
	v_mfma_f32_16x16x32_bf16 v[120:123], v[154:157], v[182:185], v[120:123]
	v_mfma_f32_16x16x32_bf16 v[108:111], v[146:149], v[190:193], v[108:111]
	v_mfma_f32_16x16x32_bf16 v[104:107], v[154:157], v[190:193], v[104:107]
	v_mfma_f32_16x16x32_bf16 v[92:95], v[146:149], v[198:201], v[92:95]
	v_mfma_f32_16x16x32_bf16 v[88:91], v[154:157], v[198:201], v[88:91]
	v_mfma_f32_16x16x32_bf16 v[76:79], v[146:149], v[206:209], v[76:79]
	v_mfma_f32_16x16x32_bf16 v[72:75], v[154:157], v[206:209], v[72:75]
	v_mfma_f32_16x16x32_bf16 v[116:119], v[162:165], v[178:181], v[116:119]
	v_mfma_f32_16x16x32_bf16 v[112:115], v[170:173], v[178:181], v[112:115]
	v_mfma_f32_16x16x32_bf16 v[100:103], v[162:165], v[186:189], v[100:103]
	v_mfma_f32_16x16x32_bf16 v[96:99], v[170:173], v[186:189], v[96:99]
	v_mfma_f32_16x16x32_bf16 v[84:87], v[162:165], v[194:197], v[84:87]
	v_mfma_f32_16x16x32_bf16 v[80:83], v[170:173], v[194:197], v[80:83]
	v_mfma_f32_16x16x32_bf16 v[68:71], v[162:165], v[202:205], v[68:71]
	v_mfma_f32_16x16x32_bf16 v[64:67], v[170:173], v[202:205], v[64:67]
	v_mfma_f32_16x16x32_bf16 v[116:119], v[166:169], v[182:185], v[116:119]
	v_mfma_f32_16x16x32_bf16 v[112:115], v[174:177], v[182:185], v[112:115]
	v_mfma_f32_16x16x32_bf16 v[100:103], v[166:169], v[190:193], v[100:103]
	v_mfma_f32_16x16x32_bf16 v[96:99], v[174:177], v[190:193], v[96:99]
	v_mfma_f32_16x16x32_bf16 v[84:87], v[166:169], v[198:201], v[84:87]
	v_mfma_f32_16x16x32_bf16 v[80:83], v[174:177], v[198:201], v[80:83]
	v_mfma_f32_16x16x32_bf16 v[68:71], v[166:169], v[206:209], v[68:71]
	v_mfma_f32_16x16x32_bf16 v[64:67], v[174:177], v[206:209], v[64:67]
	s_barrier
	s_add_i32 s8, s48, s28
	v_lshl_add_u64 v[158:159], s[12:13], 0, v[160:161]
	s_mov_b32 m0, s8
	ds_read_b128 v[178:181], v145 offset:16384
	ds_read_b128 v[182:185], v145 offset:17408
	ds_read_b128 v[186:189], v145 offset:18432
	ds_read_b128 v[190:193], v145 offset:19456
	ds_read_b128 v[194:197], v145 offset:20480
	ds_read_b128 v[198:201], v145 offset:21504
	ds_read_b128 v[202:205], v145 offset:22528
	ds_read_b128 v[206:209], v145 offset:23552
	global_load_lds_dwordx4 v[158:159], off
	s_add_i32 m0, s8, 0x2000
	s_add_u32 s8, s12, 0xb0000
	v_lshl_add_u64 v[210:211], s[12:13], 0, v[132:133]
	s_addc_u32 s9, s13, 0
	s_add_i32 s48, s49, s28
	global_load_lds_dwordx4 v[210:211], off
	v_lshl_add_u64 v[212:213], s[8:9], 0, v[160:161]
	s_mov_b32 m0, s48
	v_lshl_add_u64 v[214:215], s[14:15], 0, v[130:131]
	global_load_lds_dwordx4 v[212:213], off
	v_lshl_add_u64 v[212:213], s[8:9], 0, v[132:133]
	s_add_i32 m0, s48, 0x2000
	s_nop 0
	global_load_lds_dwordx4 v[212:213], off
	v_lshl_add_u64 v[212:213], s[14:15], 0, v[128:129]
	s_mov_b32 m0, s29
	s_nop 0
	global_load_lds_dwordx4 v[212:213], off
	s_mov_b32 m0, s30
	s_nop 0
	global_load_lds_dwordx4 v[214:215], off
	s_waitcnt vmcnt(8)
	s_waitcnt lgkmcnt(0)
	s_barrier
	s_waitcnt lgkmcnt(0)
	v_mfma_f32_16x16x32_bf16 v[60:63], v[138:141], v[178:181], v[60:63]
	v_mfma_f32_16x16x32_bf16 v[56:59], v[150:153], v[178:181], v[56:59]
	v_mfma_f32_16x16x32_bf16 v[44:47], v[138:141], v[186:189], v[44:47]
	v_mfma_f32_16x16x32_bf16 v[40:43], v[150:153], v[186:189], v[40:43]
	v_mfma_f32_16x16x32_bf16 v[28:31], v[138:141], v[194:197], v[28:31]
	v_mfma_f32_16x16x32_bf16 v[24:27], v[150:153], v[194:197], v[24:27]
	v_mfma_f32_16x16x32_bf16 v[12:15], v[138:141], v[202:205], v[12:15]
	v_mfma_f32_16x16x32_bf16 v[8:11], v[150:153], v[202:205], v[8:11]
	v_mfma_f32_16x16x32_bf16 v[60:63], v[146:149], v[182:185], v[60:63]
	v_mfma_f32_16x16x32_bf16 v[56:59], v[154:157], v[182:185], v[56:59]
	v_mfma_f32_16x16x32_bf16 v[44:47], v[146:149], v[190:193], v[44:47]
	v_mfma_f32_16x16x32_bf16 v[40:43], v[154:157], v[190:193], v[40:43]
	v_mfma_f32_16x16x32_bf16 v[28:31], v[146:149], v[198:201], v[28:31]
	v_mfma_f32_16x16x32_bf16 v[24:27], v[154:157], v[198:201], v[24:27]
	v_mfma_f32_16x16x32_bf16 v[12:15], v[146:149], v[206:209], v[12:15]
	v_mfma_f32_16x16x32_bf16 v[8:11], v[154:157], v[206:209], v[8:11]
	v_mfma_f32_16x16x32_bf16 v[52:55], v[162:165], v[178:181], v[52:55]
	v_mfma_f32_16x16x32_bf16 v[48:51], v[170:173], v[178:181], v[48:51]
	v_mfma_f32_16x16x32_bf16 v[36:39], v[162:165], v[186:189], v[36:39]
	v_mfma_f32_16x16x32_bf16 v[32:35], v[170:173], v[186:189], v[32:35]
	v_mfma_f32_16x16x32_bf16 v[20:23], v[162:165], v[194:197], v[20:23]
	v_mfma_f32_16x16x32_bf16 v[16:19], v[170:173], v[194:197], v[16:19]
	v_mfma_f32_16x16x32_bf16 v[4:7], v[162:165], v[202:205], v[4:7]
	v_mfma_f32_16x16x32_bf16 v[0:3], v[170:173], v[202:205], v[0:3]
	v_mfma_f32_16x16x32_bf16 v[52:55], v[166:169], v[182:185], v[52:55]
	v_mfma_f32_16x16x32_bf16 v[48:51], v[174:177], v[182:185], v[48:51]
	v_mfma_f32_16x16x32_bf16 v[36:39], v[166:169], v[190:193], v[36:39]
	v_mfma_f32_16x16x32_bf16 v[32:35], v[174:177], v[190:193], v[32:35]
	v_mfma_f32_16x16x32_bf16 v[20:23], v[166:169], v[198:201], v[20:23]
	v_mfma_f32_16x16x32_bf16 v[16:19], v[174:177], v[198:201], v[16:19]
	v_mfma_f32_16x16x32_bf16 v[4:7], v[166:169], v[206:209], v[4:7]
	v_mfma_f32_16x16x32_bf16 v[0:3], v[174:177], v[206:209], v[0:3]
	s_barrier
	s_add_i32 s48, 0, 0x18000
	s_add_i32 s49, 0, 0x1c000
	v_add_u32_e32 v154, s48, v143
	v_add_u32_e32 v174, s49, v143
	ds_read_b128 v[138:141], v154
	ds_read_b128 v[146:149], v154 offset:1024
	ds_read_b128 v[150:153], v154 offset:2048
	ds_read_b128 v[154:157], v154 offset:3072
	ds_read_b128 v[162:165], v174
	ds_read_b128 v[166:169], v174 offset:1024
	ds_read_b128 v[170:173], v174 offset:2048
	ds_read_b128 v[174:177], v174 offset:3072
	s_add_u32 s8, s14, 0xb0000
	s_addc_u32 s9, s15, 0
	s_mov_b32 m0, s31
	v_lshl_add_u64 v[216:217], s[8:9], 0, v[128:129]
	ds_read_b128 v[178:181], v145 offset:32768
	ds_read_b128 v[182:185], v145 offset:33792
	ds_read_b128 v[186:189], v145 offset:34816
	ds_read_b128 v[190:193], v145 offset:35840
	ds_read_b128 v[194:197], v145 offset:36864
	ds_read_b128 v[198:201], v145 offset:37888
	ds_read_b128 v[202:205], v145 offset:38912
	ds_read_b128 v[206:209], v145 offset:39936
	global_load_lds_dwordx4 v[216:217], off
	v_lshl_add_u64 v[216:217], s[8:9], 0, v[130:131]
	s_mov_b32 m0, s33
	s_nop 0
	global_load_lds_dwordx4 v[216:217], off
	s_waitcnt vmcnt(8)
	s_waitcnt lgkmcnt(0)
	s_barrier
	s_waitcnt lgkmcnt(0)
	v_mfma_f32_16x16x32_bf16 v[124:127], v[138:141], v[178:181], v[124:127]
	v_mfma_f32_16x16x32_bf16 v[120:123], v[150:153], v[178:181], v[120:123]
	v_mfma_f32_16x16x32_bf16 v[108:111], v[138:141], v[186:189], v[108:111]
	v_mfma_f32_16x16x32_bf16 v[104:107], v[150:153], v[186:189], v[104:107]
	v_mfma_f32_16x16x32_bf16 v[92:95], v[138:141], v[194:197], v[92:95]
	v_mfma_f32_16x16x32_bf16 v[88:91], v[150:153], v[194:197], v[88:91]
	v_mfma_f32_16x16x32_bf16 v[76:79], v[138:141], v[202:205], v[76:79]
	v_mfma_f32_16x16x32_bf16 v[72:75], v[150:153], v[202:205], v[72:75]
	v_mfma_f32_16x16x32_bf16 v[124:127], v[146:149], v[182:185], v[124:127]
	v_mfma_f32_16x16x32_bf16 v[120:123], v[154:157], v[182:185], v[120:123]
	v_mfma_f32_16x16x32_bf16 v[108:111], v[146:149], v[190:193], v[108:111]
	v_mfma_f32_16x16x32_bf16 v[104:107], v[154:157], v[190:193], v[104:107]
	v_mfma_f32_16x16x32_bf16 v[92:95], v[146:149], v[198:201], v[92:95]
	v_mfma_f32_16x16x32_bf16 v[88:91], v[154:157], v[198:201], v[88:91]
	v_mfma_f32_16x16x32_bf16 v[76:79], v[146:149], v[206:209], v[76:79]
	v_mfma_f32_16x16x32_bf16 v[72:75], v[154:157], v[206:209], v[72:75]
	v_mfma_f32_16x16x32_bf16 v[116:119], v[162:165], v[178:181], v[116:119]
	v_mfma_f32_16x16x32_bf16 v[112:115], v[170:173], v[178:181], v[112:115]
	v_mfma_f32_16x16x32_bf16 v[100:103], v[162:165], v[186:189], v[100:103]
	v_mfma_f32_16x16x32_bf16 v[96:99], v[170:173], v[186:189], v[96:99]
	v_mfma_f32_16x16x32_bf16 v[84:87], v[162:165], v[194:197], v[84:87]
	v_mfma_f32_16x16x32_bf16 v[80:83], v[170:173], v[194:197], v[80:83]
	v_mfma_f32_16x16x32_bf16 v[68:71], v[162:165], v[202:205], v[68:71]
	v_mfma_f32_16x16x32_bf16 v[64:67], v[170:173], v[202:205], v[64:67]
	v_mfma_f32_16x16x32_bf16 v[116:119], v[166:169], v[182:185], v[116:119]
	v_mfma_f32_16x16x32_bf16 v[112:115], v[174:177], v[182:185], v[112:115]
	v_mfma_f32_16x16x32_bf16 v[100:103], v[166:169], v[190:193], v[100:103]
	v_mfma_f32_16x16x32_bf16 v[96:99], v[174:177], v[190:193], v[96:99]
	v_mfma_f32_16x16x32_bf16 v[84:87], v[166:169], v[198:201], v[84:87]
	v_mfma_f32_16x16x32_bf16 v[80:83], v[174:177], v[198:201], v[80:83]
	v_mfma_f32_16x16x32_bf16 v[68:71], v[166:169], v[206:209], v[68:71]
	v_mfma_f32_16x16x32_bf16 v[64:67], v[174:177], v[206:209], v[64:67]
	s_barrier
	s_add_i32 s8, s48, s28
	v_lshl_add_u64 v[158:159], v[158:159], 0, s[88:89]
	s_mov_b32 m0, s8
	ds_read_b128 v[178:181], v145 offset:49152
	ds_read_b128 v[182:185], v145 offset:50176
	ds_read_b128 v[186:189], v145 offset:51200
	ds_read_b128 v[190:193], v145 offset:52224
	ds_read_b128 v[194:197], v145 offset:53248
	ds_read_b128 v[198:201], v145 offset:54272
	ds_read_b128 v[202:205], v145 offset:55296
	ds_read_b128 v[206:209], v145 offset:56320
	global_load_lds_dwordx4 v[158:159], off
	s_add_i32 m0, s8, 0x2000
	s_add_u32 s8, s12, 0xb0080
	v_lshl_add_u64 v[158:159], v[210:211], 0, s[88:89]
	s_addc_u32 s9, s13, 0
	s_add_i32 s12, s49, s28
	global_load_lds_dwordx4 v[158:159], off
	v_lshl_add_u64 v[158:159], s[8:9], 0, v[160:161]
	s_mov_b32 m0, s12
	s_nop 0
	global_load_lds_dwordx4 v[158:159], off
	v_lshl_add_u64 v[158:159], s[8:9], 0, v[132:133]
	s_add_i32 m0, s12, 0x2000
	s_nop 0
	global_load_lds_dwordx4 v[158:159], off
	v_lshl_add_u64 v[158:159], v[212:213], 0, s[88:89]
	s_mov_b32 m0, s34
	s_nop 0
	global_load_lds_dwordx4 v[158:159], off
	v_lshl_add_u64 v[158:159], v[214:215], 0, s[88:89]
	s_mov_b32 m0, s35
	s_nop 0
	global_load_lds_dwordx4 v[158:159], off
	s_waitcnt vmcnt(8)
	s_waitcnt lgkmcnt(0)
	s_barrier
	s_waitcnt lgkmcnt(0)
	v_mfma_f32_16x16x32_bf16 v[60:63], v[138:141], v[178:181], v[60:63]
	v_mfma_f32_16x16x32_bf16 v[56:59], v[150:153], v[178:181], v[56:59]
	v_mfma_f32_16x16x32_bf16 v[44:47], v[138:141], v[186:189], v[44:47]
	v_mfma_f32_16x16x32_bf16 v[40:43], v[150:153], v[186:189], v[40:43]
	v_mfma_f32_16x16x32_bf16 v[28:31], v[138:141], v[194:197], v[28:31]
	v_mfma_f32_16x16x32_bf16 v[24:27], v[150:153], v[194:197], v[24:27]
	v_mfma_f32_16x16x32_bf16 v[12:15], v[138:141], v[202:205], v[12:15]
	v_mfma_f32_16x16x32_bf16 v[8:11], v[150:153], v[202:205], v[8:11]
	v_mfma_f32_16x16x32_bf16 v[60:63], v[146:149], v[182:185], v[60:63]
	v_mfma_f32_16x16x32_bf16 v[56:59], v[154:157], v[182:185], v[56:59]
	v_mfma_f32_16x16x32_bf16 v[44:47], v[146:149], v[190:193], v[44:47]
	v_mfma_f32_16x16x32_bf16 v[40:43], v[154:157], v[190:193], v[40:43]
	v_mfma_f32_16x16x32_bf16 v[28:31], v[146:149], v[198:201], v[28:31]
	v_mfma_f32_16x16x32_bf16 v[24:27], v[154:157], v[198:201], v[24:27]
	v_mfma_f32_16x16x32_bf16 v[12:15], v[146:149], v[206:209], v[12:15]
	v_mfma_f32_16x16x32_bf16 v[8:11], v[154:157], v[206:209], v[8:11]
	v_mfma_f32_16x16x32_bf16 v[52:55], v[162:165], v[178:181], v[52:55]
	v_mfma_f32_16x16x32_bf16 v[48:51], v[170:173], v[178:181], v[48:51]
	v_mfma_f32_16x16x32_bf16 v[36:39], v[162:165], v[186:189], v[36:39]
	v_mfma_f32_16x16x32_bf16 v[32:35], v[170:173], v[186:189], v[32:35]
	v_mfma_f32_16x16x32_bf16 v[20:23], v[162:165], v[194:197], v[20:23]
	v_mfma_f32_16x16x32_bf16 v[16:19], v[170:173], v[194:197], v[16:19]
	v_mfma_f32_16x16x32_bf16 v[4:7], v[162:165], v[202:205], v[4:7]
	v_mfma_f32_16x16x32_bf16 v[0:3], v[170:173], v[202:205], v[0:3]
	v_mfma_f32_16x16x32_bf16 v[52:55], v[166:169], v[182:185], v[52:55]
	v_mfma_f32_16x16x32_bf16 v[48:51], v[174:177], v[182:185], v[48:51]
	v_mfma_f32_16x16x32_bf16 v[36:39], v[166:169], v[190:193], v[36:39]
	v_mfma_f32_16x16x32_bf16 v[32:35], v[174:177], v[190:193], v[32:35]
	v_mfma_f32_16x16x32_bf16 v[20:23], v[166:169], v[198:201], v[20:23]
	v_mfma_f32_16x16x32_bf16 v[16:19], v[174:177], v[198:201], v[16:19]
	v_mfma_f32_16x16x32_bf16 v[4:7], v[166:169], v[206:209], v[4:7]
	v_mfma_f32_16x16x32_bf16 v[0:3], v[174:177], v[206:209], v[0:3]
	s_barrier
	s_add_i32 s22, s22, 2
	s_add_u32 s21, s21, 0x100
	s_addc_u32 s90, s90, 0
	s_cmp_gt_u32 s22, 41
	s_mov_b64 s[8:9], s[10:11]
	s_cbranch_scc0 .LBB0_38
	v_lshl_add_u32 v140, s44, 8, v142
	v_lshl_or_b32 v138, s45, 8, v144
	v_lshlrev_b32_e32 v139, 12, v140
	v_lshl_add_u32 v139, v138, 2, v139
	v_lshlrev_b32_e32 v141, 11, v140
	v_lshl_add_u32 v138, v138, 1, v141
	s_mov_b64 s[8:9], s[4:5]
	global_load_dwordx4 v[146:149], v138, s[8:9]
	global_load_dwordx4 v[150:153], v138, s[8:9] offset:256
	s_add_u32 s8, s8, 0x8000
	s_addc_u32 s9, s9, 0
	global_load_dwordx4 v[154:157], v138, s[8:9]
	global_load_dwordx4 v[162:165], v138, s[8:9] offset:256
	s_add_u32 s8, s8, 0x8000
	s_addc_u32 s9, s9, 0
	global_load_dwordx4 v[166:169], v138, s[8:9]
	global_load_dwordx4 v[174:177], v138, s[8:9] offset:256
	s_add_u32 s8, s8, 0x8000
	s_addc_u32 s9, s9, 0
	global_load_dwordx4 v[178:181], v138, s[8:9]
	global_load_dwordx4 v[182:185], v138, s[8:9] offset:256
	s_add_u32 s8, s8, 0x28000
	s_addc_u32 s9, s9, 0
	global_load_dwordx4 v[186:189], v138, s[8:9]
	global_load_dwordx4 v[190:193], v138, s[8:9] offset:256
	s_add_u32 s8, s8, 0x8000
	s_addc_u32 s9, s9, 0
	global_load_dwordx4 v[194:197], v138, s[8:9]
	global_load_dwordx4 v[198:201], v138, s[8:9] offset:256
	s_add_u32 s8, s8, 0x8000
	s_addc_u32 s9, s9, 0
	global_load_dwordx4 v[202:205], v138, s[8:9]
	global_load_dwordx4 v[206:209], v138, s[8:9] offset:256
	s_add_u32 s8, s8, 0x8000
	s_addc_u32 s9, s9, 0
	global_load_dwordx4 v[210:213], v138, s[8:9]
	global_load_dwordx4 v[214:217], v138, s[8:9] offset:256
	s_and_b64 vcc, exec, s[6:7]
	s_cbranch_vccz .LBB0_41
	s_barrier

.LBB0_56:
	s_add_u32 s12, s10, 0xfffc0080
	s_addc_u32 s13, s11, -1
	s_add_i32 s48, 0, 0x10000
	s_cmp_eq_u32 s22, 12
	s_cselect_b32 s15, s20, s13
	s_cselect_b32 s14, s37, s12
	s_cselect_b32 s13, s41, s21
	s_cselect_b32 s12, s91, s96
	s_add_i32 s50, 0, 0x14000
	v_add_u32_e32 v154, s48, v147
	v_add_u32_e32 v158, s50, v147
	ds_read_b128 v[138:141], v154
	ds_read_b128 v[142:145], v154 offset:1024
	ds_read_b128 v[150:153], v154 offset:2048
	ds_read_b128 v[154:157], v154 offset:3072
	ds_read_b128 v[162:165], v158
	ds_read_b128 v[166:169], v158 offset:1024
	ds_read_b128 v[170:173], v158 offset:2048
	ds_read_b128 v[174:177], v158 offset:3072
	v_lshl_add_u64 v[158:159], s[10:11], 0, v[136:137]
	s_add_i32 m0, s30, 0xc000
	ds_read_b128 v[178:181], v149
	ds_read_b128 v[182:185], v149 offset:1024
	ds_read_b128 v[186:189], v149 offset:2048
	ds_read_b128 v[190:193], v149 offset:3072
	ds_read_b128 v[194:197], v149 offset:4096
	ds_read_b128 v[198:201], v149 offset:5120
	ds_read_b128 v[202:205], v149 offset:6144
	ds_read_b128 v[206:209], v149 offset:7168
	global_load_lds_dwordx4 v[158:159], off
	v_lshl_add_u64 v[158:159], s[10:11], 0, v[134:135]
	s_add_i32 m0, s30, 0xe000
	s_nop 0
	global_load_lds_dwordx4 v[158:159], off
	s_waitcnt vmcnt(8)
	s_waitcnt lgkmcnt(0)
	s_barrier
	s_waitcnt lgkmcnt(0)
	v_mfma_f32_16x16x32_bf16 v[124:127], v[138:141], v[178:181], v[124:127]
	v_mfma_f32_16x16x32_bf16 v[116:119], v[150:153], v[178:181], v[116:119]
	v_mfma_f32_16x16x32_bf16 v[108:111], v[138:141], v[186:189], v[108:111]
	v_mfma_f32_16x16x32_bf16 v[100:103], v[150:153], v[186:189], v[100:103]
	v_mfma_f32_16x16x32_bf16 v[92:95], v[138:141], v[194:197], v[92:95]
	v_mfma_f32_16x16x32_bf16 v[84:87], v[150:153], v[194:197], v[84:87]
	v_mfma_f32_16x16x32_bf16 v[76:79], v[138:141], v[202:205], v[76:79]
	v_mfma_f32_16x16x32_bf16 v[64:67], v[150:153], v[202:205], v[64:67]
	v_mfma_f32_16x16x32_bf16 v[124:127], v[142:145], v[182:185], v[124:127]
	v_mfma_f32_16x16x32_bf16 v[116:119], v[154:157], v[182:185], v[116:119]
	v_mfma_f32_16x16x32_bf16 v[108:111], v[142:145], v[190:193], v[108:111]
	v_mfma_f32_16x16x32_bf16 v[100:103], v[154:157], v[190:193], v[100:103]
	v_mfma_f32_16x16x32_bf16 v[92:95], v[142:145], v[198:201], v[92:95]
	v_mfma_f32_16x16x32_bf16 v[84:87], v[154:157], v[198:201], v[84:87]
	v_mfma_f32_16x16x32_bf16 v[76:79], v[142:145], v[206:209], v[76:79]
	v_mfma_f32_16x16x32_bf16 v[64:67], v[154:157], v[206:209], v[64:67]
	v_mfma_f32_16x16x32_bf16 v[120:123], v[162:165], v[178:181], v[120:123]
	v_mfma_f32_16x16x32_bf16 v[112:115], v[170:173], v[178:181], v[112:115]
	v_mfma_f32_16x16x32_bf16 v[104:107], v[162:165], v[186:189], v[104:107]
	v_mfma_f32_16x16x32_bf16 v[96:99], v[170:173], v[186:189], v[96:99]
	v_mfma_f32_16x16x32_bf16 v[88:91], v[162:165], v[194:197], v[88:91]
	v_mfma_f32_16x16x32_bf16 v[80:83], v[170:173], v[194:197], v[80:83]
	v_mfma_f32_16x16x32_bf16 v[72:75], v[162:165], v[202:205], v[72:75]
	v_mfma_f32_16x16x32_bf16 v[68:71], v[170:173], v[202:205], v[68:71]
	v_mfma_f32_16x16x32_bf16 v[120:123], v[166:169], v[182:185], v[120:123]
	v_mfma_f32_16x16x32_bf16 v[112:115], v[174:177], v[182:185], v[112:115]
	v_mfma_f32_16x16x32_bf16 v[104:107], v[166:169], v[190:193], v[104:107]
	v_mfma_f32_16x16x32_bf16 v[96:99], v[174:177], v[190:193], v[96:99]
	v_mfma_f32_16x16x32_bf16 v[88:91], v[166:169], v[198:201], v[88:91]
	v_mfma_f32_16x16x32_bf16 v[80:83], v[174:177], v[198:201], v[80:83]
	v_mfma_f32_16x16x32_bf16 v[72:75], v[166:169], v[206:209], v[72:75]
	v_mfma_f32_16x16x32_bf16 v[68:71], v[174:177], v[206:209], v[68:71]
	s_barrier
	s_add_i32 s48, s48, s28
	v_lshl_add_u64 v[158:159], s[12:13], 0, v[160:161]
	s_mov_b32 m0, s48
	ds_read_b128 v[178:181], v149 offset:16384
	ds_read_b128 v[182:185], v149 offset:17408
	ds_read_b128 v[186:189], v149 offset:18432
	ds_read_b128 v[190:193], v149 offset:19456
	ds_read_b128 v[194:197], v149 offset:20480
	ds_read_b128 v[198:201], v149 offset:21504
	ds_read_b128 v[202:205], v149 offset:22528
	ds_read_b128 v[206:209], v149 offset:23552
	global_load_lds_dwordx4 v[158:159], off
	s_add_i32 m0, s48, 0x2000
	s_add_u32 s48, s12, 0x40000
	v_lshl_add_u64 v[210:211], s[12:13], 0, v[128:129]
	s_addc_u32 s49, s13, 0
	s_add_i32 s50, s50, s28
	global_load_lds_dwordx4 v[210:211], off
	v_lshl_add_u64 v[212:213], s[48:49], 0, v[160:161]
	s_mov_b32 m0, s50
	v_lshl_add_u64 v[214:215], s[14:15], 0, v[130:131]
	global_load_lds_dwordx4 v[212:213], off
	v_lshl_add_u64 v[212:213], s[48:49], 0, v[128:129]
	s_add_i32 m0, s50, 0x2000
	s_nop 0
	global_load_lds_dwordx4 v[212:213], off
	v_lshl_add_u64 v[212:213], s[14:15], 0, v[132:133]
	s_mov_b32 m0, s30
	s_nop 0
	global_load_lds_dwordx4 v[212:213], off
	s_mov_b32 m0, s31
	s_nop 0
	global_load_lds_dwordx4 v[214:215], off
	s_waitcnt vmcnt(8)
	s_waitcnt lgkmcnt(0)
	s_barrier
	s_waitcnt lgkmcnt(0)
	v_mfma_f32_16x16x32_bf16 v[60:63], v[138:141], v[178:181], v[60:63]
	v_mfma_f32_16x16x32_bf16 v[48:51], v[150:153], v[178:181], v[48:51]
	v_mfma_f32_16x16x32_bf16 v[44:47], v[138:141], v[186:189], v[44:47]
	v_mfma_f32_16x16x32_bf16 v[32:35], v[150:153], v[186:189], v[32:35]
	v_mfma_f32_16x16x32_bf16 v[28:31], v[138:141], v[194:197], v[28:31]
	v_mfma_f32_16x16x32_bf16 v[16:19], v[150:153], v[194:197], v[16:19]
	v_mfma_f32_16x16x32_bf16 v[12:15], v[138:141], v[202:205], v[12:15]
	v_mfma_f32_16x16x32_bf16 v[0:3], v[150:153], v[202:205], v[0:3]
	v_mfma_f32_16x16x32_bf16 v[60:63], v[142:145], v[182:185], v[60:63]
	v_mfma_f32_16x16x32_bf16 v[48:51], v[154:157], v[182:185], v[48:51]
	v_mfma_f32_16x16x32_bf16 v[44:47], v[142:145], v[190:193], v[44:47]
	v_mfma_f32_16x16x32_bf16 v[32:35], v[154:157], v[190:193], v[32:35]
	v_mfma_f32_16x16x32_bf16 v[28:31], v[142:145], v[198:201], v[28:31]
	v_mfma_f32_16x16x32_bf16 v[16:19], v[154:157], v[198:201], v[16:19]
	v_mfma_f32_16x16x32_bf16 v[12:15], v[142:145], v[206:209], v[12:15]
	v_mfma_f32_16x16x32_bf16 v[0:3], v[154:157], v[206:209], v[0:3]
	v_mfma_f32_16x16x32_bf16 v[56:59], v[162:165], v[178:181], v[56:59]
	v_mfma_f32_16x16x32_bf16 v[52:55], v[170:173], v[178:181], v[52:55]
	v_mfma_f32_16x16x32_bf16 v[40:43], v[162:165], v[186:189], v[40:43]
	v_mfma_f32_16x16x32_bf16 v[36:39], v[170:173], v[186:189], v[36:39]
	v_mfma_f32_16x16x32_bf16 v[24:27], v[162:165], v[194:197], v[24:27]
	v_mfma_f32_16x16x32_bf16 v[20:23], v[170:173], v[194:197], v[20:23]
	v_mfma_f32_16x16x32_bf16 v[8:11], v[162:165], v[202:205], v[8:11]
	v_mfma_f32_16x16x32_bf16 v[4:7], v[170:173], v[202:205], v[4:7]
	v_mfma_f32_16x16x32_bf16 v[56:59], v[166:169], v[182:185], v[56:59]
	v_mfma_f32_16x16x32_bf16 v[52:55], v[174:177], v[182:185], v[52:55]
	v_mfma_f32_16x16x32_bf16 v[40:43], v[166:169], v[190:193], v[40:43]
	v_mfma_f32_16x16x32_bf16 v[36:39], v[174:177], v[190:193], v[36:39]
	v_mfma_f32_16x16x32_bf16 v[24:27], v[166:169], v[198:201], v[24:27]
	v_mfma_f32_16x16x32_bf16 v[20:23], v[174:177], v[198:201], v[20:23]
	v_mfma_f32_16x16x32_bf16 v[8:11], v[166:169], v[206:209], v[8:11]
	v_mfma_f32_16x16x32_bf16 v[4:7], v[174:177], v[206:209], v[4:7]
	s_barrier
	s_add_i32 s48, 0, 0x18000
	s_add_i32 s49, 0, 0x1c000
	v_add_u32_e32 v154, s48, v147
	v_add_u32_e32 v174, s49, v147
	ds_read_b128 v[138:141], v154
	ds_read_b128 v[142:145], v154 offset:1024
	ds_read_b128 v[150:153], v154 offset:2048
	ds_read_b128 v[154:157], v154 offset:3072
	ds_read_b128 v[162:165], v174
	ds_read_b128 v[166:169], v174 offset:1024
	ds_read_b128 v[170:173], v174 offset:2048
	ds_read_b128 v[174:177], v174 offset:3072
	s_add_u32 s14, s14, 0x40000
	s_addc_u32 s15, s15, 0
	s_mov_b32 m0, s33
	v_lshl_add_u64 v[216:217], s[14:15], 0, v[132:133]
	ds_read_b128 v[178:181], v149 offset:32768
	ds_read_b128 v[182:185], v149 offset:33792
	ds_read_b128 v[186:189], v149 offset:34816
	ds_read_b128 v[190:193], v149 offset:35840
	ds_read_b128 v[194:197], v149 offset:36864
	ds_read_b128 v[198:201], v149 offset:37888
	ds_read_b128 v[202:205], v149 offset:38912
	ds_read_b128 v[206:209], v149 offset:39936
	global_load_lds_dwordx4 v[216:217], off
	v_lshl_add_u64 v[216:217], s[14:15], 0, v[130:131]
	s_mov_b32 m0, s34
	s_nop 0
	global_load_lds_dwordx4 v[216:217], off
	s_waitcnt vmcnt(8)
	s_waitcnt lgkmcnt(0)
	s_barrier
	s_waitcnt lgkmcnt(0)
	v_mfma_f32_16x16x32_bf16 v[124:127], v[138:141], v[178:181], v[124:127]
	v_mfma_f32_16x16x32_bf16 v[116:119], v[150:153], v[178:181], v[116:119]
	v_mfma_f32_16x16x32_bf16 v[108:111], v[138:141], v[186:189], v[108:111]
	v_mfma_f32_16x16x32_bf16 v[100:103], v[150:153], v[186:189], v[100:103]
	v_mfma_f32_16x16x32_bf16 v[92:95], v[138:141], v[194:197], v[92:95]
	v_mfma_f32_16x16x32_bf16 v[84:87], v[150:153], v[194:197], v[84:87]
	v_mfma_f32_16x16x32_bf16 v[76:79], v[138:141], v[202:205], v[76:79]
	v_mfma_f32_16x16x32_bf16 v[64:67], v[150:153], v[202:205], v[64:67]
	v_mfma_f32_16x16x32_bf16 v[124:127], v[142:145], v[182:185], v[124:127]
	v_mfma_f32_16x16x32_bf16 v[116:119], v[154:157], v[182:185], v[116:119]
	v_mfma_f32_16x16x32_bf16 v[108:111], v[142:145], v[190:193], v[108:111]
	v_mfma_f32_16x16x32_bf16 v[100:103], v[154:157], v[190:193], v[100:103]
	v_mfma_f32_16x16x32_bf16 v[92:95], v[142:145], v[198:201], v[92:95]
	v_mfma_f32_16x16x32_bf16 v[84:87], v[154:157], v[198:201], v[84:87]
	v_mfma_f32_16x16x32_bf16 v[76:79], v[142:145], v[206:209], v[76:79]
	v_mfma_f32_16x16x32_bf16 v[64:67], v[154:157], v[206:209], v[64:67]
	v_mfma_f32_16x16x32_bf16 v[120:123], v[162:165], v[178:181], v[120:123]
	v_mfma_f32_16x16x32_bf16 v[112:115], v[170:173], v[178:181], v[112:115]
	v_mfma_f32_16x16x32_bf16 v[104:107], v[162:165], v[186:189], v[104:107]
	v_mfma_f32_16x16x32_bf16 v[96:99], v[170:173], v[186:189], v[96:99]
	v_mfma_f32_16x16x32_bf16 v[88:91], v[162:165], v[194:197], v[88:91]
	v_mfma_f32_16x16x32_bf16 v[80:83], v[170:173], v[194:197], v[80:83]
	v_mfma_f32_16x16x32_bf16 v[72:75], v[162:165], v[202:205], v[72:75]
	v_mfma_f32_16x16x32_bf16 v[68:71], v[170:173], v[202:205], v[68:71]
	v_mfma_f32_16x16x32_bf16 v[120:123], v[166:169], v[182:185], v[120:123]
	v_mfma_f32_16x16x32_bf16 v[112:115], v[174:177], v[182:185], v[112:115]
	v_mfma_f32_16x16x32_bf16 v[104:107], v[166:169], v[190:193], v[104:107]
	v_mfma_f32_16x16x32_bf16 v[96:99], v[174:177], v[190:193], v[96:99]
	v_mfma_f32_16x16x32_bf16 v[88:91], v[166:169], v[198:201], v[88:91]
	v_mfma_f32_16x16x32_bf16 v[80:83], v[174:177], v[198:201], v[80:83]
	v_mfma_f32_16x16x32_bf16 v[72:75], v[166:169], v[206:209], v[72:75]
	v_mfma_f32_16x16x32_bf16 v[68:71], v[174:177], v[206:209], v[68:71]
	s_barrier
	s_add_i32 s14, s48, s28
	v_lshl_add_u64 v[158:159], v[158:159], 0, s[88:89]
	s_mov_b32 m0, s14
	ds_read_b128 v[178:181], v149 offset:49152
	ds_read_b128 v[182:185], v149 offset:50176
	ds_read_b128 v[186:189], v149 offset:51200
	ds_read_b128 v[190:193], v149 offset:52224
	ds_read_b128 v[194:197], v149 offset:53248
	ds_read_b128 v[198:201], v149 offset:54272
	ds_read_b128 v[202:205], v149 offset:55296
	ds_read_b128 v[206:209], v149 offset:56320
	global_load_lds_dwordx4 v[158:159], off
	s_add_i32 m0, s14, 0x2000
	s_add_u32 s12, s12, 0x40080
	v_lshl_add_u64 v[158:159], v[210:211], 0, s[88:89]
	s_addc_u32 s13, s13, 0
	s_add_i32 s14, s49, s28
	global_load_lds_dwordx4 v[158:159], off
	v_lshl_add_u64 v[158:159], s[12:13], 0, v[160:161]
	s_mov_b32 m0, s14
	s_nop 0
	global_load_lds_dwordx4 v[158:159], off
	v_lshl_add_u64 v[158:159], s[12:13], 0, v[128:129]
	s_add_i32 m0, s14, 0x2000
	s_nop 0
	global_load_lds_dwordx4 v[158:159], off
	v_lshl_add_u64 v[158:159], v[212:213], 0, s[88:89]
	s_mov_b32 m0, s35
	s_nop 0
	global_load_lds_dwordx4 v[158:159], off
	v_lshl_add_u64 v[158:159], v[214:215], 0, s[88:89]
	s_mov_b32 m0, s90
	s_nop 0
	global_load_lds_dwordx4 v[158:159], off
	s_waitcnt vmcnt(8)
	s_waitcnt lgkmcnt(0)
	s_barrier
	s_waitcnt lgkmcnt(0)
	v_mfma_f32_16x16x32_bf16 v[60:63], v[138:141], v[178:181], v[60:63]
	v_mfma_f32_16x16x32_bf16 v[48:51], v[150:153], v[178:181], v[48:51]
	v_mfma_f32_16x16x32_bf16 v[44:47], v[138:141], v[186:189], v[44:47]
	v_mfma_f32_16x16x32_bf16 v[32:35], v[150:153], v[186:189], v[32:35]
	v_mfma_f32_16x16x32_bf16 v[28:31], v[138:141], v[194:197], v[28:31]
	v_mfma_f32_16x16x32_bf16 v[16:19], v[150:153], v[194:197], v[16:19]
	v_mfma_f32_16x16x32_bf16 v[12:15], v[138:141], v[202:205], v[12:15]
	v_mfma_f32_16x16x32_bf16 v[0:3], v[150:153], v[202:205], v[0:3]
	v_mfma_f32_16x16x32_bf16 v[60:63], v[142:145], v[182:185], v[60:63]
	v_mfma_f32_16x16x32_bf16 v[48:51], v[154:157], v[182:185], v[48:51]
	v_mfma_f32_16x16x32_bf16 v[44:47], v[142:145], v[190:193], v[44:47]
	v_mfma_f32_16x16x32_bf16 v[32:35], v[154:157], v[190:193], v[32:35]
	v_mfma_f32_16x16x32_bf16 v[28:31], v[142:145], v[198:201], v[28:31]
	v_mfma_f32_16x16x32_bf16 v[16:19], v[154:157], v[198:201], v[16:19]
	v_mfma_f32_16x16x32_bf16 v[12:15], v[142:145], v[206:209], v[12:15]
	v_mfma_f32_16x16x32_bf16 v[0:3], v[154:157], v[206:209], v[0:3]
	v_mfma_f32_16x16x32_bf16 v[56:59], v[162:165], v[178:181], v[56:59]
	v_mfma_f32_16x16x32_bf16 v[52:55], v[170:173], v[178:181], v[52:55]
	v_mfma_f32_16x16x32_bf16 v[40:43], v[162:165], v[186:189], v[40:43]
	v_mfma_f32_16x16x32_bf16 v[36:39], v[170:173], v[186:189], v[36:39]
	v_mfma_f32_16x16x32_bf16 v[24:27], v[162:165], v[194:197], v[24:27]
	v_mfma_f32_16x16x32_bf16 v[20:23], v[170:173], v[194:197], v[20:23]
	v_mfma_f32_16x16x32_bf16 v[8:11], v[162:165], v[202:205], v[8:11]
	v_mfma_f32_16x16x32_bf16 v[4:7], v[170:173], v[202:205], v[4:7]
	v_mfma_f32_16x16x32_bf16 v[56:59], v[166:169], v[182:185], v[56:59]
	v_mfma_f32_16x16x32_bf16 v[52:55], v[174:177], v[182:185], v[52:55]
	v_mfma_f32_16x16x32_bf16 v[40:43], v[166:169], v[190:193], v[40:43]
	v_mfma_f32_16x16x32_bf16 v[36:39], v[174:177], v[190:193], v[36:39]
	v_mfma_f32_16x16x32_bf16 v[24:27], v[166:169], v[198:201], v[24:27]
	v_mfma_f32_16x16x32_bf16 v[20:23], v[174:177], v[198:201], v[20:23]
	v_mfma_f32_16x16x32_bf16 v[8:11], v[166:169], v[206:209], v[8:11]
	v_mfma_f32_16x16x32_bf16 v[4:7], v[174:177], v[206:209], v[4:7]
	s_barrier
	s_add_i32 s22, s22, 2
	s_add_u32 s96, s96, 0x100
	s_addc_u32 s21, s21, 0
	s_add_u32 s10, s10, 0x100
	s_addc_u32 s11, s11, 0
	s_cmp_gt_u32 s22, 13
	s_cbranch_scc0 .LBB0_56
	v_lshl_add_u32 v192, s8, 8, v146
	v_lshlrev_b32_e32 v192, 3, v192
	global_load_dwordx2 v[176:177], v192, s[4:5]
	global_load_dwordx2 v[178:179], v192, s[4:5] offset:128
	global_load_dwordx2 v[180:181], v192, s[4:5] offset:256
	global_load_dwordx2 v[182:183], v192, s[4:5] offset:384
	global_load_dwordx2 v[184:185], v192, s[4:5] offset:1024
	global_load_dwordx2 v[186:187], v192, s[4:5] offset:1152
	global_load_dwordx2 v[188:189], v192, s[4:5] offset:1280
	global_load_dwordx2 v[190:191], v192, s[4:5] offset:1408
	s_and_b64 vcc, exec, s[6:7]
	s_cbranch_vccz .LBB0_59
	s_barrier

.LBB0_84:
	s_add_u32 s12, vcc_lo, 0xfffc0080
	s_addc_u32 s13, vcc_hi, -1
	s_add_i32 s48, 0, 0x10000
	s_cmp_eq_u32 s22, 12
	s_cselect_b32 s15, s9, s13
	s_cselect_b32 s14, s20, s12
	s_cselect_b32 s13, s37, s21
	s_cselect_b32 s12, s45, s90
	s_add_i32 s50, 0, 0x14000
	v_add_u32_e32 v154, s48, v143
	v_add_u32_e32 v158, s50, v143
	ds_read_b128 v[138:141], v154
	ds_read_b128 v[146:149], v154 offset:1024
	ds_read_b128 v[150:153], v154 offset:2048
	ds_read_b128 v[154:157], v154 offset:3072
	ds_read_b128 v[162:165], v158
	ds_read_b128 v[166:169], v158 offset:1024
	ds_read_b128 v[170:173], v158 offset:2048
	ds_read_b128 v[174:177], v158 offset:3072
	v_lshl_add_u64 v[158:159], vcc, 0, v[136:137]
	s_add_i32 m0, s11, 0xc000
	ds_read_b128 v[178:181], v145
	ds_read_b128 v[182:185], v145 offset:1024
	ds_read_b128 v[186:189], v145 offset:2048
	ds_read_b128 v[190:193], v145 offset:3072
	ds_read_b128 v[194:197], v145 offset:4096
	ds_read_b128 v[198:201], v145 offset:5120
	ds_read_b128 v[202:205], v145 offset:6144
	ds_read_b128 v[206:209], v145 offset:7168
	global_load_lds_dwordx4 v[158:159], off
	v_lshl_add_u64 v[158:159], vcc, 0, v[134:135]
	s_add_i32 m0, s11, 0xe000
	s_nop 0
	global_load_lds_dwordx4 v[158:159], off
	s_waitcnt vmcnt(8)
	s_waitcnt lgkmcnt(0)
	s_barrier
	s_waitcnt lgkmcnt(0)
	v_mfma_f32_16x16x32_bf16 v[124:127], v[138:141], v[178:181], v[124:127]
	v_mfma_f32_16x16x32_bf16 v[120:123], v[150:153], v[178:181], v[120:123]
	v_mfma_f32_16x16x32_bf16 v[108:111], v[138:141], v[186:189], v[108:111]
	v_mfma_f32_16x16x32_bf16 v[104:107], v[150:153], v[186:189], v[104:107]
	v_mfma_f32_16x16x32_bf16 v[92:95], v[138:141], v[194:197], v[92:95]
	v_mfma_f32_16x16x32_bf16 v[88:91], v[150:153], v[194:197], v[88:91]
	v_mfma_f32_16x16x32_bf16 v[76:79], v[138:141], v[202:205], v[76:79]
	v_mfma_f32_16x16x32_bf16 v[72:75], v[150:153], v[202:205], v[72:75]
	v_mfma_f32_16x16x32_bf16 v[124:127], v[146:149], v[182:185], v[124:127]
	v_mfma_f32_16x16x32_bf16 v[120:123], v[154:157], v[182:185], v[120:123]
	v_mfma_f32_16x16x32_bf16 v[108:111], v[146:149], v[190:193], v[108:111]
	v_mfma_f32_16x16x32_bf16 v[104:107], v[154:157], v[190:193], v[104:107]
	v_mfma_f32_16x16x32_bf16 v[92:95], v[146:149], v[198:201], v[92:95]
	v_mfma_f32_16x16x32_bf16 v[88:91], v[154:157], v[198:201], v[88:91]
	v_mfma_f32_16x16x32_bf16 v[76:79], v[146:149], v[206:209], v[76:79]
	v_mfma_f32_16x16x32_bf16 v[72:75], v[154:157], v[206:209], v[72:75]
	v_mfma_f32_16x16x32_bf16 v[116:119], v[162:165], v[178:181], v[116:119]
	v_mfma_f32_16x16x32_bf16 v[112:115], v[170:173], v[178:181], v[112:115]
	v_mfma_f32_16x16x32_bf16 v[100:103], v[162:165], v[186:189], v[100:103]
	v_mfma_f32_16x16x32_bf16 v[96:99], v[170:173], v[186:189], v[96:99]
	v_mfma_f32_16x16x32_bf16 v[84:87], v[162:165], v[194:197], v[84:87]
	v_mfma_f32_16x16x32_bf16 v[80:83], v[170:173], v[194:197], v[80:83]
	v_mfma_f32_16x16x32_bf16 v[68:71], v[162:165], v[202:205], v[68:71]
	v_mfma_f32_16x16x32_bf16 v[64:67], v[170:173], v[202:205], v[64:67]
	v_mfma_f32_16x16x32_bf16 v[116:119], v[166:169], v[182:185], v[116:119]
	v_mfma_f32_16x16x32_bf16 v[112:115], v[174:177], v[182:185], v[112:115]
	v_mfma_f32_16x16x32_bf16 v[100:103], v[166:169], v[190:193], v[100:103]
	v_mfma_f32_16x16x32_bf16 v[96:99], v[174:177], v[190:193], v[96:99]
	v_mfma_f32_16x16x32_bf16 v[84:87], v[166:169], v[198:201], v[84:87]
	v_mfma_f32_16x16x32_bf16 v[80:83], v[174:177], v[198:201], v[80:83]
	v_mfma_f32_16x16x32_bf16 v[68:71], v[166:169], v[206:209], v[68:71]
	v_mfma_f32_16x16x32_bf16 v[64:67], v[174:177], v[206:209], v[64:67]
	s_barrier
	s_add_i32 s48, s48, s28
	v_lshl_add_u64 v[158:159], s[12:13], 0, v[160:161]
	s_mov_b32 m0, s48
	ds_read_b128 v[178:181], v145 offset:16384
	ds_read_b128 v[182:185], v145 offset:17408
	ds_read_b128 v[186:189], v145 offset:18432
	ds_read_b128 v[190:193], v145 offset:19456
	ds_read_b128 v[194:197], v145 offset:20480
	ds_read_b128 v[198:201], v145 offset:21504
	ds_read_b128 v[202:205], v145 offset:22528
	ds_read_b128 v[206:209], v145 offset:23552
	global_load_lds_dwordx4 v[158:159], off
	s_add_i32 m0, s48, 0x2000
	s_add_u32 s48, s12, 0x40000
	v_lshl_add_u64 v[210:211], s[12:13], 0, v[132:133]
	s_addc_u32 s49, s13, 0
	s_add_i32 s50, s50, s28
	global_load_lds_dwordx4 v[210:211], off
	v_lshl_add_u64 v[212:213], s[48:49], 0, v[160:161]
	s_mov_b32 m0, s50
	v_lshl_add_u64 v[214:215], s[14:15], 0, v[130:131]
	global_load_lds_dwordx4 v[212:213], off
	v_lshl_add_u64 v[212:213], s[48:49], 0, v[132:133]
	s_add_i32 m0, s50, 0x2000
	s_nop 0
	global_load_lds_dwordx4 v[212:213], off
	v_lshl_add_u64 v[212:213], s[14:15], 0, v[128:129]
	s_mov_b32 m0, s11
	s_nop 0
	global_load_lds_dwordx4 v[212:213], off
	s_mov_b32 m0, s29
	s_nop 0
	global_load_lds_dwordx4 v[214:215], off
	s_waitcnt vmcnt(8)
	s_waitcnt lgkmcnt(0)
	s_barrier
	s_waitcnt lgkmcnt(0)
	v_mfma_f32_16x16x32_bf16 v[60:63], v[138:141], v[178:181], v[60:63]
	v_mfma_f32_16x16x32_bf16 v[56:59], v[150:153], v[178:181], v[56:59]
	v_mfma_f32_16x16x32_bf16 v[44:47], v[138:141], v[186:189], v[44:47]
	v_mfma_f32_16x16x32_bf16 v[40:43], v[150:153], v[186:189], v[40:43]
	v_mfma_f32_16x16x32_bf16 v[28:31], v[138:141], v[194:197], v[28:31]
	v_mfma_f32_16x16x32_bf16 v[24:27], v[150:153], v[194:197], v[24:27]
	v_mfma_f32_16x16x32_bf16 v[12:15], v[138:141], v[202:205], v[12:15]
	v_mfma_f32_16x16x32_bf16 v[8:11], v[150:153], v[202:205], v[8:11]
	v_mfma_f32_16x16x32_bf16 v[60:63], v[146:149], v[182:185], v[60:63]
	v_mfma_f32_16x16x32_bf16 v[56:59], v[154:157], v[182:185], v[56:59]
	v_mfma_f32_16x16x32_bf16 v[44:47], v[146:149], v[190:193], v[44:47]
	v_mfma_f32_16x16x32_bf16 v[40:43], v[154:157], v[190:193], v[40:43]
	v_mfma_f32_16x16x32_bf16 v[28:31], v[146:149], v[198:201], v[28:31]
	v_mfma_f32_16x16x32_bf16 v[24:27], v[154:157], v[198:201], v[24:27]
	v_mfma_f32_16x16x32_bf16 v[12:15], v[146:149], v[206:209], v[12:15]
	v_mfma_f32_16x16x32_bf16 v[8:11], v[154:157], v[206:209], v[8:11]
	v_mfma_f32_16x16x32_bf16 v[52:55], v[162:165], v[178:181], v[52:55]
	v_mfma_f32_16x16x32_bf16 v[48:51], v[170:173], v[178:181], v[48:51]
	v_mfma_f32_16x16x32_bf16 v[36:39], v[162:165], v[186:189], v[36:39]
	v_mfma_f32_16x16x32_bf16 v[32:35], v[170:173], v[186:189], v[32:35]
	v_mfma_f32_16x16x32_bf16 v[20:23], v[162:165], v[194:197], v[20:23]
	v_mfma_f32_16x16x32_bf16 v[16:19], v[170:173], v[194:197], v[16:19]
	v_mfma_f32_16x16x32_bf16 v[4:7], v[162:165], v[202:205], v[4:7]
	v_mfma_f32_16x16x32_bf16 v[0:3], v[170:173], v[202:205], v[0:3]
	v_mfma_f32_16x16x32_bf16 v[52:55], v[166:169], v[182:185], v[52:55]
	v_mfma_f32_16x16x32_bf16 v[48:51], v[174:177], v[182:185], v[48:51]
	v_mfma_f32_16x16x32_bf16 v[36:39], v[166:169], v[190:193], v[36:39]
	v_mfma_f32_16x16x32_bf16 v[32:35], v[174:177], v[190:193], v[32:35]
	v_mfma_f32_16x16x32_bf16 v[20:23], v[166:169], v[198:201], v[20:23]
	v_mfma_f32_16x16x32_bf16 v[16:19], v[174:177], v[198:201], v[16:19]
	v_mfma_f32_16x16x32_bf16 v[4:7], v[166:169], v[206:209], v[4:7]
	v_mfma_f32_16x16x32_bf16 v[0:3], v[174:177], v[206:209], v[0:3]
	s_barrier
	s_add_i32 s48, 0, 0x18000
	s_add_i32 s49, 0, 0x1c000
	v_add_u32_e32 v154, s48, v143
	v_add_u32_e32 v174, s49, v143
	ds_read_b128 v[138:141], v154
	ds_read_b128 v[146:149], v154 offset:1024
	ds_read_b128 v[150:153], v154 offset:2048
	ds_read_b128 v[154:157], v154 offset:3072
	ds_read_b128 v[162:165], v174
	ds_read_b128 v[166:169], v174 offset:1024
	ds_read_b128 v[170:173], v174 offset:2048
	ds_read_b128 v[174:177], v174 offset:3072
	s_add_u32 s14, s14, 0x40000
	s_addc_u32 s15, s15, 0
	s_mov_b32 m0, s30
	v_lshl_add_u64 v[216:217], s[14:15], 0, v[128:129]
	ds_read_b128 v[178:181], v145 offset:32768
	ds_read_b128 v[182:185], v145 offset:33792
	ds_read_b128 v[186:189], v145 offset:34816
	ds_read_b128 v[190:193], v145 offset:35840
	ds_read_b128 v[194:197], v145 offset:36864
	ds_read_b128 v[198:201], v145 offset:37888
	ds_read_b128 v[202:205], v145 offset:38912
	ds_read_b128 v[206:209], v145 offset:39936
	global_load_lds_dwordx4 v[216:217], off
	v_lshl_add_u64 v[216:217], s[14:15], 0, v[130:131]
	s_mov_b32 m0, s31
	s_nop 0
	global_load_lds_dwordx4 v[216:217], off
	s_waitcnt vmcnt(8)
	s_waitcnt lgkmcnt(0)
	s_barrier
	s_waitcnt lgkmcnt(0)
	v_mfma_f32_16x16x32_bf16 v[124:127], v[138:141], v[178:181], v[124:127]
	v_mfma_f32_16x16x32_bf16 v[120:123], v[150:153], v[178:181], v[120:123]
	v_mfma_f32_16x16x32_bf16 v[108:111], v[138:141], v[186:189], v[108:111]
	v_mfma_f32_16x16x32_bf16 v[104:107], v[150:153], v[186:189], v[104:107]
	v_mfma_f32_16x16x32_bf16 v[92:95], v[138:141], v[194:197], v[92:95]
	v_mfma_f32_16x16x32_bf16 v[88:91], v[150:153], v[194:197], v[88:91]
	v_mfma_f32_16x16x32_bf16 v[76:79], v[138:141], v[202:205], v[76:79]
	v_mfma_f32_16x16x32_bf16 v[72:75], v[150:153], v[202:205], v[72:75]
	v_mfma_f32_16x16x32_bf16 v[124:127], v[146:149], v[182:185], v[124:127]
	v_mfma_f32_16x16x32_bf16 v[120:123], v[154:157], v[182:185], v[120:123]
	v_mfma_f32_16x16x32_bf16 v[108:111], v[146:149], v[190:193], v[108:111]
	v_mfma_f32_16x16x32_bf16 v[104:107], v[154:157], v[190:193], v[104:107]
	v_mfma_f32_16x16x32_bf16 v[92:95], v[146:149], v[198:201], v[92:95]
	v_mfma_f32_16x16x32_bf16 v[88:91], v[154:157], v[198:201], v[88:91]
	v_mfma_f32_16x16x32_bf16 v[76:79], v[146:149], v[206:209], v[76:79]
	v_mfma_f32_16x16x32_bf16 v[72:75], v[154:157], v[206:209], v[72:75]
	v_mfma_f32_16x16x32_bf16 v[116:119], v[162:165], v[178:181], v[116:119]
	v_mfma_f32_16x16x32_bf16 v[112:115], v[170:173], v[178:181], v[112:115]
	v_mfma_f32_16x16x32_bf16 v[100:103], v[162:165], v[186:189], v[100:103]
	v_mfma_f32_16x16x32_bf16 v[96:99], v[170:173], v[186:189], v[96:99]
	v_mfma_f32_16x16x32_bf16 v[84:87], v[162:165], v[194:197], v[84:87]
	v_mfma_f32_16x16x32_bf16 v[80:83], v[170:173], v[194:197], v[80:83]
	v_mfma_f32_16x16x32_bf16 v[68:71], v[162:165], v[202:205], v[68:71]
	v_mfma_f32_16x16x32_bf16 v[64:67], v[170:173], v[202:205], v[64:67]
	v_mfma_f32_16x16x32_bf16 v[116:119], v[166:169], v[182:185], v[116:119]
	v_mfma_f32_16x16x32_bf16 v[112:115], v[174:177], v[182:185], v[112:115]
	v_mfma_f32_16x16x32_bf16 v[100:103], v[166:169], v[190:193], v[100:103]
	v_mfma_f32_16x16x32_bf16 v[96:99], v[174:177], v[190:193], v[96:99]
	v_mfma_f32_16x16x32_bf16 v[84:87], v[166:169], v[198:201], v[84:87]
	v_mfma_f32_16x16x32_bf16 v[80:83], v[174:177], v[198:201], v[80:83]
	v_mfma_f32_16x16x32_bf16 v[68:71], v[166:169], v[206:209], v[68:71]
	v_mfma_f32_16x16x32_bf16 v[64:67], v[174:177], v[206:209], v[64:67]
	s_barrier
	s_add_i32 s14, s48, s28
	v_lshl_add_u64 v[158:159], v[158:159], 0, s[88:89]
	s_mov_b32 m0, s14
	ds_read_b128 v[178:181], v145 offset:49152
	ds_read_b128 v[182:185], v145 offset:50176
	ds_read_b128 v[186:189], v145 offset:51200
	ds_read_b128 v[190:193], v145 offset:52224
	ds_read_b128 v[194:197], v145 offset:53248
	ds_read_b128 v[198:201], v145 offset:54272
	ds_read_b128 v[202:205], v145 offset:55296
	ds_read_b128 v[206:209], v145 offset:56320
	global_load_lds_dwordx4 v[158:159], off
	s_add_i32 m0, s14, 0x2000
	s_add_u32 s12, s12, 0x40080
	v_lshl_add_u64 v[158:159], v[210:211], 0, s[88:89]
	s_addc_u32 s13, s13, 0
	s_add_i32 s14, s49, s28
	global_load_lds_dwordx4 v[158:159], off
	v_lshl_add_u64 v[158:159], s[12:13], 0, v[160:161]
	s_mov_b32 m0, s14
	s_nop 0
	global_load_lds_dwordx4 v[158:159], off
	v_lshl_add_u64 v[158:159], s[12:13], 0, v[132:133]
	s_add_i32 m0, s14, 0x2000
	s_nop 0
	global_load_lds_dwordx4 v[158:159], off
	v_lshl_add_u64 v[158:159], v[212:213], 0, s[88:89]
	s_mov_b32 m0, s33
	s_nop 0
	global_load_lds_dwordx4 v[158:159], off
	v_lshl_add_u64 v[158:159], v[214:215], 0, s[88:89]
	s_mov_b32 m0, s34
	s_nop 0
	global_load_lds_dwordx4 v[158:159], off
	s_waitcnt vmcnt(8)
	s_waitcnt lgkmcnt(0)
	s_barrier
	s_waitcnt lgkmcnt(0)
	v_mfma_f32_16x16x32_bf16 v[60:63], v[138:141], v[178:181], v[60:63]
	v_mfma_f32_16x16x32_bf16 v[56:59], v[150:153], v[178:181], v[56:59]
	v_mfma_f32_16x16x32_bf16 v[44:47], v[138:141], v[186:189], v[44:47]
	v_mfma_f32_16x16x32_bf16 v[40:43], v[150:153], v[186:189], v[40:43]
	v_mfma_f32_16x16x32_bf16 v[28:31], v[138:141], v[194:197], v[28:31]
	v_mfma_f32_16x16x32_bf16 v[24:27], v[150:153], v[194:197], v[24:27]
	v_mfma_f32_16x16x32_bf16 v[12:15], v[138:141], v[202:205], v[12:15]
	v_mfma_f32_16x16x32_bf16 v[8:11], v[150:153], v[202:205], v[8:11]
	v_mfma_f32_16x16x32_bf16 v[60:63], v[146:149], v[182:185], v[60:63]
	v_mfma_f32_16x16x32_bf16 v[56:59], v[154:157], v[182:185], v[56:59]
	v_mfma_f32_16x16x32_bf16 v[44:47], v[146:149], v[190:193], v[44:47]
	v_mfma_f32_16x16x32_bf16 v[40:43], v[154:157], v[190:193], v[40:43]
	v_mfma_f32_16x16x32_bf16 v[28:31], v[146:149], v[198:201], v[28:31]
	v_mfma_f32_16x16x32_bf16 v[24:27], v[154:157], v[198:201], v[24:27]
	v_mfma_f32_16x16x32_bf16 v[12:15], v[146:149], v[206:209], v[12:15]
	v_mfma_f32_16x16x32_bf16 v[8:11], v[154:157], v[206:209], v[8:11]
	v_mfma_f32_16x16x32_bf16 v[52:55], v[162:165], v[178:181], v[52:55]
	v_mfma_f32_16x16x32_bf16 v[48:51], v[170:173], v[178:181], v[48:51]
	v_mfma_f32_16x16x32_bf16 v[36:39], v[162:165], v[186:189], v[36:39]
	v_mfma_f32_16x16x32_bf16 v[32:35], v[170:173], v[186:189], v[32:35]
	v_mfma_f32_16x16x32_bf16 v[20:23], v[162:165], v[194:197], v[20:23]
	v_mfma_f32_16x16x32_bf16 v[16:19], v[170:173], v[194:197], v[16:19]
	v_mfma_f32_16x16x32_bf16 v[4:7], v[162:165], v[202:205], v[4:7]
	v_mfma_f32_16x16x32_bf16 v[0:3], v[170:173], v[202:205], v[0:3]
	v_mfma_f32_16x16x32_bf16 v[52:55], v[166:169], v[182:185], v[52:55]
	v_mfma_f32_16x16x32_bf16 v[48:51], v[174:177], v[182:185], v[48:51]
	v_mfma_f32_16x16x32_bf16 v[36:39], v[166:169], v[190:193], v[36:39]
	v_mfma_f32_16x16x32_bf16 v[32:35], v[174:177], v[190:193], v[32:35]
	v_mfma_f32_16x16x32_bf16 v[20:23], v[166:169], v[198:201], v[20:23]
	v_mfma_f32_16x16x32_bf16 v[16:19], v[174:177], v[198:201], v[16:19]
	v_mfma_f32_16x16x32_bf16 v[4:7], v[166:169], v[206:209], v[4:7]
	v_mfma_f32_16x16x32_bf16 v[0:3], v[174:177], v[206:209], v[0:3]
	s_barrier
	s_add_i32 s22, s22, 2
	s_add_u32 s90, s90, 0x100
	s_addc_u32 s21, s21, 0
	s_add_u32 vcc_lo, vcc_lo, 0x100
	s_addc_u32 vcc_hi, vcc_hi, 0
	s_cmp_gt_u32 s22, 13
	s_cbranch_scc0 .LBB0_84
	v_lshl_add_u32 v140, s8, 8, v142
	v_lshl_or_b32 v138, s10, 8, v144
	v_lshlrev_b32_e32 v141, 11, v140
	v_lshl_add_u32 v138, v138, 1, v141
	v_lshlrev_b32_e32 v139, 3, v140
	s_mov_b64 s[8:9], s[2:3]
	global_load_dwordx4 v[146:149], v138, s[8:9]
	global_load_dwordx4 v[150:153], v138, s[8:9] offset:256
	s_add_u32 s8, s8, 0x8000
	s_addc_u32 s9, s9, 0
	global_load_dwordx4 v[154:157], v138, s[8:9]
	global_load_dwordx4 v[162:165], v138, s[8:9] offset:256
	s_add_u32 s8, s8, 0x8000
	s_addc_u32 s9, s9, 0
	global_load_dwordx4 v[166:169], v138, s[8:9]
	global_load_dwordx4 v[174:177], v138, s[8:9] offset:256
	s_add_u32 s8, s8, 0x8000
	s_addc_u32 s9, s9, 0
	global_load_dwordx4 v[178:181], v138, s[8:9]
	global_load_dwordx4 v[182:185], v138, s[8:9] offset:256
	s_add_u32 s8, s8, 0x28000
	s_addc_u32 s9, s9, 0
	global_load_dwordx4 v[186:189], v138, s[8:9]
	global_load_dwordx4 v[190:193], v138, s[8:9] offset:256
	s_add_u32 s8, s8, 0x8000
	s_addc_u32 s9, s9, 0
	global_load_dwordx4 v[194:197], v138, s[8:9]
	global_load_dwordx4 v[198:201], v138, s[8:9] offset:256
	s_add_u32 s8, s8, 0x8000
	s_addc_u32 s9, s9, 0
	global_load_dwordx4 v[202:205], v138, s[8:9]
	global_load_dwordx4 v[206:209], v138, s[8:9] offset:256
	s_add_u32 s8, s8, 0x8000
	s_addc_u32 s9, s9, 0
	global_load_dwordx4 v[210:213], v138, s[8:9]
	global_load_dwordx4 v[214:217], v138, s[8:9] offset:256
	s_and_b64 vcc, exec, s[6:7]
	s_cbranch_vccz .LBB0_87
	s_barrier

.LBB0_139:
	s_add_u32 s14, s10, 0xfffc0080
	s_addc_u32 s15, s11, -1
	s_add_i32 s48, 0, 0x10000
	s_cmp_eq_u32 s22, 12
	s_cselect_b32 s93, s9, s15
	s_cselect_b32 s92, s41, s14
	s_cselect_b32 s15, s45, s21
	s_cselect_b32 s14, vcc_lo, vcc_hi
	s_add_i32 s50, 0, 0x14000
	v_add_u32_e32 v140, s48, v202
	v_add_u32_e32 v156, s50, v202
	ds_read_b128 v[128:131], v140
	ds_read_b128 v[132:135], v140 offset:1024
	ds_read_b128 v[136:139], v140 offset:2048
	ds_read_b128 v[140:143], v140 offset:3072
	ds_read_b128 v[144:147], v156
	ds_read_b128 v[148:151], v156 offset:1024
	ds_read_b128 v[152:155], v156 offset:2048
	ds_read_b128 v[156:159], v156 offset:3072
	v_lshl_add_u64 v[162:163], s[10:11], 0, v[186:187]
	s_add_i32 m0, s31, 0xc000
	ds_read_b128 v[188:191], v204
	ds_read_b128 v[192:195], v204 offset:1024
	ds_read_b128 v[196:199], v204 offset:2048
	ds_read_b128 v[206:209], v204 offset:3072
	ds_read_b128 v[210:213], v204 offset:4096
	ds_read_b128 v[214:217], v204 offset:5120
	ds_read_b128 v[238:241], v204 offset:6144
	ds_read_b128 v[246:249], v204 offset:7168
	global_load_lds_dwordx4 v[162:163], off
	v_lshl_add_u64 v[162:163], s[10:11], 0, v[184:185]
	s_add_i32 m0, s31, 0xe000
	s_nop 0
	global_load_lds_dwordx4 v[162:163], off
	s_waitcnt vmcnt(8)
	s_waitcnt lgkmcnt(0)
	s_barrier
	s_waitcnt lgkmcnt(0)
	v_mfma_f32_16x16x32_bf16 v[124:127], v[128:131], v[188:191], v[124:127]
	v_mfma_f32_16x16x32_bf16 v[120:123], v[136:139], v[188:191], v[120:123]
	v_mfma_f32_16x16x32_bf16 v[108:111], v[128:131], v[196:199], v[108:111]
	v_mfma_f32_16x16x32_bf16 v[104:107], v[136:139], v[196:199], v[104:107]
	v_mfma_f32_16x16x32_bf16 v[92:95], v[128:131], v[210:213], v[92:95]
	v_mfma_f32_16x16x32_bf16 v[88:91], v[136:139], v[210:213], v[88:91]
	v_mfma_f32_16x16x32_bf16 v[76:79], v[128:131], v[238:241], v[76:79]
	v_mfma_f32_16x16x32_bf16 v[72:75], v[136:139], v[238:241], v[72:75]
	v_mfma_f32_16x16x32_bf16 v[124:127], v[132:135], v[192:195], v[124:127]
	v_mfma_f32_16x16x32_bf16 v[120:123], v[140:143], v[192:195], v[120:123]
	v_mfma_f32_16x16x32_bf16 v[108:111], v[132:135], v[206:209], v[108:111]
	v_mfma_f32_16x16x32_bf16 v[104:107], v[140:143], v[206:209], v[104:107]
	v_mfma_f32_16x16x32_bf16 v[92:95], v[132:135], v[214:217], v[92:95]
	v_mfma_f32_16x16x32_bf16 v[88:91], v[140:143], v[214:217], v[88:91]
	v_mfma_f32_16x16x32_bf16 v[76:79], v[132:135], v[246:249], v[76:79]
	v_mfma_f32_16x16x32_bf16 v[72:75], v[140:143], v[246:249], v[72:75]
	v_mfma_f32_16x16x32_bf16 v[116:119], v[144:147], v[188:191], v[116:119]
	v_mfma_f32_16x16x32_bf16 v[112:115], v[152:155], v[188:191], v[112:115]
	v_mfma_f32_16x16x32_bf16 v[100:103], v[144:147], v[196:199], v[100:103]
	v_mfma_f32_16x16x32_bf16 v[96:99], v[152:155], v[196:199], v[96:99]
	v_mfma_f32_16x16x32_bf16 v[84:87], v[144:147], v[210:213], v[84:87]
	v_mfma_f32_16x16x32_bf16 v[80:83], v[152:155], v[210:213], v[80:83]
	v_mfma_f32_16x16x32_bf16 v[68:71], v[144:147], v[238:241], v[68:71]
	v_mfma_f32_16x16x32_bf16 v[64:67], v[152:155], v[238:241], v[64:67]
	v_mfma_f32_16x16x32_bf16 v[116:119], v[148:151], v[192:195], v[116:119]
	v_mfma_f32_16x16x32_bf16 v[112:115], v[156:159], v[192:195], v[112:115]
	v_mfma_f32_16x16x32_bf16 v[100:103], v[148:151], v[206:209], v[100:103]
	v_mfma_f32_16x16x32_bf16 v[96:99], v[156:159], v[206:209], v[96:99]
	v_mfma_f32_16x16x32_bf16 v[84:87], v[148:151], v[214:217], v[84:87]
	v_mfma_f32_16x16x32_bf16 v[80:83], v[156:159], v[214:217], v[80:83]
	v_mfma_f32_16x16x32_bf16 v[68:71], v[148:151], v[246:249], v[68:71]
	v_mfma_f32_16x16x32_bf16 v[64:67], v[156:159], v[246:249], v[64:67]
	s_barrier
	s_add_i32 s48, s48, s29
	v_lshl_add_u64 v[162:163], s[14:15], 0, v[178:179]
	s_mov_b32 m0, s48
	ds_read_b128 v[188:191], v204 offset:16384
	ds_read_b128 v[192:195], v204 offset:17408
	ds_read_b128 v[196:199], v204 offset:18432
	ds_read_b128 v[206:209], v204 offset:19456
	ds_read_b128 v[210:213], v204 offset:20480
	ds_read_b128 v[214:217], v204 offset:21504
	ds_read_b128 v[238:241], v204 offset:22528
	ds_read_b128 v[246:249], v204 offset:23552
	global_load_lds_dwordx4 v[162:163], off
	s_add_i32 m0, s48, 0x2000
	s_add_u32 s48, s14, 0x40000
	v_lshl_add_u64 v[164:165], s[14:15], 0, v[174:175]
	s_addc_u32 s49, s15, 0
	s_add_i32 s50, s50, s29
	global_load_lds_dwordx4 v[164:165], off
	v_lshl_add_u64 v[166:167], s[48:49], 0, v[178:179]
	s_mov_b32 m0, s50
	v_lshl_add_u64 v[168:169], s[92:93], 0, v[176:177]
	global_load_lds_dwordx4 v[166:167], off
	v_lshl_add_u64 v[166:167], s[48:49], 0, v[174:175]
	s_add_i32 m0, s50, 0x2000
	s_nop 0
	global_load_lds_dwordx4 v[166:167], off
	v_lshl_add_u64 v[166:167], s[92:93], 0, v[180:181]
	s_mov_b32 m0, s31
	s_nop 0
	global_load_lds_dwordx4 v[166:167], off
	s_mov_b32 m0, s34
	s_nop 0
	global_load_lds_dwordx4 v[168:169], off
	s_waitcnt vmcnt(8)
	s_waitcnt lgkmcnt(0)
	s_barrier
	s_waitcnt lgkmcnt(0)
	v_mfma_f32_16x16x32_bf16 v[60:63], v[128:131], v[188:191], v[60:63]
	v_mfma_f32_16x16x32_bf16 v[56:59], v[136:139], v[188:191], v[56:59]
	v_mfma_f32_16x16x32_bf16 v[44:47], v[128:131], v[196:199], v[44:47]
	v_mfma_f32_16x16x32_bf16 v[40:43], v[136:139], v[196:199], v[40:43]
	v_mfma_f32_16x16x32_bf16 v[28:31], v[128:131], v[210:213], v[28:31]
	v_mfma_f32_16x16x32_bf16 v[24:27], v[136:139], v[210:213], v[24:27]
	v_mfma_f32_16x16x32_bf16 v[12:15], v[128:131], v[238:241], v[12:15]
	v_mfma_f32_16x16x32_bf16 v[8:11], v[136:139], v[238:241], v[8:11]
	v_mfma_f32_16x16x32_bf16 v[60:63], v[132:135], v[192:195], v[60:63]
	v_mfma_f32_16x16x32_bf16 v[56:59], v[140:143], v[192:195], v[56:59]
	v_mfma_f32_16x16x32_bf16 v[44:47], v[132:135], v[206:209], v[44:47]
	v_mfma_f32_16x16x32_bf16 v[40:43], v[140:143], v[206:209], v[40:43]
	v_mfma_f32_16x16x32_bf16 v[28:31], v[132:135], v[214:217], v[28:31]
	v_mfma_f32_16x16x32_bf16 v[24:27], v[140:143], v[214:217], v[24:27]
	v_mfma_f32_16x16x32_bf16 v[12:15], v[132:135], v[246:249], v[12:15]
	v_mfma_f32_16x16x32_bf16 v[8:11], v[140:143], v[246:249], v[8:11]
	v_mfma_f32_16x16x32_bf16 v[52:55], v[144:147], v[188:191], v[52:55]
	v_mfma_f32_16x16x32_bf16 v[48:51], v[152:155], v[188:191], v[48:51]
	v_mfma_f32_16x16x32_bf16 v[36:39], v[144:147], v[196:199], v[36:39]
	v_mfma_f32_16x16x32_bf16 v[32:35], v[152:155], v[196:199], v[32:35]
	v_mfma_f32_16x16x32_bf16 v[20:23], v[144:147], v[210:213], v[20:23]
	v_mfma_f32_16x16x32_bf16 v[16:19], v[152:155], v[210:213], v[16:19]
	v_mfma_f32_16x16x32_bf16 v[4:7], v[144:147], v[238:241], v[4:7]
	v_mfma_f32_16x16x32_bf16 v[0:3], v[152:155], v[238:241], v[0:3]
	v_mfma_f32_16x16x32_bf16 v[52:55], v[148:151], v[192:195], v[52:55]
	v_mfma_f32_16x16x32_bf16 v[48:51], v[156:159], v[192:195], v[48:51]
	v_mfma_f32_16x16x32_bf16 v[36:39], v[148:151], v[206:209], v[36:39]
	v_mfma_f32_16x16x32_bf16 v[32:35], v[156:159], v[206:209], v[32:35]
	v_mfma_f32_16x16x32_bf16 v[20:23], v[148:151], v[214:217], v[20:23]
	v_mfma_f32_16x16x32_bf16 v[16:19], v[156:159], v[214:217], v[16:19]
	v_mfma_f32_16x16x32_bf16 v[4:7], v[148:151], v[246:249], v[4:7]
	v_mfma_f32_16x16x32_bf16 v[0:3], v[156:159], v[246:249], v[0:3]
	s_barrier
	s_add_i32 s50, 0, 0x18000
	s_add_i32 s51, 0, 0x1c000
	v_add_u32_e32 v140, s50, v202
	v_add_u32_e32 v156, s51, v202
	ds_read_b128 v[128:131], v140
	ds_read_b128 v[132:135], v140 offset:1024
	ds_read_b128 v[136:139], v140 offset:2048
	ds_read_b128 v[140:143], v140 offset:3072
	ds_read_b128 v[144:147], v156
	ds_read_b128 v[148:151], v156 offset:1024
	ds_read_b128 v[152:155], v156 offset:2048
	ds_read_b128 v[156:159], v156 offset:3072
	s_add_u32 s48, s92, 0x40000
	s_addc_u32 s49, s93, 0
	s_mov_b32 m0, s35
	v_lshl_add_u64 v[170:171], s[48:49], 0, v[180:181]
	ds_read_b128 v[188:191], v204 offset:32768
	ds_read_b128 v[192:195], v204 offset:33792
	ds_read_b128 v[196:199], v204 offset:34816
	ds_read_b128 v[206:209], v204 offset:35840
	ds_read_b128 v[210:213], v204 offset:36864
	ds_read_b128 v[214:217], v204 offset:37888
	ds_read_b128 v[238:241], v204 offset:38912
	ds_read_b128 v[246:249], v204 offset:39936
	global_load_lds_dwordx4 v[170:171], off
	v_lshl_add_u64 v[170:171], s[48:49], 0, v[176:177]
	s_mov_b32 m0, s90
	s_nop 0
	global_load_lds_dwordx4 v[170:171], off
	s_waitcnt vmcnt(8)
	s_waitcnt lgkmcnt(0)
	s_barrier
	s_waitcnt lgkmcnt(0)
	v_mfma_f32_16x16x32_bf16 v[124:127], v[128:131], v[188:191], v[124:127]
	v_mfma_f32_16x16x32_bf16 v[120:123], v[136:139], v[188:191], v[120:123]
	v_mfma_f32_16x16x32_bf16 v[108:111], v[128:131], v[196:199], v[108:111]
	v_mfma_f32_16x16x32_bf16 v[104:107], v[136:139], v[196:199], v[104:107]
	v_mfma_f32_16x16x32_bf16 v[92:95], v[128:131], v[210:213], v[92:95]
	v_mfma_f32_16x16x32_bf16 v[88:91], v[136:139], v[210:213], v[88:91]
	v_mfma_f32_16x16x32_bf16 v[76:79], v[128:131], v[238:241], v[76:79]
	v_mfma_f32_16x16x32_bf16 v[72:75], v[136:139], v[238:241], v[72:75]
	v_mfma_f32_16x16x32_bf16 v[124:127], v[132:135], v[192:195], v[124:127]
	v_mfma_f32_16x16x32_bf16 v[120:123], v[140:143], v[192:195], v[120:123]
	v_mfma_f32_16x16x32_bf16 v[108:111], v[132:135], v[206:209], v[108:111]
	v_mfma_f32_16x16x32_bf16 v[104:107], v[140:143], v[206:209], v[104:107]
	v_mfma_f32_16x16x32_bf16 v[92:95], v[132:135], v[214:217], v[92:95]
	v_mfma_f32_16x16x32_bf16 v[88:91], v[140:143], v[214:217], v[88:91]
	v_mfma_f32_16x16x32_bf16 v[76:79], v[132:135], v[246:249], v[76:79]
	v_mfma_f32_16x16x32_bf16 v[72:75], v[140:143], v[246:249], v[72:75]
	v_mfma_f32_16x16x32_bf16 v[116:119], v[144:147], v[188:191], v[116:119]
	v_mfma_f32_16x16x32_bf16 v[112:115], v[152:155], v[188:191], v[112:115]
	v_mfma_f32_16x16x32_bf16 v[100:103], v[144:147], v[196:199], v[100:103]
	v_mfma_f32_16x16x32_bf16 v[96:99], v[152:155], v[196:199], v[96:99]
	v_mfma_f32_16x16x32_bf16 v[84:87], v[144:147], v[210:213], v[84:87]
	v_mfma_f32_16x16x32_bf16 v[80:83], v[152:155], v[210:213], v[80:83]
	v_mfma_f32_16x16x32_bf16 v[68:71], v[144:147], v[238:241], v[68:71]
	v_mfma_f32_16x16x32_bf16 v[64:67], v[152:155], v[238:241], v[64:67]
	v_mfma_f32_16x16x32_bf16 v[116:119], v[148:151], v[192:195], v[116:119]
	v_mfma_f32_16x16x32_bf16 v[112:115], v[156:159], v[192:195], v[112:115]
	v_mfma_f32_16x16x32_bf16 v[100:103], v[148:151], v[206:209], v[100:103]
	v_mfma_f32_16x16x32_bf16 v[96:99], v[156:159], v[206:209], v[96:99]
	v_mfma_f32_16x16x32_bf16 v[84:87], v[148:151], v[214:217], v[84:87]
	v_mfma_f32_16x16x32_bf16 v[80:83], v[156:159], v[214:217], v[80:83]
	v_mfma_f32_16x16x32_bf16 v[68:71], v[148:151], v[246:249], v[68:71]
	v_mfma_f32_16x16x32_bf16 v[64:67], v[156:159], v[246:249], v[64:67]
	s_barrier
	s_add_i32 s48, s50, s29
	v_lshl_add_u64 v[162:163], v[162:163], 0, s[88:89]
	s_mov_b32 m0, s48
	ds_read_b128 v[188:191], v204 offset:49152
	ds_read_b128 v[192:195], v204 offset:50176
	ds_read_b128 v[196:199], v204 offset:51200
	ds_read_b128 v[206:209], v204 offset:52224
	ds_read_b128 v[210:213], v204 offset:53248
	ds_read_b128 v[214:217], v204 offset:54272
	ds_read_b128 v[238:241], v204 offset:55296
	ds_read_b128 v[246:249], v204 offset:56320
	global_load_lds_dwordx4 v[162:163], off
	s_add_i32 m0, s48, 0x2000
	s_add_u32 s14, s14, 0x40080
	v_lshl_add_u64 v[162:163], v[164:165], 0, s[88:89]
	s_addc_u32 s15, s15, 0
	s_add_i32 s48, s51, s29
	global_load_lds_dwordx4 v[162:163], off
	v_lshl_add_u64 v[162:163], s[14:15], 0, v[178:179]
	s_mov_b32 m0, s48
	s_nop 0
	global_load_lds_dwordx4 v[162:163], off
	v_lshl_add_u64 v[162:163], s[14:15], 0, v[174:175]
	s_add_i32 m0, s48, 0x2000
	s_nop 0
	global_load_lds_dwordx4 v[162:163], off
	v_lshl_add_u64 v[162:163], v[166:167], 0, s[88:89]
	s_mov_b32 m0, s19
	s_nop 0
	global_load_lds_dwordx4 v[162:163], off
	v_lshl_add_u64 v[162:163], v[168:169], 0, s[88:89]
	s_mov_b32 m0, s33
	s_nop 0
	global_load_lds_dwordx4 v[162:163], off
	s_waitcnt vmcnt(8)
	s_waitcnt lgkmcnt(0)
	s_barrier
	s_waitcnt lgkmcnt(0)
	v_mfma_f32_16x16x32_bf16 v[60:63], v[128:131], v[188:191], v[60:63]
	v_mfma_f32_16x16x32_bf16 v[56:59], v[136:139], v[188:191], v[56:59]
	v_mfma_f32_16x16x32_bf16 v[44:47], v[128:131], v[196:199], v[44:47]
	v_mfma_f32_16x16x32_bf16 v[40:43], v[136:139], v[196:199], v[40:43]
	v_mfma_f32_16x16x32_bf16 v[28:31], v[128:131], v[210:213], v[28:31]
	v_mfma_f32_16x16x32_bf16 v[24:27], v[136:139], v[210:213], v[24:27]
	v_mfma_f32_16x16x32_bf16 v[12:15], v[128:131], v[238:241], v[12:15]
	v_mfma_f32_16x16x32_bf16 v[8:11], v[136:139], v[238:241], v[8:11]
	v_mfma_f32_16x16x32_bf16 v[60:63], v[132:135], v[192:195], v[60:63]
	v_mfma_f32_16x16x32_bf16 v[56:59], v[140:143], v[192:195], v[56:59]
	v_mfma_f32_16x16x32_bf16 v[44:47], v[132:135], v[206:209], v[44:47]
	v_mfma_f32_16x16x32_bf16 v[40:43], v[140:143], v[206:209], v[40:43]
	v_mfma_f32_16x16x32_bf16 v[28:31], v[132:135], v[214:217], v[28:31]
	v_mfma_f32_16x16x32_bf16 v[24:27], v[140:143], v[214:217], v[24:27]
	v_mfma_f32_16x16x32_bf16 v[12:15], v[132:135], v[246:249], v[12:15]
	v_mfma_f32_16x16x32_bf16 v[8:11], v[140:143], v[246:249], v[8:11]
	v_mfma_f32_16x16x32_bf16 v[52:55], v[144:147], v[188:191], v[52:55]
	v_mfma_f32_16x16x32_bf16 v[48:51], v[152:155], v[188:191], v[48:51]
	v_mfma_f32_16x16x32_bf16 v[36:39], v[144:147], v[196:199], v[36:39]
	v_mfma_f32_16x16x32_bf16 v[32:35], v[152:155], v[196:199], v[32:35]
	v_mfma_f32_16x16x32_bf16 v[20:23], v[144:147], v[210:213], v[20:23]
	v_mfma_f32_16x16x32_bf16 v[16:19], v[152:155], v[210:213], v[16:19]
	v_mfma_f32_16x16x32_bf16 v[4:7], v[144:147], v[238:241], v[4:7]
	v_mfma_f32_16x16x32_bf16 v[0:3], v[152:155], v[238:241], v[0:3]
	v_mfma_f32_16x16x32_bf16 v[52:55], v[148:151], v[192:195], v[52:55]
	v_mfma_f32_16x16x32_bf16 v[48:51], v[156:159], v[192:195], v[48:51]
	v_mfma_f32_16x16x32_bf16 v[36:39], v[148:151], v[206:209], v[36:39]
	v_mfma_f32_16x16x32_bf16 v[32:35], v[156:159], v[206:209], v[32:35]
	v_mfma_f32_16x16x32_bf16 v[20:23], v[148:151], v[214:217], v[20:23]
	v_mfma_f32_16x16x32_bf16 v[16:19], v[156:159], v[214:217], v[16:19]
	v_mfma_f32_16x16x32_bf16 v[4:7], v[148:151], v[246:249], v[4:7]
	v_mfma_f32_16x16x32_bf16 v[0:3], v[156:159], v[246:249], v[0:3]
	s_barrier
	s_add_i32 s22, s22, 2
	s_add_u32 vcc_hi, vcc_hi, 0x100
	s_addc_u32 s21, s21, 0
	s_add_u32 s10, s10, 0x100
	s_addc_u32 s11, s11, 0
	s_cmp_gt_u32 s22, 13
	s_cbranch_scc0 .LBB0_139
	s_and_b64 vcc, exec, s[36:37]
	s_cbranch_vccz .LBB0_142
	s_barrier

.LBB0_178:
	s_add_u32 s10, s8, 0x100
	s_addc_u32 s11, s9, 0
	s_add_i32 s48, 0, 0x10000
	s_cmp_eq_u32 s22, 40
	s_cselect_b32 s15, s1, s11
	s_cselect_b32 s14, s0, s10
	s_cselect_b32 s13, s45, s96
	s_cselect_b32 s12, s44, s21
	s_add_i32 s49, 0, 0x14000
	v_add_u32_e32 v154, s48, v143
	v_add_u32_e32 v158, s49, v143
	ds_read_b128 v[138:141], v154
	ds_read_b128 v[146:149], v154 offset:1024
	ds_read_b128 v[150:153], v154 offset:2048
	ds_read_b128 v[154:157], v154 offset:3072
	ds_read_b128 v[174:177], v158
	ds_read_b128 v[178:181], v158 offset:1024
	ds_read_b128 v[182:185], v158 offset:2048
	ds_read_b128 v[186:189], v158 offset:3072
	v_lshl_add_u64 v[158:159], s[8:9], 0, v[136:137]
	s_add_i32 m0, s29, 0xc000
	ds_read_b128 v[190:193], v145
	ds_read_b128 v[194:197], v145 offset:1024
	ds_read_b128 v[198:201], v145 offset:2048
	ds_read_b128 v[202:205], v145 offset:3072
	ds_read_b128 v[206:209], v145 offset:4096
	ds_read_b128 v[210:213], v145 offset:5120
	ds_read_b128 v[214:217], v145 offset:6144
	ds_read_b128 v[238:241], v145 offset:7168
	global_load_lds_dwordx4 v[158:159], off
	v_lshl_add_u64 v[158:159], s[8:9], 0, v[134:135]
	s_add_i32 m0, s29, 0xe000
	s_nop 0
	global_load_lds_dwordx4 v[158:159], off
	s_waitcnt vmcnt(8)
	s_waitcnt lgkmcnt(0)
	s_barrier
	s_waitcnt lgkmcnt(0)
	v_mfma_f32_16x16x32_bf16 v[124:127], v[138:141], v[190:193], v[124:127]
	v_mfma_f32_16x16x32_bf16 v[120:123], v[150:153], v[190:193], v[120:123]
	v_mfma_f32_16x16x32_bf16 v[108:111], v[138:141], v[198:201], v[108:111]
	v_mfma_f32_16x16x32_bf16 v[104:107], v[150:153], v[198:201], v[104:107]
	v_mfma_f32_16x16x32_bf16 v[92:95], v[138:141], v[206:209], v[92:95]
	v_mfma_f32_16x16x32_bf16 v[88:91], v[150:153], v[206:209], v[88:91]
	v_mfma_f32_16x16x32_bf16 v[76:79], v[138:141], v[214:217], v[76:79]
	v_mfma_f32_16x16x32_bf16 v[72:75], v[150:153], v[214:217], v[72:75]
	v_mfma_f32_16x16x32_bf16 v[124:127], v[146:149], v[194:197], v[124:127]
	v_mfma_f32_16x16x32_bf16 v[120:123], v[154:157], v[194:197], v[120:123]
	v_mfma_f32_16x16x32_bf16 v[108:111], v[146:149], v[202:205], v[108:111]
	v_mfma_f32_16x16x32_bf16 v[104:107], v[154:157], v[202:205], v[104:107]
	v_mfma_f32_16x16x32_bf16 v[92:95], v[146:149], v[210:213], v[92:95]
	v_mfma_f32_16x16x32_bf16 v[88:91], v[154:157], v[210:213], v[88:91]
	v_mfma_f32_16x16x32_bf16 v[76:79], v[146:149], v[238:241], v[76:79]
	v_mfma_f32_16x16x32_bf16 v[72:75], v[154:157], v[238:241], v[72:75]
	v_mfma_f32_16x16x32_bf16 v[116:119], v[174:177], v[190:193], v[116:119]
	v_mfma_f32_16x16x32_bf16 v[112:115], v[182:185], v[190:193], v[112:115]
	v_mfma_f32_16x16x32_bf16 v[100:103], v[174:177], v[198:201], v[100:103]
	v_mfma_f32_16x16x32_bf16 v[96:99], v[182:185], v[198:201], v[96:99]
	v_mfma_f32_16x16x32_bf16 v[84:87], v[174:177], v[206:209], v[84:87]
	v_mfma_f32_16x16x32_bf16 v[80:83], v[182:185], v[206:209], v[80:83]
	v_mfma_f32_16x16x32_bf16 v[68:71], v[174:177], v[214:217], v[68:71]
	v_mfma_f32_16x16x32_bf16 v[64:67], v[182:185], v[214:217], v[64:67]
	v_mfma_f32_16x16x32_bf16 v[116:119], v[178:181], v[194:197], v[116:119]
	v_mfma_f32_16x16x32_bf16 v[112:115], v[186:189], v[194:197], v[112:115]
	v_mfma_f32_16x16x32_bf16 v[100:103], v[178:181], v[202:205], v[100:103]
	v_mfma_f32_16x16x32_bf16 v[96:99], v[186:189], v[202:205], v[96:99]
	v_mfma_f32_16x16x32_bf16 v[84:87], v[178:181], v[210:213], v[84:87]
	v_mfma_f32_16x16x32_bf16 v[80:83], v[186:189], v[210:213], v[80:83]
	v_mfma_f32_16x16x32_bf16 v[68:71], v[178:181], v[238:241], v[68:71]
	v_mfma_f32_16x16x32_bf16 v[64:67], v[186:189], v[238:241], v[64:67]
	s_barrier
	s_add_i32 s8, s48, s28
	v_lshl_add_u64 v[158:159], s[12:13], 0, v[160:161]
	s_mov_b32 m0, s8
	ds_read_b128 v[190:193], v145 offset:16384
	ds_read_b128 v[194:197], v145 offset:17408
	ds_read_b128 v[198:201], v145 offset:18432
	ds_read_b128 v[202:205], v145 offset:19456
	ds_read_b128 v[206:209], v145 offset:20480
	ds_read_b128 v[210:213], v145 offset:21504
	ds_read_b128 v[214:217], v145 offset:22528
	ds_read_b128 v[238:241], v145 offset:23552
	global_load_lds_dwordx4 v[158:159], off
	s_add_i32 m0, s8, 0x2000
	s_add_u32 s8, s12, 0xb0000
	v_lshl_add_u64 v[162:163], s[12:13], 0, v[132:133]
	s_addc_u32 s9, s13, 0
	s_add_i32 s48, s49, s28
	global_load_lds_dwordx4 v[162:163], off
	v_lshl_add_u64 v[164:165], s[8:9], 0, v[160:161]
	s_mov_b32 m0, s48
	v_lshl_add_u64 v[166:167], s[14:15], 0, v[130:131]
	global_load_lds_dwordx4 v[164:165], off
	v_lshl_add_u64 v[164:165], s[8:9], 0, v[132:133]
	s_add_i32 m0, s48, 0x2000
	s_nop 0
	global_load_lds_dwordx4 v[164:165], off
	v_lshl_add_u64 v[164:165], s[14:15], 0, v[128:129]
	s_mov_b32 m0, s29
	s_nop 0
	global_load_lds_dwordx4 v[164:165], off
	s_mov_b32 m0, s30
	s_nop 0
	global_load_lds_dwordx4 v[166:167], off
	s_waitcnt vmcnt(8)
	s_waitcnt lgkmcnt(0)
	s_barrier
	s_waitcnt lgkmcnt(0)
	v_mfma_f32_16x16x32_bf16 v[60:63], v[138:141], v[190:193], v[60:63]
	v_mfma_f32_16x16x32_bf16 v[56:59], v[150:153], v[190:193], v[56:59]
	v_mfma_f32_16x16x32_bf16 v[44:47], v[138:141], v[198:201], v[44:47]
	v_mfma_f32_16x16x32_bf16 v[40:43], v[150:153], v[198:201], v[40:43]
	v_mfma_f32_16x16x32_bf16 v[28:31], v[138:141], v[206:209], v[28:31]
	v_mfma_f32_16x16x32_bf16 v[24:27], v[150:153], v[206:209], v[24:27]
	v_mfma_f32_16x16x32_bf16 v[12:15], v[138:141], v[214:217], v[12:15]
	v_mfma_f32_16x16x32_bf16 v[8:11], v[150:153], v[214:217], v[8:11]
	v_mfma_f32_16x16x32_bf16 v[60:63], v[146:149], v[194:197], v[60:63]
	v_mfma_f32_16x16x32_bf16 v[56:59], v[154:157], v[194:197], v[56:59]
	v_mfma_f32_16x16x32_bf16 v[44:47], v[146:149], v[202:205], v[44:47]
	v_mfma_f32_16x16x32_bf16 v[40:43], v[154:157], v[202:205], v[40:43]
	v_mfma_f32_16x16x32_bf16 v[28:31], v[146:149], v[210:213], v[28:31]
	v_mfma_f32_16x16x32_bf16 v[24:27], v[154:157], v[210:213], v[24:27]
	v_mfma_f32_16x16x32_bf16 v[12:15], v[146:149], v[238:241], v[12:15]
	v_mfma_f32_16x16x32_bf16 v[8:11], v[154:157], v[238:241], v[8:11]
	v_mfma_f32_16x16x32_bf16 v[52:55], v[174:177], v[190:193], v[52:55]
	v_mfma_f32_16x16x32_bf16 v[48:51], v[182:185], v[190:193], v[48:51]
	v_mfma_f32_16x16x32_bf16 v[36:39], v[174:177], v[198:201], v[36:39]
	v_mfma_f32_16x16x32_bf16 v[32:35], v[182:185], v[198:201], v[32:35]
	v_mfma_f32_16x16x32_bf16 v[20:23], v[174:177], v[206:209], v[20:23]
	v_mfma_f32_16x16x32_bf16 v[16:19], v[182:185], v[206:209], v[16:19]
	v_mfma_f32_16x16x32_bf16 v[4:7], v[174:177], v[214:217], v[4:7]
	v_mfma_f32_16x16x32_bf16 v[0:3], v[182:185], v[214:217], v[0:3]
	v_mfma_f32_16x16x32_bf16 v[52:55], v[178:181], v[194:197], v[52:55]
	v_mfma_f32_16x16x32_bf16 v[48:51], v[186:189], v[194:197], v[48:51]
	v_mfma_f32_16x16x32_bf16 v[36:39], v[178:181], v[202:205], v[36:39]
	v_mfma_f32_16x16x32_bf16 v[32:35], v[186:189], v[202:205], v[32:35]
	v_mfma_f32_16x16x32_bf16 v[20:23], v[178:181], v[210:213], v[20:23]
	v_mfma_f32_16x16x32_bf16 v[16:19], v[186:189], v[210:213], v[16:19]
	v_mfma_f32_16x16x32_bf16 v[4:7], v[178:181], v[238:241], v[4:7]
	v_mfma_f32_16x16x32_bf16 v[0:3], v[186:189], v[238:241], v[0:3]
	s_barrier
	s_add_i32 s48, 0, 0x18000
	s_add_i32 s49, 0, 0x1c000
	v_add_u32_e32 v154, s48, v143
	v_add_u32_e32 v168, s49, v143
	ds_read_b128 v[138:141], v154
	ds_read_b128 v[146:149], v154 offset:1024
	ds_read_b128 v[150:153], v154 offset:2048
	ds_read_b128 v[154:157], v154 offset:3072
	ds_read_b128 v[174:177], v168
	ds_read_b128 v[178:181], v168 offset:1024
	ds_read_b128 v[182:185], v168 offset:2048
	ds_read_b128 v[186:189], v168 offset:3072
	s_add_u32 s8, s14, 0xb0000
	s_addc_u32 s9, s15, 0
	s_mov_b32 m0, s31
	v_lshl_add_u64 v[168:169], s[8:9], 0, v[128:129]
	ds_read_b128 v[190:193], v145 offset:32768
	ds_read_b128 v[194:197], v145 offset:33792
	ds_read_b128 v[198:201], v145 offset:34816
	ds_read_b128 v[202:205], v145 offset:35840
	ds_read_b128 v[206:209], v145 offset:36864
	ds_read_b128 v[210:213], v145 offset:37888
	ds_read_b128 v[214:217], v145 offset:38912
	ds_read_b128 v[238:241], v145 offset:39936
	global_load_lds_dwordx4 v[168:169], off
	v_lshl_add_u64 v[168:169], s[8:9], 0, v[130:131]
	s_mov_b32 m0, s33
	s_nop 0
	global_load_lds_dwordx4 v[168:169], off
	s_waitcnt vmcnt(8)
	s_waitcnt lgkmcnt(0)
	s_barrier
	s_waitcnt lgkmcnt(0)
	v_mfma_f32_16x16x32_bf16 v[124:127], v[138:141], v[190:193], v[124:127]
	v_mfma_f32_16x16x32_bf16 v[120:123], v[150:153], v[190:193], v[120:123]
	v_mfma_f32_16x16x32_bf16 v[108:111], v[138:141], v[198:201], v[108:111]
	v_mfma_f32_16x16x32_bf16 v[104:107], v[150:153], v[198:201], v[104:107]
	v_mfma_f32_16x16x32_bf16 v[92:95], v[138:141], v[206:209], v[92:95]
	v_mfma_f32_16x16x32_bf16 v[88:91], v[150:153], v[206:209], v[88:91]
	v_mfma_f32_16x16x32_bf16 v[76:79], v[138:141], v[214:217], v[76:79]
	v_mfma_f32_16x16x32_bf16 v[72:75], v[150:153], v[214:217], v[72:75]
	v_mfma_f32_16x16x32_bf16 v[124:127], v[146:149], v[194:197], v[124:127]
	v_mfma_f32_16x16x32_bf16 v[120:123], v[154:157], v[194:197], v[120:123]
	v_mfma_f32_16x16x32_bf16 v[108:111], v[146:149], v[202:205], v[108:111]
	v_mfma_f32_16x16x32_bf16 v[104:107], v[154:157], v[202:205], v[104:107]
	v_mfma_f32_16x16x32_bf16 v[92:95], v[146:149], v[210:213], v[92:95]
	v_mfma_f32_16x16x32_bf16 v[88:91], v[154:157], v[210:213], v[88:91]
	v_mfma_f32_16x16x32_bf16 v[76:79], v[146:149], v[238:241], v[76:79]
	v_mfma_f32_16x16x32_bf16 v[72:75], v[154:157], v[238:241], v[72:75]
	v_mfma_f32_16x16x32_bf16 v[116:119], v[174:177], v[190:193], v[116:119]
	v_mfma_f32_16x16x32_bf16 v[112:115], v[182:185], v[190:193], v[112:115]
	v_mfma_f32_16x16x32_bf16 v[100:103], v[174:177], v[198:201], v[100:103]
	v_mfma_f32_16x16x32_bf16 v[96:99], v[182:185], v[198:201], v[96:99]
	v_mfma_f32_16x16x32_bf16 v[84:87], v[174:177], v[206:209], v[84:87]
	v_mfma_f32_16x16x32_bf16 v[80:83], v[182:185], v[206:209], v[80:83]
	v_mfma_f32_16x16x32_bf16 v[68:71], v[174:177], v[214:217], v[68:71]
	v_mfma_f32_16x16x32_bf16 v[64:67], v[182:185], v[214:217], v[64:67]
	v_mfma_f32_16x16x32_bf16 v[116:119], v[178:181], v[194:197], v[116:119]
	v_mfma_f32_16x16x32_bf16 v[112:115], v[186:189], v[194:197], v[112:115]
	v_mfma_f32_16x16x32_bf16 v[100:103], v[178:181], v[202:205], v[100:103]
	v_mfma_f32_16x16x32_bf16 v[96:99], v[186:189], v[202:205], v[96:99]
	v_mfma_f32_16x16x32_bf16 v[84:87], v[178:181], v[210:213], v[84:87]
	v_mfma_f32_16x16x32_bf16 v[80:83], v[186:189], v[210:213], v[80:83]
	v_mfma_f32_16x16x32_bf16 v[68:71], v[178:181], v[238:241], v[68:71]
	v_mfma_f32_16x16x32_bf16 v[64:67], v[186:189], v[238:241], v[64:67]
	s_barrier
	s_add_i32 s8, s48, s28
	v_lshl_add_u64 v[158:159], v[158:159], 0, s[88:89]
	s_mov_b32 m0, s8
	ds_read_b128 v[190:193], v145 offset:49152
	ds_read_b128 v[194:197], v145 offset:50176
	ds_read_b128 v[198:201], v145 offset:51200
	ds_read_b128 v[202:205], v145 offset:52224
	ds_read_b128 v[206:209], v145 offset:53248
	ds_read_b128 v[210:213], v145 offset:54272
	ds_read_b128 v[214:217], v145 offset:55296
	ds_read_b128 v[238:241], v145 offset:56320
	global_load_lds_dwordx4 v[158:159], off
	s_add_i32 m0, s8, 0x2000
	s_add_u32 s8, s12, 0xb0080
	v_lshl_add_u64 v[158:159], v[162:163], 0, s[88:89]
	s_addc_u32 s9, s13, 0
	s_add_i32 s12, s49, s28
	global_load_lds_dwordx4 v[158:159], off
	v_lshl_add_u64 v[158:159], s[8:9], 0, v[160:161]
	s_mov_b32 m0, s12
	s_nop 0
	global_load_lds_dwordx4 v[158:159], off
	v_lshl_add_u64 v[158:159], s[8:9], 0, v[132:133]
	s_add_i32 m0, s12, 0x2000
	s_nop 0
	global_load_lds_dwordx4 v[158:159], off
	v_lshl_add_u64 v[158:159], v[164:165], 0, s[88:89]
	s_mov_b32 m0, s34
	s_nop 0
	global_load_lds_dwordx4 v[158:159], off
	v_lshl_add_u64 v[158:159], v[166:167], 0, s[88:89]
	s_mov_b32 m0, s35
	s_nop 0
	global_load_lds_dwordx4 v[158:159], off
	s_waitcnt vmcnt(8)
	s_waitcnt lgkmcnt(0)
	s_barrier
	s_waitcnt lgkmcnt(0)
	v_mfma_f32_16x16x32_bf16 v[60:63], v[138:141], v[190:193], v[60:63]
	v_mfma_f32_16x16x32_bf16 v[56:59], v[150:153], v[190:193], v[56:59]
	v_mfma_f32_16x16x32_bf16 v[44:47], v[138:141], v[198:201], v[44:47]
	v_mfma_f32_16x16x32_bf16 v[40:43], v[150:153], v[198:201], v[40:43]
	v_mfma_f32_16x16x32_bf16 v[28:31], v[138:141], v[206:209], v[28:31]
	v_mfma_f32_16x16x32_bf16 v[24:27], v[150:153], v[206:209], v[24:27]
	v_mfma_f32_16x16x32_bf16 v[12:15], v[138:141], v[214:217], v[12:15]
	v_mfma_f32_16x16x32_bf16 v[8:11], v[150:153], v[214:217], v[8:11]
	v_mfma_f32_16x16x32_bf16 v[60:63], v[146:149], v[194:197], v[60:63]
	v_mfma_f32_16x16x32_bf16 v[56:59], v[154:157], v[194:197], v[56:59]
	v_mfma_f32_16x16x32_bf16 v[44:47], v[146:149], v[202:205], v[44:47]
	v_mfma_f32_16x16x32_bf16 v[40:43], v[154:157], v[202:205], v[40:43]
	v_mfma_f32_16x16x32_bf16 v[28:31], v[146:149], v[210:213], v[28:31]
	v_mfma_f32_16x16x32_bf16 v[24:27], v[154:157], v[210:213], v[24:27]
	v_mfma_f32_16x16x32_bf16 v[12:15], v[146:149], v[238:241], v[12:15]
	v_mfma_f32_16x16x32_bf16 v[8:11], v[154:157], v[238:241], v[8:11]
	v_mfma_f32_16x16x32_bf16 v[52:55], v[174:177], v[190:193], v[52:55]
	v_mfma_f32_16x16x32_bf16 v[48:51], v[182:185], v[190:193], v[48:51]
	v_mfma_f32_16x16x32_bf16 v[36:39], v[174:177], v[198:201], v[36:39]
	v_mfma_f32_16x16x32_bf16 v[32:35], v[182:185], v[198:201], v[32:35]
	v_mfma_f32_16x16x32_bf16 v[20:23], v[174:177], v[206:209], v[20:23]
	v_mfma_f32_16x16x32_bf16 v[16:19], v[182:185], v[206:209], v[16:19]
	v_mfma_f32_16x16x32_bf16 v[4:7], v[174:177], v[214:217], v[4:7]
	v_mfma_f32_16x16x32_bf16 v[0:3], v[182:185], v[214:217], v[0:3]
	v_mfma_f32_16x16x32_bf16 v[52:55], v[178:181], v[194:197], v[52:55]
	v_mfma_f32_16x16x32_bf16 v[48:51], v[186:189], v[194:197], v[48:51]
	v_mfma_f32_16x16x32_bf16 v[36:39], v[178:181], v[202:205], v[36:39]
	v_mfma_f32_16x16x32_bf16 v[32:35], v[186:189], v[202:205], v[32:35]
	v_mfma_f32_16x16x32_bf16 v[20:23], v[178:181], v[210:213], v[20:23]
	v_mfma_f32_16x16x32_bf16 v[16:19], v[186:189], v[210:213], v[16:19]
	v_mfma_f32_16x16x32_bf16 v[4:7], v[178:181], v[238:241], v[4:7]
	v_mfma_f32_16x16x32_bf16 v[0:3], v[186:189], v[238:241], v[0:3]
	s_barrier
	s_add_i32 s22, s22, 2
	s_add_u32 s21, s21, 0x100
	s_addc_u32 s96, s96, 0
	s_cmp_gt_u32 s22, 41
	s_mov_b64 s[8:9], s[10:11]
	s_cbranch_scc0 .LBB0_178
	v_lshl_add_u32 v140, s20, 8, v142
	v_lshl_or_b32 v138, s93, 8, v144
	v_lshlrev_b32_e32 v141, 11, v140
	v_lshl_add_u32 v138, v138, 1, v141
	v_lshlrev_b32_e32 v139, 3, v140
	s_mov_b64 s[8:9], s[4:5]
	global_load_dwordx4 v[146:149], v138, s[8:9]
	global_load_dwordx4 v[150:153], v138, s[8:9] offset:256
	s_add_u32 s8, s8, 0x8000
	s_addc_u32 s9, s9, 0
	global_load_dwordx4 v[154:157], v138, s[8:9]
	global_load_dwordx4 v[162:165], v138, s[8:9] offset:256
	s_add_u32 s8, s8, 0x8000
	s_addc_u32 s9, s9, 0
	global_load_dwordx4 v[166:169], v138, s[8:9]
	global_load_dwordx4 v[174:177], v138, s[8:9] offset:256
	s_add_u32 s8, s8, 0x8000
	s_addc_u32 s9, s9, 0
	global_load_dwordx4 v[178:181], v138, s[8:9]
	global_load_dwordx4 v[182:185], v138, s[8:9] offset:256
	s_add_u32 s8, s8, 0x28000
	s_addc_u32 s9, s9, 0
	global_load_dwordx4 v[186:189], v138, s[8:9]
	global_load_dwordx4 v[190:193], v138, s[8:9] offset:256
	s_add_u32 s8, s8, 0x8000
	s_addc_u32 s9, s9, 0
	global_load_dwordx4 v[194:197], v138, s[8:9]
	global_load_dwordx4 v[198:201], v138, s[8:9] offset:256
	s_add_u32 s8, s8, 0x8000
	s_addc_u32 s9, s9, 0
	global_load_dwordx4 v[202:205], v138, s[8:9]
	global_load_dwordx4 v[206:209], v138, s[8:9] offset:256
	s_add_u32 s8, s8, 0x8000
	s_addc_u32 s9, s9, 0
	global_load_dwordx4 v[210:213], v138, s[8:9]
	global_load_dwordx4 v[214:217], v138, s[8:9] offset:256
	s_and_b64 vcc, exec, s[36:37]
	s_cbranch_vccz .LBB0_181
	s_barrier

.LBB0_212:
	s_add_u32 s12, s10, 0xfffc0080
	s_addc_u32 s13, s11, -1
	s_add_i32 s22, 0, 0x10000
	s_cmp_eq_u32 s21, 12
	s_cselect_b32 s15, s20, s13
	s_cselect_b32 s14, s37, s12
	s_cselect_b32 s13, s41, s97
	s_cselect_b32 s12, s91, s96
	s_add_i32 s50, 0, 0x14000
	v_add_u32_e32 v154, s22, v147
	v_add_u32_e32 v158, s50, v147
	ds_read_b128 v[138:141], v154
	ds_read_b128 v[142:145], v154 offset:1024
	ds_read_b128 v[150:153], v154 offset:2048
	ds_read_b128 v[154:157], v154 offset:3072
	ds_read_b128 v[174:177], v158
	ds_read_b128 v[178:181], v158 offset:1024
	ds_read_b128 v[182:185], v158 offset:2048
	ds_read_b128 v[186:189], v158 offset:3072
	v_lshl_add_u64 v[158:159], s[10:11], 0, v[136:137]
	s_add_i32 m0, s30, 0xc000
	ds_read_b128 v[190:193], v149
	ds_read_b128 v[194:197], v149 offset:1024
	ds_read_b128 v[198:201], v149 offset:2048
	ds_read_b128 v[202:205], v149 offset:3072
	ds_read_b128 v[206:209], v149 offset:4096
	ds_read_b128 v[210:213], v149 offset:5120
	ds_read_b128 v[214:217], v149 offset:6144
	ds_read_b128 v[238:241], v149 offset:7168
	global_load_lds_dwordx4 v[158:159], off
	v_lshl_add_u64 v[158:159], s[10:11], 0, v[134:135]
	s_add_i32 m0, s30, 0xe000
	s_nop 0
	global_load_lds_dwordx4 v[158:159], off
	s_waitcnt vmcnt(8)
	s_waitcnt lgkmcnt(0)
	s_barrier
	s_waitcnt lgkmcnt(0)
	v_mfma_f32_16x16x32_bf16 v[124:127], v[138:141], v[190:193], v[124:127]
	v_mfma_f32_16x16x32_bf16 v[116:119], v[150:153], v[190:193], v[116:119]
	v_mfma_f32_16x16x32_bf16 v[108:111], v[138:141], v[198:201], v[108:111]
	v_mfma_f32_16x16x32_bf16 v[100:103], v[150:153], v[198:201], v[100:103]
	v_mfma_f32_16x16x32_bf16 v[92:95], v[138:141], v[206:209], v[92:95]
	v_mfma_f32_16x16x32_bf16 v[84:87], v[150:153], v[206:209], v[84:87]
	v_mfma_f32_16x16x32_bf16 v[76:79], v[138:141], v[214:217], v[76:79]
	v_mfma_f32_16x16x32_bf16 v[64:67], v[150:153], v[214:217], v[64:67]
	v_mfma_f32_16x16x32_bf16 v[124:127], v[142:145], v[194:197], v[124:127]
	v_mfma_f32_16x16x32_bf16 v[116:119], v[154:157], v[194:197], v[116:119]
	v_mfma_f32_16x16x32_bf16 v[108:111], v[142:145], v[202:205], v[108:111]
	v_mfma_f32_16x16x32_bf16 v[100:103], v[154:157], v[202:205], v[100:103]
	v_mfma_f32_16x16x32_bf16 v[92:95], v[142:145], v[210:213], v[92:95]
	v_mfma_f32_16x16x32_bf16 v[84:87], v[154:157], v[210:213], v[84:87]
	v_mfma_f32_16x16x32_bf16 v[76:79], v[142:145], v[238:241], v[76:79]
	v_mfma_f32_16x16x32_bf16 v[64:67], v[154:157], v[238:241], v[64:67]
	v_mfma_f32_16x16x32_bf16 v[120:123], v[174:177], v[190:193], v[120:123]
	v_mfma_f32_16x16x32_bf16 v[112:115], v[182:185], v[190:193], v[112:115]
	v_mfma_f32_16x16x32_bf16 v[104:107], v[174:177], v[198:201], v[104:107]
	v_mfma_f32_16x16x32_bf16 v[96:99], v[182:185], v[198:201], v[96:99]
	v_mfma_f32_16x16x32_bf16 v[88:91], v[174:177], v[206:209], v[88:91]
	v_mfma_f32_16x16x32_bf16 v[80:83], v[182:185], v[206:209], v[80:83]
	v_mfma_f32_16x16x32_bf16 v[72:75], v[174:177], v[214:217], v[72:75]
	v_mfma_f32_16x16x32_bf16 v[68:71], v[182:185], v[214:217], v[68:71]
	v_mfma_f32_16x16x32_bf16 v[120:123], v[178:181], v[194:197], v[120:123]
	v_mfma_f32_16x16x32_bf16 v[112:115], v[186:189], v[194:197], v[112:115]
	v_mfma_f32_16x16x32_bf16 v[104:107], v[178:181], v[202:205], v[104:107]
	v_mfma_f32_16x16x32_bf16 v[96:99], v[186:189], v[202:205], v[96:99]
	v_mfma_f32_16x16x32_bf16 v[88:91], v[178:181], v[210:213], v[88:91]
	v_mfma_f32_16x16x32_bf16 v[80:83], v[186:189], v[210:213], v[80:83]
	v_mfma_f32_16x16x32_bf16 v[72:75], v[178:181], v[238:241], v[72:75]
	v_mfma_f32_16x16x32_bf16 v[68:71], v[186:189], v[238:241], v[68:71]
	s_barrier
	s_add_i32 s22, s22, s28
	v_lshl_add_u64 v[158:159], s[12:13], 0, v[160:161]
	s_mov_b32 m0, s22
	ds_read_b128 v[190:193], v149 offset:16384
	ds_read_b128 v[194:197], v149 offset:17408
	ds_read_b128 v[198:201], v149 offset:18432
	ds_read_b128 v[202:205], v149 offset:19456
	ds_read_b128 v[206:209], v149 offset:20480
	ds_read_b128 v[210:213], v149 offset:21504
	ds_read_b128 v[214:217], v149 offset:22528
	ds_read_b128 v[238:241], v149 offset:23552
	global_load_lds_dwordx4 v[158:159], off
	s_add_i32 m0, s22, 0x2000
	s_add_u32 s48, s12, 0x40000
	v_lshl_add_u64 v[162:163], s[12:13], 0, v[128:129]
	s_addc_u32 s49, s13, 0
	s_add_i32 s22, s50, s28
	global_load_lds_dwordx4 v[162:163], off
	v_lshl_add_u64 v[164:165], s[48:49], 0, v[160:161]
	s_mov_b32 m0, s22
	v_lshl_add_u64 v[166:167], s[14:15], 0, v[130:131]
	global_load_lds_dwordx4 v[164:165], off
	v_lshl_add_u64 v[164:165], s[48:49], 0, v[128:129]
	s_add_i32 m0, s22, 0x2000
	s_nop 0
	global_load_lds_dwordx4 v[164:165], off
	v_lshl_add_u64 v[164:165], s[14:15], 0, v[132:133]
	s_mov_b32 m0, s30
	s_nop 0
	global_load_lds_dwordx4 v[164:165], off
	s_mov_b32 m0, s31
	s_nop 0
	global_load_lds_dwordx4 v[166:167], off
	s_waitcnt vmcnt(8)
	s_waitcnt lgkmcnt(0)
	s_barrier
	s_waitcnt lgkmcnt(0)
	v_mfma_f32_16x16x32_bf16 v[60:63], v[138:141], v[190:193], v[60:63]
	v_mfma_f32_16x16x32_bf16 v[48:51], v[150:153], v[190:193], v[48:51]
	v_mfma_f32_16x16x32_bf16 v[44:47], v[138:141], v[198:201], v[44:47]
	v_mfma_f32_16x16x32_bf16 v[32:35], v[150:153], v[198:201], v[32:35]
	v_mfma_f32_16x16x32_bf16 v[28:31], v[138:141], v[206:209], v[28:31]
	v_mfma_f32_16x16x32_bf16 v[16:19], v[150:153], v[206:209], v[16:19]
	v_mfma_f32_16x16x32_bf16 v[12:15], v[138:141], v[214:217], v[12:15]
	v_mfma_f32_16x16x32_bf16 v[0:3], v[150:153], v[214:217], v[0:3]
	v_mfma_f32_16x16x32_bf16 v[60:63], v[142:145], v[194:197], v[60:63]
	v_mfma_f32_16x16x32_bf16 v[48:51], v[154:157], v[194:197], v[48:51]
	v_mfma_f32_16x16x32_bf16 v[44:47], v[142:145], v[202:205], v[44:47]
	v_mfma_f32_16x16x32_bf16 v[32:35], v[154:157], v[202:205], v[32:35]
	v_mfma_f32_16x16x32_bf16 v[28:31], v[142:145], v[210:213], v[28:31]
	v_mfma_f32_16x16x32_bf16 v[16:19], v[154:157], v[210:213], v[16:19]
	v_mfma_f32_16x16x32_bf16 v[12:15], v[142:145], v[238:241], v[12:15]
	v_mfma_f32_16x16x32_bf16 v[0:3], v[154:157], v[238:241], v[0:3]
	v_mfma_f32_16x16x32_bf16 v[56:59], v[174:177], v[190:193], v[56:59]
	v_mfma_f32_16x16x32_bf16 v[52:55], v[182:185], v[190:193], v[52:55]
	v_mfma_f32_16x16x32_bf16 v[40:43], v[174:177], v[198:201], v[40:43]
	v_mfma_f32_16x16x32_bf16 v[36:39], v[182:185], v[198:201], v[36:39]
	v_mfma_f32_16x16x32_bf16 v[24:27], v[174:177], v[206:209], v[24:27]
	v_mfma_f32_16x16x32_bf16 v[20:23], v[182:185], v[206:209], v[20:23]
	v_mfma_f32_16x16x32_bf16 v[8:11], v[174:177], v[214:217], v[8:11]
	v_mfma_f32_16x16x32_bf16 v[4:7], v[182:185], v[214:217], v[4:7]
	v_mfma_f32_16x16x32_bf16 v[56:59], v[178:181], v[194:197], v[56:59]
	v_mfma_f32_16x16x32_bf16 v[52:55], v[186:189], v[194:197], v[52:55]
	v_mfma_f32_16x16x32_bf16 v[40:43], v[178:181], v[202:205], v[40:43]
	v_mfma_f32_16x16x32_bf16 v[36:39], v[186:189], v[202:205], v[36:39]
	v_mfma_f32_16x16x32_bf16 v[24:27], v[178:181], v[210:213], v[24:27]
	v_mfma_f32_16x16x32_bf16 v[20:23], v[186:189], v[210:213], v[20:23]
	v_mfma_f32_16x16x32_bf16 v[8:11], v[178:181], v[238:241], v[8:11]
	v_mfma_f32_16x16x32_bf16 v[4:7], v[186:189], v[238:241], v[4:7]
	s_barrier
	s_add_i32 s22, 0, 0x18000
	s_add_i32 s48, 0, 0x1c000
	v_add_u32_e32 v154, s22, v147
	v_add_u32_e32 v168, s48, v147
	ds_read_b128 v[138:141], v154
	ds_read_b128 v[142:145], v154 offset:1024
	ds_read_b128 v[150:153], v154 offset:2048
	ds_read_b128 v[154:157], v154 offset:3072
	ds_read_b128 v[174:177], v168
	ds_read_b128 v[178:181], v168 offset:1024
	ds_read_b128 v[182:185], v168 offset:2048
	ds_read_b128 v[186:189], v168 offset:3072
	s_add_u32 s14, s14, 0x40000
	s_addc_u32 s15, s15, 0
	s_mov_b32 m0, s33
	v_lshl_add_u64 v[168:169], s[14:15], 0, v[132:133]
	ds_read_b128 v[190:193], v149 offset:32768
	ds_read_b128 v[194:197], v149 offset:33792
	ds_read_b128 v[198:201], v149 offset:34816
	ds_read_b128 v[202:205], v149 offset:35840
	ds_read_b128 v[206:209], v149 offset:36864
	ds_read_b128 v[210:213], v149 offset:37888
	ds_read_b128 v[214:217], v149 offset:38912
	ds_read_b128 v[238:241], v149 offset:39936
	global_load_lds_dwordx4 v[168:169], off
	v_lshl_add_u64 v[168:169], s[14:15], 0, v[130:131]
	s_mov_b32 m0, s34
	s_nop 0
	global_load_lds_dwordx4 v[168:169], off
	s_waitcnt vmcnt(8)
	s_waitcnt lgkmcnt(0)
	s_barrier
	s_waitcnt lgkmcnt(0)
	v_mfma_f32_16x16x32_bf16 v[124:127], v[138:141], v[190:193], v[124:127]
	v_mfma_f32_16x16x32_bf16 v[116:119], v[150:153], v[190:193], v[116:119]
	v_mfma_f32_16x16x32_bf16 v[108:111], v[138:141], v[198:201], v[108:111]
	v_mfma_f32_16x16x32_bf16 v[100:103], v[150:153], v[198:201], v[100:103]
	v_mfma_f32_16x16x32_bf16 v[92:95], v[138:141], v[206:209], v[92:95]
	v_mfma_f32_16x16x32_bf16 v[84:87], v[150:153], v[206:209], v[84:87]
	v_mfma_f32_16x16x32_bf16 v[76:79], v[138:141], v[214:217], v[76:79]
	v_mfma_f32_16x16x32_bf16 v[64:67], v[150:153], v[214:217], v[64:67]
	v_mfma_f32_16x16x32_bf16 v[124:127], v[142:145], v[194:197], v[124:127]
	v_mfma_f32_16x16x32_bf16 v[116:119], v[154:157], v[194:197], v[116:119]
	v_mfma_f32_16x16x32_bf16 v[108:111], v[142:145], v[202:205], v[108:111]
	v_mfma_f32_16x16x32_bf16 v[100:103], v[154:157], v[202:205], v[100:103]
	v_mfma_f32_16x16x32_bf16 v[92:95], v[142:145], v[210:213], v[92:95]
	v_mfma_f32_16x16x32_bf16 v[84:87], v[154:157], v[210:213], v[84:87]
	v_mfma_f32_16x16x32_bf16 v[76:79], v[142:145], v[238:241], v[76:79]
	v_mfma_f32_16x16x32_bf16 v[64:67], v[154:157], v[238:241], v[64:67]
	v_mfma_f32_16x16x32_bf16 v[120:123], v[174:177], v[190:193], v[120:123]
	v_mfma_f32_16x16x32_bf16 v[112:115], v[182:185], v[190:193], v[112:115]
	v_mfma_f32_16x16x32_bf16 v[104:107], v[174:177], v[198:201], v[104:107]
	v_mfma_f32_16x16x32_bf16 v[96:99], v[182:185], v[198:201], v[96:99]
	v_mfma_f32_16x16x32_bf16 v[88:91], v[174:177], v[206:209], v[88:91]
	v_mfma_f32_16x16x32_bf16 v[80:83], v[182:185], v[206:209], v[80:83]
	v_mfma_f32_16x16x32_bf16 v[72:75], v[174:177], v[214:217], v[72:75]
	v_mfma_f32_16x16x32_bf16 v[68:71], v[182:185], v[214:217], v[68:71]
	v_mfma_f32_16x16x32_bf16 v[120:123], v[178:181], v[194:197], v[120:123]
	v_mfma_f32_16x16x32_bf16 v[112:115], v[186:189], v[194:197], v[112:115]
	v_mfma_f32_16x16x32_bf16 v[104:107], v[178:181], v[202:205], v[104:107]
	v_mfma_f32_16x16x32_bf16 v[96:99], v[186:189], v[202:205], v[96:99]
	v_mfma_f32_16x16x32_bf16 v[88:91], v[178:181], v[210:213], v[88:91]
	v_mfma_f32_16x16x32_bf16 v[80:83], v[186:189], v[210:213], v[80:83]
	v_mfma_f32_16x16x32_bf16 v[72:75], v[178:181], v[238:241], v[72:75]
	v_mfma_f32_16x16x32_bf16 v[68:71], v[186:189], v[238:241], v[68:71]
	s_barrier
	s_add_i32 s14, s22, s28
	v_lshl_add_u64 v[158:159], v[158:159], 0, s[88:89]
	s_mov_b32 m0, s14
	ds_read_b128 v[190:193], v149 offset:49152
	ds_read_b128 v[194:197], v149 offset:50176
	ds_read_b128 v[198:201], v149 offset:51200
	ds_read_b128 v[202:205], v149 offset:52224
	ds_read_b128 v[206:209], v149 offset:53248
	ds_read_b128 v[210:213], v149 offset:54272
	ds_read_b128 v[214:217], v149 offset:55296
	ds_read_b128 v[238:241], v149 offset:56320
	global_load_lds_dwordx4 v[158:159], off
	s_add_i32 m0, s14, 0x2000
	s_add_u32 s12, s12, 0x40080
	v_lshl_add_u64 v[158:159], v[162:163], 0, s[88:89]
	s_addc_u32 s13, s13, 0
	s_add_i32 s14, s48, s28
	global_load_lds_dwordx4 v[158:159], off
	v_lshl_add_u64 v[158:159], s[12:13], 0, v[160:161]
	s_mov_b32 m0, s14
	s_nop 0
	global_load_lds_dwordx4 v[158:159], off
	v_lshl_add_u64 v[158:159], s[12:13], 0, v[128:129]
	s_add_i32 m0, s14, 0x2000
	s_nop 0
	global_load_lds_dwordx4 v[158:159], off
	v_lshl_add_u64 v[158:159], v[164:165], 0, s[88:89]
	s_mov_b32 m0, s35
	s_nop 0
	global_load_lds_dwordx4 v[158:159], off
	v_lshl_add_u64 v[158:159], v[166:167], 0, s[88:89]
	s_mov_b32 m0, s90
	s_nop 0
	global_load_lds_dwordx4 v[158:159], off
	s_waitcnt vmcnt(8)
	s_waitcnt lgkmcnt(0)
	s_barrier
	s_waitcnt lgkmcnt(0)
	v_mfma_f32_16x16x32_bf16 v[60:63], v[138:141], v[190:193], v[60:63]
	v_mfma_f32_16x16x32_bf16 v[48:51], v[150:153], v[190:193], v[48:51]
	v_mfma_f32_16x16x32_bf16 v[44:47], v[138:141], v[198:201], v[44:47]
	v_mfma_f32_16x16x32_bf16 v[32:35], v[150:153], v[198:201], v[32:35]
	v_mfma_f32_16x16x32_bf16 v[28:31], v[138:141], v[206:209], v[28:31]
	v_mfma_f32_16x16x32_bf16 v[16:19], v[150:153], v[206:209], v[16:19]
	v_mfma_f32_16x16x32_bf16 v[12:15], v[138:141], v[214:217], v[12:15]
	v_mfma_f32_16x16x32_bf16 v[0:3], v[150:153], v[214:217], v[0:3]
	v_mfma_f32_16x16x32_bf16 v[60:63], v[142:145], v[194:197], v[60:63]
	v_mfma_f32_16x16x32_bf16 v[48:51], v[154:157], v[194:197], v[48:51]
	v_mfma_f32_16x16x32_bf16 v[44:47], v[142:145], v[202:205], v[44:47]
	v_mfma_f32_16x16x32_bf16 v[32:35], v[154:157], v[202:205], v[32:35]
	v_mfma_f32_16x16x32_bf16 v[28:31], v[142:145], v[210:213], v[28:31]
	v_mfma_f32_16x16x32_bf16 v[16:19], v[154:157], v[210:213], v[16:19]
	v_mfma_f32_16x16x32_bf16 v[12:15], v[142:145], v[238:241], v[12:15]
	v_mfma_f32_16x16x32_bf16 v[0:3], v[154:157], v[238:241], v[0:3]
	v_mfma_f32_16x16x32_bf16 v[56:59], v[174:177], v[190:193], v[56:59]
	v_mfma_f32_16x16x32_bf16 v[52:55], v[182:185], v[190:193], v[52:55]
	v_mfma_f32_16x16x32_bf16 v[40:43], v[174:177], v[198:201], v[40:43]
	v_mfma_f32_16x16x32_bf16 v[36:39], v[182:185], v[198:201], v[36:39]
	v_mfma_f32_16x16x32_bf16 v[24:27], v[174:177], v[206:209], v[24:27]
	v_mfma_f32_16x16x32_bf16 v[20:23], v[182:185], v[206:209], v[20:23]
	v_mfma_f32_16x16x32_bf16 v[8:11], v[174:177], v[214:217], v[8:11]
	v_mfma_f32_16x16x32_bf16 v[4:7], v[182:185], v[214:217], v[4:7]
	v_mfma_f32_16x16x32_bf16 v[56:59], v[178:181], v[194:197], v[56:59]
	v_mfma_f32_16x16x32_bf16 v[52:55], v[186:189], v[194:197], v[52:55]
	v_mfma_f32_16x16x32_bf16 v[40:43], v[178:181], v[202:205], v[40:43]
	v_mfma_f32_16x16x32_bf16 v[36:39], v[186:189], v[202:205], v[36:39]
	v_mfma_f32_16x16x32_bf16 v[24:27], v[178:181], v[210:213], v[24:27]
	v_mfma_f32_16x16x32_bf16 v[20:23], v[186:189], v[210:213], v[20:23]
	v_mfma_f32_16x16x32_bf16 v[8:11], v[178:181], v[238:241], v[8:11]
	v_mfma_f32_16x16x32_bf16 v[4:7], v[186:189], v[238:241], v[4:7]
	s_barrier
	s_add_i32 s21, s21, 2
	s_add_u32 s96, s96, 0x100
	s_addc_u32 s97, s97, 0
	s_add_u32 s10, s10, 0x100
	s_addc_u32 s11, s11, 0
	s_cmp_gt_u32 s21, 13
	s_cbranch_scc0 .LBB0_212
	v_lshl_add_u32 v192, s8, 8, v146
	v_lshlrev_b32_e32 v192, 3, v192
	global_load_dwordx2 v[176:177], v192, s[4:5]
	global_load_dwordx2 v[178:179], v192, s[4:5] offset:128
	global_load_dwordx2 v[180:181], v192, s[4:5] offset:256
	global_load_dwordx2 v[182:183], v192, s[4:5] offset:384
	global_load_dwordx2 v[184:185], v192, s[4:5] offset:1024
	global_load_dwordx2 v[186:187], v192, s[4:5] offset:1152
	global_load_dwordx2 v[188:189], v192, s[4:5] offset:1280
	global_load_dwordx2 v[190:191], v192, s[4:5] offset:1408
	s_and_b64 vcc, exec, s[6:7]
	s_cbranch_vccz .LBB0_215
	s_barrier

.LBB0_310:
	s_add_u32 s12, vcc_lo, 0xfffc0080
	s_addc_u32 s13, vcc_hi, -1
	s_add_i32 s22, 0, 0x10000
	s_cmp_eq_u32 s21, 12
	s_cselect_b32 s93, s9, s13
	s_cselect_b32 s92, s20, s12
	s_cselect_b32 s13, s11, s91
	s_cselect_b32 s12, s45, s90
	s_add_i32 s50, 0, 0x14000
	v_add_u32_e32 v154, s22, v143
	v_add_u32_e32 v158, s50, v143
	ds_read_b128 v[138:141], v154
	ds_read_b128 v[146:149], v154 offset:1024
	ds_read_b128 v[150:153], v154 offset:2048
	ds_read_b128 v[154:157], v154 offset:3072
	ds_read_b128 v[174:177], v158
	ds_read_b128 v[178:181], v158 offset:1024
	ds_read_b128 v[182:185], v158 offset:2048
	ds_read_b128 v[186:189], v158 offset:3072
	v_lshl_add_u64 v[158:159], vcc, 0, v[136:137]
	s_add_i32 m0, s29, 0xc000
	ds_read_b128 v[190:193], v145
	ds_read_b128 v[194:197], v145 offset:1024
	ds_read_b128 v[198:201], v145 offset:2048
	ds_read_b128 v[202:205], v145 offset:3072
	ds_read_b128 v[206:209], v145 offset:4096
	ds_read_b128 v[210:213], v145 offset:5120
	ds_read_b128 v[214:217], v145 offset:6144
	ds_read_b128 v[238:241], v145 offset:7168
	global_load_lds_dwordx4 v[158:159], off
	v_lshl_add_u64 v[158:159], vcc, 0, v[134:135]
	s_add_i32 m0, s29, 0xe000
	s_nop 0
	global_load_lds_dwordx4 v[158:159], off
	s_waitcnt vmcnt(8)
	s_waitcnt lgkmcnt(0)
	s_barrier
	s_waitcnt lgkmcnt(0)
	v_mfma_f32_16x16x32_bf16 v[124:127], v[138:141], v[190:193], v[124:127]
	v_mfma_f32_16x16x32_bf16 v[120:123], v[150:153], v[190:193], v[120:123]
	v_mfma_f32_16x16x32_bf16 v[108:111], v[138:141], v[198:201], v[108:111]
	v_mfma_f32_16x16x32_bf16 v[104:107], v[150:153], v[198:201], v[104:107]
	v_mfma_f32_16x16x32_bf16 v[92:95], v[138:141], v[206:209], v[92:95]
	v_mfma_f32_16x16x32_bf16 v[88:91], v[150:153], v[206:209], v[88:91]
	v_mfma_f32_16x16x32_bf16 v[76:79], v[138:141], v[214:217], v[76:79]
	v_mfma_f32_16x16x32_bf16 v[72:75], v[150:153], v[214:217], v[72:75]
	v_mfma_f32_16x16x32_bf16 v[124:127], v[146:149], v[194:197], v[124:127]
	v_mfma_f32_16x16x32_bf16 v[120:123], v[154:157], v[194:197], v[120:123]
	v_mfma_f32_16x16x32_bf16 v[108:111], v[146:149], v[202:205], v[108:111]
	v_mfma_f32_16x16x32_bf16 v[104:107], v[154:157], v[202:205], v[104:107]
	v_mfma_f32_16x16x32_bf16 v[92:95], v[146:149], v[210:213], v[92:95]
	v_mfma_f32_16x16x32_bf16 v[88:91], v[154:157], v[210:213], v[88:91]
	v_mfma_f32_16x16x32_bf16 v[76:79], v[146:149], v[238:241], v[76:79]
	v_mfma_f32_16x16x32_bf16 v[72:75], v[154:157], v[238:241], v[72:75]
	v_mfma_f32_16x16x32_bf16 v[116:119], v[174:177], v[190:193], v[116:119]
	v_mfma_f32_16x16x32_bf16 v[112:115], v[182:185], v[190:193], v[112:115]
	v_mfma_f32_16x16x32_bf16 v[100:103], v[174:177], v[198:201], v[100:103]
	v_mfma_f32_16x16x32_bf16 v[96:99], v[182:185], v[198:201], v[96:99]
	v_mfma_f32_16x16x32_bf16 v[84:87], v[174:177], v[206:209], v[84:87]
	v_mfma_f32_16x16x32_bf16 v[80:83], v[182:185], v[206:209], v[80:83]
	v_mfma_f32_16x16x32_bf16 v[68:71], v[174:177], v[214:217], v[68:71]
	v_mfma_f32_16x16x32_bf16 v[64:67], v[182:185], v[214:217], v[64:67]
	v_mfma_f32_16x16x32_bf16 v[116:119], v[178:181], v[194:197], v[116:119]
	v_mfma_f32_16x16x32_bf16 v[112:115], v[186:189], v[194:197], v[112:115]
	v_mfma_f32_16x16x32_bf16 v[100:103], v[178:181], v[202:205], v[100:103]
	v_mfma_f32_16x16x32_bf16 v[96:99], v[186:189], v[202:205], v[96:99]
	v_mfma_f32_16x16x32_bf16 v[84:87], v[178:181], v[210:213], v[84:87]
	v_mfma_f32_16x16x32_bf16 v[80:83], v[186:189], v[210:213], v[80:83]
	v_mfma_f32_16x16x32_bf16 v[68:71], v[178:181], v[238:241], v[68:71]
	v_mfma_f32_16x16x32_bf16 v[64:67], v[186:189], v[238:241], v[64:67]
	s_barrier
	s_add_i32 s22, s22, s28
	v_lshl_add_u64 v[158:159], s[12:13], 0, v[160:161]
	s_mov_b32 m0, s22
	ds_read_b128 v[190:193], v145 offset:16384
	ds_read_b128 v[194:197], v145 offset:17408
	ds_read_b128 v[198:201], v145 offset:18432
	ds_read_b128 v[202:205], v145 offset:19456
	ds_read_b128 v[206:209], v145 offset:20480
	ds_read_b128 v[210:213], v145 offset:21504
	ds_read_b128 v[214:217], v145 offset:22528
	ds_read_b128 v[238:241], v145 offset:23552
	global_load_lds_dwordx4 v[158:159], off
	s_add_i32 m0, s22, 0x2000
	s_add_u32 s48, s12, 0x40000
	v_lshl_add_u64 v[162:163], s[12:13], 0, v[132:133]
	s_addc_u32 s49, s13, 0
	s_add_i32 s22, s50, s28
	global_load_lds_dwordx4 v[162:163], off
	v_lshl_add_u64 v[164:165], s[48:49], 0, v[160:161]
	s_mov_b32 m0, s22
	v_lshl_add_u64 v[166:167], s[92:93], 0, v[130:131]
	global_load_lds_dwordx4 v[164:165], off
	v_lshl_add_u64 v[164:165], s[48:49], 0, v[132:133]
	s_add_i32 m0, s22, 0x2000
	s_nop 0
	global_load_lds_dwordx4 v[164:165], off
	v_lshl_add_u64 v[164:165], s[92:93], 0, v[128:129]
	s_mov_b32 m0, s29
	s_nop 0
	global_load_lds_dwordx4 v[164:165], off
	s_mov_b32 m0, s30
	s_nop 0
	global_load_lds_dwordx4 v[166:167], off
	s_waitcnt vmcnt(8)
	s_waitcnt lgkmcnt(0)
	s_barrier
	s_waitcnt lgkmcnt(0)
	v_mfma_f32_16x16x32_bf16 v[60:63], v[138:141], v[190:193], v[60:63]
	v_mfma_f32_16x16x32_bf16 v[56:59], v[150:153], v[190:193], v[56:59]
	v_mfma_f32_16x16x32_bf16 v[44:47], v[138:141], v[198:201], v[44:47]
	v_mfma_f32_16x16x32_bf16 v[40:43], v[150:153], v[198:201], v[40:43]
	v_mfma_f32_16x16x32_bf16 v[28:31], v[138:141], v[206:209], v[28:31]
	v_mfma_f32_16x16x32_bf16 v[24:27], v[150:153], v[206:209], v[24:27]
	v_mfma_f32_16x16x32_bf16 v[12:15], v[138:141], v[214:217], v[12:15]
	v_mfma_f32_16x16x32_bf16 v[8:11], v[150:153], v[214:217], v[8:11]
	v_mfma_f32_16x16x32_bf16 v[60:63], v[146:149], v[194:197], v[60:63]
	v_mfma_f32_16x16x32_bf16 v[56:59], v[154:157], v[194:197], v[56:59]
	v_mfma_f32_16x16x32_bf16 v[44:47], v[146:149], v[202:205], v[44:47]
	v_mfma_f32_16x16x32_bf16 v[40:43], v[154:157], v[202:205], v[40:43]
	v_mfma_f32_16x16x32_bf16 v[28:31], v[146:149], v[210:213], v[28:31]
	v_mfma_f32_16x16x32_bf16 v[24:27], v[154:157], v[210:213], v[24:27]
	v_mfma_f32_16x16x32_bf16 v[12:15], v[146:149], v[238:241], v[12:15]
	v_mfma_f32_16x16x32_bf16 v[8:11], v[154:157], v[238:241], v[8:11]
	v_mfma_f32_16x16x32_bf16 v[52:55], v[174:177], v[190:193], v[52:55]
	v_mfma_f32_16x16x32_bf16 v[48:51], v[182:185], v[190:193], v[48:51]
	v_mfma_f32_16x16x32_bf16 v[36:39], v[174:177], v[198:201], v[36:39]
	v_mfma_f32_16x16x32_bf16 v[32:35], v[182:185], v[198:201], v[32:35]
	v_mfma_f32_16x16x32_bf16 v[20:23], v[174:177], v[206:209], v[20:23]
	v_mfma_f32_16x16x32_bf16 v[16:19], v[182:185], v[206:209], v[16:19]
	v_mfma_f32_16x16x32_bf16 v[4:7], v[174:177], v[214:217], v[4:7]
	v_mfma_f32_16x16x32_bf16 v[0:3], v[182:185], v[214:217], v[0:3]
	v_mfma_f32_16x16x32_bf16 v[52:55], v[178:181], v[194:197], v[52:55]
	v_mfma_f32_16x16x32_bf16 v[48:51], v[186:189], v[194:197], v[48:51]
	v_mfma_f32_16x16x32_bf16 v[36:39], v[178:181], v[202:205], v[36:39]
	v_mfma_f32_16x16x32_bf16 v[32:35], v[186:189], v[202:205], v[32:35]
	v_mfma_f32_16x16x32_bf16 v[20:23], v[178:181], v[210:213], v[20:23]
	v_mfma_f32_16x16x32_bf16 v[16:19], v[186:189], v[210:213], v[16:19]
	v_mfma_f32_16x16x32_bf16 v[4:7], v[178:181], v[238:241], v[4:7]
	v_mfma_f32_16x16x32_bf16 v[0:3], v[186:189], v[238:241], v[0:3]
	s_barrier
	s_add_i32 s22, 0, 0x18000
	s_add_i32 s50, 0, 0x1c000
	v_add_u32_e32 v154, s22, v143
	v_add_u32_e32 v168, s50, v143
	ds_read_b128 v[138:141], v154
	ds_read_b128 v[146:149], v154 offset:1024
	ds_read_b128 v[150:153], v154 offset:2048
	ds_read_b128 v[154:157], v154 offset:3072
	ds_read_b128 v[174:177], v168
	ds_read_b128 v[178:181], v168 offset:1024
	ds_read_b128 v[182:185], v168 offset:2048
	ds_read_b128 v[186:189], v168 offset:3072
	s_add_u32 s48, s92, 0x40000
	s_addc_u32 s49, s93, 0
	s_mov_b32 m0, s31
	v_lshl_add_u64 v[168:169], s[48:49], 0, v[128:129]
	ds_read_b128 v[190:193], v145 offset:32768
	ds_read_b128 v[194:197], v145 offset:33792
	ds_read_b128 v[198:201], v145 offset:34816
	ds_read_b128 v[202:205], v145 offset:35840
	ds_read_b128 v[206:209], v145 offset:36864
	ds_read_b128 v[210:213], v145 offset:37888
	ds_read_b128 v[214:217], v145 offset:38912
	ds_read_b128 v[238:241], v145 offset:39936
	global_load_lds_dwordx4 v[168:169], off
	v_lshl_add_u64 v[168:169], s[48:49], 0, v[130:131]
	s_mov_b32 m0, s33
	s_nop 0
	global_load_lds_dwordx4 v[168:169], off
	s_waitcnt vmcnt(8)
	s_waitcnt lgkmcnt(0)
	s_barrier
	s_waitcnt lgkmcnt(0)
	v_mfma_f32_16x16x32_bf16 v[124:127], v[138:141], v[190:193], v[124:127]
	v_mfma_f32_16x16x32_bf16 v[120:123], v[150:153], v[190:193], v[120:123]
	v_mfma_f32_16x16x32_bf16 v[108:111], v[138:141], v[198:201], v[108:111]
	v_mfma_f32_16x16x32_bf16 v[104:107], v[150:153], v[198:201], v[104:107]
	v_mfma_f32_16x16x32_bf16 v[92:95], v[138:141], v[206:209], v[92:95]
	v_mfma_f32_16x16x32_bf16 v[88:91], v[150:153], v[206:209], v[88:91]
	v_mfma_f32_16x16x32_bf16 v[76:79], v[138:141], v[214:217], v[76:79]
	v_mfma_f32_16x16x32_bf16 v[72:75], v[150:153], v[214:217], v[72:75]
	v_mfma_f32_16x16x32_bf16 v[124:127], v[146:149], v[194:197], v[124:127]
	v_mfma_f32_16x16x32_bf16 v[120:123], v[154:157], v[194:197], v[120:123]
	v_mfma_f32_16x16x32_bf16 v[108:111], v[146:149], v[202:205], v[108:111]
	v_mfma_f32_16x16x32_bf16 v[104:107], v[154:157], v[202:205], v[104:107]
	v_mfma_f32_16x16x32_bf16 v[92:95], v[146:149], v[210:213], v[92:95]
	v_mfma_f32_16x16x32_bf16 v[88:91], v[154:157], v[210:213], v[88:91]
	v_mfma_f32_16x16x32_bf16 v[76:79], v[146:149], v[238:241], v[76:79]
	v_mfma_f32_16x16x32_bf16 v[72:75], v[154:157], v[238:241], v[72:75]
	v_mfma_f32_16x16x32_bf16 v[116:119], v[174:177], v[190:193], v[116:119]
	v_mfma_f32_16x16x32_bf16 v[112:115], v[182:185], v[190:193], v[112:115]
	v_mfma_f32_16x16x32_bf16 v[100:103], v[174:177], v[198:201], v[100:103]
	v_mfma_f32_16x16x32_bf16 v[96:99], v[182:185], v[198:201], v[96:99]
	v_mfma_f32_16x16x32_bf16 v[84:87], v[174:177], v[206:209], v[84:87]
	v_mfma_f32_16x16x32_bf16 v[80:83], v[182:185], v[206:209], v[80:83]
	v_mfma_f32_16x16x32_bf16 v[68:71], v[174:177], v[214:217], v[68:71]
	v_mfma_f32_16x16x32_bf16 v[64:67], v[182:185], v[214:217], v[64:67]
	v_mfma_f32_16x16x32_bf16 v[116:119], v[178:181], v[194:197], v[116:119]
	v_mfma_f32_16x16x32_bf16 v[112:115], v[186:189], v[194:197], v[112:115]
	v_mfma_f32_16x16x32_bf16 v[100:103], v[178:181], v[202:205], v[100:103]
	v_mfma_f32_16x16x32_bf16 v[96:99], v[186:189], v[202:205], v[96:99]
	v_mfma_f32_16x16x32_bf16 v[84:87], v[178:181], v[210:213], v[84:87]
	v_mfma_f32_16x16x32_bf16 v[80:83], v[186:189], v[210:213], v[80:83]
	v_mfma_f32_16x16x32_bf16 v[68:71], v[178:181], v[238:241], v[68:71]
	v_mfma_f32_16x16x32_bf16 v[64:67], v[186:189], v[238:241], v[64:67]
	s_barrier
	s_add_i32 s22, s22, s28
	v_lshl_add_u64 v[158:159], v[158:159], 0, s[88:89]
	s_mov_b32 m0, s22
	ds_read_b128 v[190:193], v145 offset:49152
	ds_read_b128 v[194:197], v145 offset:50176
	ds_read_b128 v[198:201], v145 offset:51200
	ds_read_b128 v[202:205], v145 offset:52224
	ds_read_b128 v[206:209], v145 offset:53248
	ds_read_b128 v[210:213], v145 offset:54272
	ds_read_b128 v[214:217], v145 offset:55296
	ds_read_b128 v[238:241], v145 offset:56320
	global_load_lds_dwordx4 v[158:159], off
	s_add_i32 m0, s22, 0x2000
	s_add_u32 s12, s12, 0x40080
	v_lshl_add_u64 v[158:159], v[162:163], 0, s[88:89]
	s_addc_u32 s13, s13, 0
	s_add_i32 s22, s50, s28
	global_load_lds_dwordx4 v[158:159], off
	v_lshl_add_u64 v[158:159], s[12:13], 0, v[160:161]
	s_mov_b32 m0, s22
	s_nop 0
	global_load_lds_dwordx4 v[158:159], off
	v_lshl_add_u64 v[158:159], s[12:13], 0, v[132:133]
	s_add_i32 m0, s22, 0x2000
	s_nop 0
	global_load_lds_dwordx4 v[158:159], off
	v_lshl_add_u64 v[158:159], v[164:165], 0, s[88:89]
	s_mov_b32 m0, s34
	s_nop 0
	global_load_lds_dwordx4 v[158:159], off
	v_lshl_add_u64 v[158:159], v[166:167], 0, s[88:89]
	s_mov_b32 m0, s35
	s_nop 0
	global_load_lds_dwordx4 v[158:159], off
	s_waitcnt vmcnt(8)
	s_waitcnt lgkmcnt(0)
	s_barrier
	s_waitcnt lgkmcnt(0)
	v_mfma_f32_16x16x32_bf16 v[60:63], v[138:141], v[190:193], v[60:63]
	v_mfma_f32_16x16x32_bf16 v[56:59], v[150:153], v[190:193], v[56:59]
	v_mfma_f32_16x16x32_bf16 v[44:47], v[138:141], v[198:201], v[44:47]
	v_mfma_f32_16x16x32_bf16 v[40:43], v[150:153], v[198:201], v[40:43]
	v_mfma_f32_16x16x32_bf16 v[28:31], v[138:141], v[206:209], v[28:31]
	v_mfma_f32_16x16x32_bf16 v[24:27], v[150:153], v[206:209], v[24:27]
	v_mfma_f32_16x16x32_bf16 v[12:15], v[138:141], v[214:217], v[12:15]
	v_mfma_f32_16x16x32_bf16 v[8:11], v[150:153], v[214:217], v[8:11]
	v_mfma_f32_16x16x32_bf16 v[60:63], v[146:149], v[194:197], v[60:63]
	v_mfma_f32_16x16x32_bf16 v[56:59], v[154:157], v[194:197], v[56:59]
	v_mfma_f32_16x16x32_bf16 v[44:47], v[146:149], v[202:205], v[44:47]
	v_mfma_f32_16x16x32_bf16 v[40:43], v[154:157], v[202:205], v[40:43]
	v_mfma_f32_16x16x32_bf16 v[28:31], v[146:149], v[210:213], v[28:31]
	v_mfma_f32_16x16x32_bf16 v[24:27], v[154:157], v[210:213], v[24:27]
	v_mfma_f32_16x16x32_bf16 v[12:15], v[146:149], v[238:241], v[12:15]
	v_mfma_f32_16x16x32_bf16 v[8:11], v[154:157], v[238:241], v[8:11]
	v_mfma_f32_16x16x32_bf16 v[52:55], v[174:177], v[190:193], v[52:55]
	v_mfma_f32_16x16x32_bf16 v[48:51], v[182:185], v[190:193], v[48:51]
	v_mfma_f32_16x16x32_bf16 v[36:39], v[174:177], v[198:201], v[36:39]
	v_mfma_f32_16x16x32_bf16 v[32:35], v[182:185], v[198:201], v[32:35]
	v_mfma_f32_16x16x32_bf16 v[20:23], v[174:177], v[206:209], v[20:23]
	v_mfma_f32_16x16x32_bf16 v[16:19], v[182:185], v[206:209], v[16:19]
	v_mfma_f32_16x16x32_bf16 v[4:7], v[174:177], v[214:217], v[4:7]
	v_mfma_f32_16x16x32_bf16 v[0:3], v[182:185], v[214:217], v[0:3]
	v_mfma_f32_16x16x32_bf16 v[52:55], v[178:181], v[194:197], v[52:55]
	v_mfma_f32_16x16x32_bf16 v[48:51], v[186:189], v[194:197], v[48:51]
	v_mfma_f32_16x16x32_bf16 v[36:39], v[178:181], v[202:205], v[36:39]
	v_mfma_f32_16x16x32_bf16 v[32:35], v[186:189], v[202:205], v[32:35]
	v_mfma_f32_16x16x32_bf16 v[20:23], v[178:181], v[210:213], v[20:23]
	v_mfma_f32_16x16x32_bf16 v[16:19], v[186:189], v[210:213], v[16:19]
	v_mfma_f32_16x16x32_bf16 v[4:7], v[178:181], v[238:241], v[4:7]
	v_mfma_f32_16x16x32_bf16 v[0:3], v[186:189], v[238:241], v[0:3]
	s_barrier
	s_add_i32 s21, s21, 2
	s_add_u32 s90, s90, 0x100
	s_addc_u32 s91, s91, 0
	s_add_u32 vcc_lo, vcc_lo, 0x100
	s_addc_u32 vcc_hi, vcc_hi, 0
	s_cmp_gt_u32 s21, 13
	s_cbranch_scc0 .LBB0_310
	v_lshl_add_u32 v140, s36, 8, v142
	v_lshl_or_b32 v138, s44, 8, v144
	v_lshlrev_b32_e32 v141, 11, v140
	v_lshl_add_u32 v138, v138, 1, v141
	v_lshlrev_b32_e32 v139, 3, v140
	s_mov_b64 s[12:13], s[2:3]
	global_load_dwordx4 v[146:149], v138, s[12:13]
	global_load_dwordx4 v[150:153], v138, s[12:13] offset:256
	s_add_u32 s12, s12, 0x8000
	s_addc_u32 s13, s13, 0
	global_load_dwordx4 v[154:157], v138, s[12:13]
	global_load_dwordx4 v[162:165], v138, s[12:13] offset:256
	s_add_u32 s12, s12, 0x8000
	s_addc_u32 s13, s13, 0
	global_load_dwordx4 v[166:169], v138, s[12:13]
	global_load_dwordx4 v[174:177], v138, s[12:13] offset:256
	s_add_u32 s12, s12, 0x8000
	s_addc_u32 s13, s13, 0
	global_load_dwordx4 v[178:181], v138, s[12:13]
	global_load_dwordx4 v[182:185], v138, s[12:13] offset:256
	s_add_u32 s12, s12, 0x28000
	s_addc_u32 s13, s13, 0
	global_load_dwordx4 v[186:189], v138, s[12:13]
	global_load_dwordx4 v[190:193], v138, s[12:13] offset:256
	s_add_u32 s12, s12, 0x8000
	s_addc_u32 s13, s13, 0
	global_load_dwordx4 v[194:197], v138, s[12:13]
	global_load_dwordx4 v[198:201], v138, s[12:13] offset:256
	s_add_u32 s12, s12, 0x8000
	s_addc_u32 s13, s13, 0
	global_load_dwordx4 v[202:205], v138, s[12:13]
	global_load_dwordx4 v[206:209], v138, s[12:13] offset:256
	s_add_u32 s12, s12, 0x8000
	s_addc_u32 s13, s13, 0
	global_load_dwordx4 v[210:213], v138, s[12:13]
	global_load_dwordx4 v[214:217], v138, s[12:13] offset:256
	s_and_b64 vcc, exec, s[6:7]
	s_cbranch_vccz .LBB0_313
	s_barrier

.LBB0_399:
	s_add_u32 s8, s0, 0xfffc0080
	s_addc_u32 s9, s1, -1
	s_add_i32 s22, 0, 0x10000
	s_cmp_eq_u32 s21, 12
	s_cselect_b32 s11, s7, s9
	s_cselect_b32 s10, s19, s8
	s_cselect_b32 s9, s20, s91
	s_cselect_b32 s8, s33, s90
	s_add_i32 s48, 0, 0x14000
	v_add_u32_e32 v152, s22, v157
	v_add_u32_e32 v162, s48, v157
	ds_read_b128 v[128:131], v152
	ds_read_b128 v[144:147], v152 offset:1024
	ds_read_b128 v[148:151], v152 offset:2048
	ds_read_b128 v[152:155], v152 offset:3072
	ds_read_b128 v[176:179], v162
	ds_read_b128 v[180:183], v162 offset:1024
	ds_read_b128 v[184:187], v162 offset:2048
	ds_read_b128 v[188:191], v162 offset:3072
	v_lshl_add_u64 v[162:163], s[0:1], 0, v[142:143]
	s_add_i32 m0, s27, 0xc000
	ds_read_b128 v[192:195], v159
	ds_read_b128 v[196:199], v159 offset:1024
	ds_read_b128 v[200:203], v159 offset:2048
	ds_read_b128 v[204:207], v159 offset:3072
	ds_read_b128 v[208:211], v159 offset:4096
	ds_read_b128 v[212:215], v159 offset:5120
	ds_read_b128 v[238:241], v159 offset:6144
	ds_read_b128 v[246:249], v159 offset:7168
	global_load_lds_dwordx4 v[162:163], off
	v_lshl_add_u64 v[162:163], s[0:1], 0, v[140:141]
	s_add_i32 m0, s27, 0xe000
	s_nop 0
	global_load_lds_dwordx4 v[162:163], off
	s_waitcnt vmcnt(8)
	s_waitcnt lgkmcnt(0)
	s_barrier
	s_waitcnt lgkmcnt(0)
	v_mfma_f32_16x16x32_bf16 v[124:127], v[128:131], v[192:195], v[124:127]
	v_mfma_f32_16x16x32_bf16 v[116:119], v[148:151], v[192:195], v[116:119]
	v_mfma_f32_16x16x32_bf16 v[108:111], v[128:131], v[200:203], v[108:111]
	v_mfma_f32_16x16x32_bf16 v[100:103], v[148:151], v[200:203], v[100:103]
	v_mfma_f32_16x16x32_bf16 v[92:95], v[128:131], v[208:211], v[92:95]
	v_mfma_f32_16x16x32_bf16 v[84:87], v[148:151], v[208:211], v[84:87]
	v_mfma_f32_16x16x32_bf16 v[76:79], v[128:131], v[238:241], v[76:79]
	v_mfma_f32_16x16x32_bf16 v[68:71], v[148:151], v[238:241], v[68:71]
	v_mfma_f32_16x16x32_bf16 v[124:127], v[144:147], v[196:199], v[124:127]
	v_mfma_f32_16x16x32_bf16 v[116:119], v[152:155], v[196:199], v[116:119]
	v_mfma_f32_16x16x32_bf16 v[108:111], v[144:147], v[204:207], v[108:111]
	v_mfma_f32_16x16x32_bf16 v[100:103], v[152:155], v[204:207], v[100:103]
	v_mfma_f32_16x16x32_bf16 v[92:95], v[144:147], v[212:215], v[92:95]
	v_mfma_f32_16x16x32_bf16 v[84:87], v[152:155], v[212:215], v[84:87]
	v_mfma_f32_16x16x32_bf16 v[76:79], v[144:147], v[246:249], v[76:79]
	v_mfma_f32_16x16x32_bf16 v[68:71], v[152:155], v[246:249], v[68:71]
	v_mfma_f32_16x16x32_bf16 v[120:123], v[176:179], v[192:195], v[120:123]
	v_mfma_f32_16x16x32_bf16 v[112:115], v[184:187], v[192:195], v[112:115]
	v_mfma_f32_16x16x32_bf16 v[104:107], v[176:179], v[200:203], v[104:107]
	v_mfma_f32_16x16x32_bf16 v[96:99], v[184:187], v[200:203], v[96:99]
	v_mfma_f32_16x16x32_bf16 v[88:91], v[176:179], v[208:211], v[88:91]
	v_mfma_f32_16x16x32_bf16 v[80:83], v[184:187], v[208:211], v[80:83]
	v_mfma_f32_16x16x32_bf16 v[72:75], v[176:179], v[238:241], v[72:75]
	v_mfma_f32_16x16x32_bf16 v[64:67], v[184:187], v[238:241], v[64:67]
	v_mfma_f32_16x16x32_bf16 v[120:123], v[180:183], v[196:199], v[120:123]
	v_mfma_f32_16x16x32_bf16 v[112:115], v[188:191], v[196:199], v[112:115]
	v_mfma_f32_16x16x32_bf16 v[104:107], v[180:183], v[204:207], v[104:107]
	v_mfma_f32_16x16x32_bf16 v[96:99], v[188:191], v[204:207], v[96:99]
	v_mfma_f32_16x16x32_bf16 v[88:91], v[180:183], v[212:215], v[88:91]
	v_mfma_f32_16x16x32_bf16 v[80:83], v[188:191], v[212:215], v[80:83]
	v_mfma_f32_16x16x32_bf16 v[72:75], v[180:183], v[246:249], v[72:75]
	v_mfma_f32_16x16x32_bf16 v[64:67], v[188:191], v[246:249], v[64:67]
	s_barrier
	s_add_i32 s22, s22, s25
	v_lshl_add_u64 v[162:163], s[8:9], 0, v[136:137]
	s_mov_b32 m0, s22
	ds_read_b128 v[192:195], v159 offset:16384
	ds_read_b128 v[196:199], v159 offset:17408
	ds_read_b128 v[200:203], v159 offset:18432
	ds_read_b128 v[204:207], v159 offset:19456
	ds_read_b128 v[208:211], v159 offset:20480
	ds_read_b128 v[212:215], v159 offset:21504
	ds_read_b128 v[238:241], v159 offset:22528
	ds_read_b128 v[246:249], v159 offset:23552
	global_load_lds_dwordx4 v[162:163], off
	s_add_i32 m0, s22, 0x2000
	s_add_u32 vcc_lo, s8, 0x40000
	v_lshl_add_u64 v[164:165], s[8:9], 0, v[132:133]
	s_addc_u32 vcc_hi, s9, 0
	s_add_i32 s22, s48, s25
	global_load_lds_dwordx4 v[164:165], off
	v_lshl_add_u64 v[166:167], vcc, 0, v[136:137]
	s_mov_b32 m0, s22
	v_lshl_add_u64 v[168:169], s[10:11], 0, v[134:135]
	global_load_lds_dwordx4 v[166:167], off
	v_lshl_add_u64 v[166:167], vcc, 0, v[132:133]
	s_add_i32 m0, s22, 0x2000
	s_nop 0
	global_load_lds_dwordx4 v[166:167], off
	v_lshl_add_u64 v[166:167], s[10:11], 0, v[138:139]
	s_mov_b32 m0, s27
	s_nop 0
	global_load_lds_dwordx4 v[166:167], off
	s_mov_b32 m0, s45
	s_nop 0
	global_load_lds_dwordx4 v[168:169], off
	s_waitcnt vmcnt(8)
	s_waitcnt lgkmcnt(0)
	s_barrier
	s_waitcnt lgkmcnt(0)
	v_mfma_f32_16x16x32_bf16 v[60:63], v[128:131], v[192:195], v[60:63]
	v_mfma_f32_16x16x32_bf16 v[52:55], v[148:151], v[192:195], v[52:55]
	v_mfma_f32_16x16x32_bf16 v[44:47], v[128:131], v[200:203], v[44:47]
	v_mfma_f32_16x16x32_bf16 v[36:39], v[148:151], v[200:203], v[36:39]
	v_mfma_f32_16x16x32_bf16 v[28:31], v[128:131], v[208:211], v[28:31]
	v_mfma_f32_16x16x32_bf16 v[20:23], v[148:151], v[208:211], v[20:23]
	v_mfma_f32_16x16x32_bf16 v[12:15], v[128:131], v[238:241], v[12:15]
	v_mfma_f32_16x16x32_bf16 v[4:7], v[148:151], v[238:241], v[4:7]
	v_mfma_f32_16x16x32_bf16 v[60:63], v[144:147], v[196:199], v[60:63]
	v_mfma_f32_16x16x32_bf16 v[52:55], v[152:155], v[196:199], v[52:55]
	v_mfma_f32_16x16x32_bf16 v[44:47], v[144:147], v[204:207], v[44:47]
	v_mfma_f32_16x16x32_bf16 v[36:39], v[152:155], v[204:207], v[36:39]
	v_mfma_f32_16x16x32_bf16 v[28:31], v[144:147], v[212:215], v[28:31]
	v_mfma_f32_16x16x32_bf16 v[20:23], v[152:155], v[212:215], v[20:23]
	v_mfma_f32_16x16x32_bf16 v[12:15], v[144:147], v[246:249], v[12:15]
	v_mfma_f32_16x16x32_bf16 v[4:7], v[152:155], v[246:249], v[4:7]
	v_mfma_f32_16x16x32_bf16 v[56:59], v[176:179], v[192:195], v[56:59]
	v_mfma_f32_16x16x32_bf16 v[48:51], v[184:187], v[192:195], v[48:51]
	v_mfma_f32_16x16x32_bf16 v[40:43], v[176:179], v[200:203], v[40:43]
	v_mfma_f32_16x16x32_bf16 v[32:35], v[184:187], v[200:203], v[32:35]
	v_mfma_f32_16x16x32_bf16 v[24:27], v[176:179], v[208:211], v[24:27]
	v_mfma_f32_16x16x32_bf16 v[16:19], v[184:187], v[208:211], v[16:19]
	v_mfma_f32_16x16x32_bf16 v[8:11], v[176:179], v[238:241], v[8:11]
	v_mfma_f32_16x16x32_bf16 v[0:3], v[184:187], v[238:241], v[0:3]
	v_mfma_f32_16x16x32_bf16 v[56:59], v[180:183], v[196:199], v[56:59]
	v_mfma_f32_16x16x32_bf16 v[48:51], v[188:191], v[196:199], v[48:51]
	v_mfma_f32_16x16x32_bf16 v[40:43], v[180:183], v[204:207], v[40:43]
	v_mfma_f32_16x16x32_bf16 v[32:35], v[188:191], v[204:207], v[32:35]
	v_mfma_f32_16x16x32_bf16 v[24:27], v[180:183], v[212:215], v[24:27]
	v_mfma_f32_16x16x32_bf16 v[16:19], v[188:191], v[212:215], v[16:19]
	v_mfma_f32_16x16x32_bf16 v[8:11], v[180:183], v[246:249], v[8:11]
	v_mfma_f32_16x16x32_bf16 v[0:3], v[188:191], v[246:249], v[0:3]
	s_barrier
	s_add_i32 s22, 0, 0x18000
	s_add_i32 s48, 0, 0x1c000
	v_add_u32_e32 v152, s22, v157
	v_add_u32_e32 v170, s48, v157
	ds_read_b128 v[128:131], v152
	ds_read_b128 v[144:147], v152 offset:1024
	ds_read_b128 v[148:151], v152 offset:2048
	ds_read_b128 v[152:155], v152 offset:3072
	ds_read_b128 v[176:179], v170
	ds_read_b128 v[180:183], v170 offset:1024
	ds_read_b128 v[184:187], v170 offset:2048
	ds_read_b128 v[188:191], v170 offset:3072
	s_add_u32 s10, s10, 0x40000
	s_addc_u32 s11, s11, 0
	s_mov_b32 m0, s28
	v_lshl_add_u64 v[170:171], s[10:11], 0, v[138:139]
	ds_read_b128 v[192:195], v159 offset:32768
	ds_read_b128 v[196:199], v159 offset:33792
	ds_read_b128 v[200:203], v159 offset:34816
	ds_read_b128 v[204:207], v159 offset:35840
	ds_read_b128 v[208:211], v159 offset:36864
	ds_read_b128 v[212:215], v159 offset:37888
	ds_read_b128 v[238:241], v159 offset:38912
	ds_read_b128 v[246:249], v159 offset:39936
	global_load_lds_dwordx4 v[170:171], off
	v_lshl_add_u64 v[170:171], s[10:11], 0, v[134:135]
	s_mov_b32 m0, s29
	s_nop 0
	global_load_lds_dwordx4 v[170:171], off
	s_waitcnt vmcnt(8)
	s_waitcnt lgkmcnt(0)
	s_barrier
	s_waitcnt lgkmcnt(0)
	v_mfma_f32_16x16x32_bf16 v[124:127], v[128:131], v[192:195], v[124:127]
	v_mfma_f32_16x16x32_bf16 v[116:119], v[148:151], v[192:195], v[116:119]
	v_mfma_f32_16x16x32_bf16 v[108:111], v[128:131], v[200:203], v[108:111]
	v_mfma_f32_16x16x32_bf16 v[100:103], v[148:151], v[200:203], v[100:103]
	v_mfma_f32_16x16x32_bf16 v[92:95], v[128:131], v[208:211], v[92:95]
	v_mfma_f32_16x16x32_bf16 v[84:87], v[148:151], v[208:211], v[84:87]
	v_mfma_f32_16x16x32_bf16 v[76:79], v[128:131], v[238:241], v[76:79]
	v_mfma_f32_16x16x32_bf16 v[68:71], v[148:151], v[238:241], v[68:71]
	v_mfma_f32_16x16x32_bf16 v[124:127], v[144:147], v[196:199], v[124:127]
	v_mfma_f32_16x16x32_bf16 v[116:119], v[152:155], v[196:199], v[116:119]
	v_mfma_f32_16x16x32_bf16 v[108:111], v[144:147], v[204:207], v[108:111]
	v_mfma_f32_16x16x32_bf16 v[100:103], v[152:155], v[204:207], v[100:103]
	v_mfma_f32_16x16x32_bf16 v[92:95], v[144:147], v[212:215], v[92:95]
	v_mfma_f32_16x16x32_bf16 v[84:87], v[152:155], v[212:215], v[84:87]
	v_mfma_f32_16x16x32_bf16 v[76:79], v[144:147], v[246:249], v[76:79]
	v_mfma_f32_16x16x32_bf16 v[68:71], v[152:155], v[246:249], v[68:71]
	v_mfma_f32_16x16x32_bf16 v[120:123], v[176:179], v[192:195], v[120:123]
	v_mfma_f32_16x16x32_bf16 v[112:115], v[184:187], v[192:195], v[112:115]
	v_mfma_f32_16x16x32_bf16 v[104:107], v[176:179], v[200:203], v[104:107]
	v_mfma_f32_16x16x32_bf16 v[96:99], v[184:187], v[200:203], v[96:99]
	v_mfma_f32_16x16x32_bf16 v[88:91], v[176:179], v[208:211], v[88:91]
	v_mfma_f32_16x16x32_bf16 v[80:83], v[184:187], v[208:211], v[80:83]
	v_mfma_f32_16x16x32_bf16 v[72:75], v[176:179], v[238:241], v[72:75]
	v_mfma_f32_16x16x32_bf16 v[64:67], v[184:187], v[238:241], v[64:67]
	v_mfma_f32_16x16x32_bf16 v[120:123], v[180:183], v[196:199], v[120:123]
	v_mfma_f32_16x16x32_bf16 v[112:115], v[188:191], v[196:199], v[112:115]
	v_mfma_f32_16x16x32_bf16 v[104:107], v[180:183], v[204:207], v[104:107]
	v_mfma_f32_16x16x32_bf16 v[96:99], v[188:191], v[204:207], v[96:99]
	v_mfma_f32_16x16x32_bf16 v[88:91], v[180:183], v[212:215], v[88:91]
	v_mfma_f32_16x16x32_bf16 v[80:83], v[188:191], v[212:215], v[80:83]
	v_mfma_f32_16x16x32_bf16 v[72:75], v[180:183], v[246:249], v[72:75]
	v_mfma_f32_16x16x32_bf16 v[64:67], v[188:191], v[246:249], v[64:67]
	s_barrier
	s_add_i32 s10, s22, s25
	v_lshl_add_u64 v[162:163], v[162:163], 0, s[88:89]
	s_mov_b32 m0, s10
	ds_read_b128 v[192:195], v159 offset:49152
	ds_read_b128 v[196:199], v159 offset:50176
	ds_read_b128 v[200:203], v159 offset:51200
	ds_read_b128 v[204:207], v159 offset:52224
	ds_read_b128 v[208:211], v159 offset:53248
	ds_read_b128 v[212:215], v159 offset:54272
	ds_read_b128 v[238:241], v159 offset:55296
	ds_read_b128 v[246:249], v159 offset:56320
	global_load_lds_dwordx4 v[162:163], off
	s_add_i32 m0, s10, 0x2000
	s_add_u32 s8, s8, 0x40080
	v_lshl_add_u64 v[162:163], v[164:165], 0, s[88:89]
	s_addc_u32 s9, s9, 0
	s_add_i32 s10, s48, s25
	global_load_lds_dwordx4 v[162:163], off
	v_lshl_add_u64 v[162:163], s[8:9], 0, v[136:137]
	s_mov_b32 m0, s10
	s_nop 0
	global_load_lds_dwordx4 v[162:163], off
	v_lshl_add_u64 v[162:163], s[8:9], 0, v[132:133]
	s_add_i32 m0, s10, 0x2000
	s_nop 0
	global_load_lds_dwordx4 v[162:163], off
	v_lshl_add_u64 v[162:163], v[166:167], 0, s[88:89]
	s_mov_b32 m0, s30
	s_nop 0
	global_load_lds_dwordx4 v[162:163], off
	v_lshl_add_u64 v[162:163], v[168:169], 0, s[88:89]
	s_mov_b32 m0, s31
	s_nop 0
	global_load_lds_dwordx4 v[162:163], off
	s_waitcnt vmcnt(8)
	s_waitcnt lgkmcnt(0)
	s_barrier
	s_waitcnt lgkmcnt(0)
	v_mfma_f32_16x16x32_bf16 v[60:63], v[128:131], v[192:195], v[60:63]
	v_mfma_f32_16x16x32_bf16 v[52:55], v[148:151], v[192:195], v[52:55]
	v_mfma_f32_16x16x32_bf16 v[44:47], v[128:131], v[200:203], v[44:47]
	v_mfma_f32_16x16x32_bf16 v[36:39], v[148:151], v[200:203], v[36:39]
	v_mfma_f32_16x16x32_bf16 v[28:31], v[128:131], v[208:211], v[28:31]
	v_mfma_f32_16x16x32_bf16 v[20:23], v[148:151], v[208:211], v[20:23]
	v_mfma_f32_16x16x32_bf16 v[12:15], v[128:131], v[238:241], v[12:15]
	v_mfma_f32_16x16x32_bf16 v[4:7], v[148:151], v[238:241], v[4:7]
	v_mfma_f32_16x16x32_bf16 v[60:63], v[144:147], v[196:199], v[60:63]
	v_mfma_f32_16x16x32_bf16 v[52:55], v[152:155], v[196:199], v[52:55]
	v_mfma_f32_16x16x32_bf16 v[44:47], v[144:147], v[204:207], v[44:47]
	v_mfma_f32_16x16x32_bf16 v[36:39], v[152:155], v[204:207], v[36:39]
	v_mfma_f32_16x16x32_bf16 v[28:31], v[144:147], v[212:215], v[28:31]
	v_mfma_f32_16x16x32_bf16 v[20:23], v[152:155], v[212:215], v[20:23]
	v_mfma_f32_16x16x32_bf16 v[12:15], v[144:147], v[246:249], v[12:15]
	v_mfma_f32_16x16x32_bf16 v[4:7], v[152:155], v[246:249], v[4:7]
	v_mfma_f32_16x16x32_bf16 v[56:59], v[176:179], v[192:195], v[56:59]
	v_mfma_f32_16x16x32_bf16 v[48:51], v[184:187], v[192:195], v[48:51]
	v_mfma_f32_16x16x32_bf16 v[40:43], v[176:179], v[200:203], v[40:43]
	v_mfma_f32_16x16x32_bf16 v[32:35], v[184:187], v[200:203], v[32:35]
	v_mfma_f32_16x16x32_bf16 v[24:27], v[176:179], v[208:211], v[24:27]
	v_mfma_f32_16x16x32_bf16 v[16:19], v[184:187], v[208:211], v[16:19]
	v_mfma_f32_16x16x32_bf16 v[8:11], v[176:179], v[238:241], v[8:11]
	v_mfma_f32_16x16x32_bf16 v[0:3], v[184:187], v[238:241], v[0:3]
	v_mfma_f32_16x16x32_bf16 v[56:59], v[180:183], v[196:199], v[56:59]
	v_mfma_f32_16x16x32_bf16 v[48:51], v[188:191], v[196:199], v[48:51]
	v_mfma_f32_16x16x32_bf16 v[40:43], v[180:183], v[204:207], v[40:43]
	v_mfma_f32_16x16x32_bf16 v[32:35], v[188:191], v[204:207], v[32:35]
	v_mfma_f32_16x16x32_bf16 v[24:27], v[180:183], v[212:215], v[24:27]
	v_mfma_f32_16x16x32_bf16 v[16:19], v[188:191], v[212:215], v[16:19]
	v_mfma_f32_16x16x32_bf16 v[8:11], v[180:183], v[246:249], v[8:11]
	v_mfma_f32_16x16x32_bf16 v[0:3], v[188:191], v[246:249], v[0:3]
	s_barrier
	s_add_i32 s21, s21, 2
	s_add_u32 s90, s90, 0x100
	s_addc_u32 s91, s91, 0
	s_add_u32 s0, s0, 0x100
	s_addc_u32 s1, s1, 0
	s_cmp_gt_u32 s21, 13
	s_cbranch_scc0 .LBB0_399
	v_lshl_add_u32 v212, s44, 8, v156
	v_lshlrev_b32_e32 v212, 3, v212
	global_load_dwordx2 v[196:197], v212, s[36:37]
	global_load_dwordx2 v[198:199], v212, s[36:37] offset:128
	global_load_dwordx2 v[200:201], v212, s[36:37] offset:256
	global_load_dwordx2 v[202:203], v212, s[36:37] offset:384
	global_load_dwordx2 v[204:205], v212, s[36:37] offset:1024
	global_load_dwordx2 v[206:207], v212, s[36:37] offset:1152
	global_load_dwordx2 v[208:209], v212, s[36:37] offset:1280
	global_load_dwordx2 v[210:211], v212, s[36:37] offset:1408
	s_and_b64 vcc, exec, s[92:93]
	s_cbranch_vccnz .LBB0_404
	s_cmp_gt_i32 s35, 3
	s_mov_b64 s[0:1], -1
	s_cbranch_scc1 .LBB0_405

.LBB0_439:
	s_add_u32 s10, s8, 0x100
	s_addc_u32 s11, s9, 0
	s_add_i32 s48, 0, 0x10000
	s_cmp_eq_u32 s22, 40
	s_cselect_b32 s15, s1, s11
	s_cselect_b32 s14, s0, s10
	s_cselect_b32 s13, s45, s92
	s_cselect_b32 s12, s44, s21
	s_add_i32 s49, 0, 0x14000
	v_add_u32_e32 v154, s48, v143
	v_add_u32_e32 v158, s49, v143
	ds_read_b128 v[138:141], v154
	ds_read_b128 v[146:149], v154 offset:1024
	ds_read_b128 v[150:153], v154 offset:2048
	ds_read_b128 v[154:157], v154 offset:3072
	ds_read_b128 v[174:177], v158
	ds_read_b128 v[178:181], v158 offset:1024
	ds_read_b128 v[182:185], v158 offset:2048
	ds_read_b128 v[186:189], v158 offset:3072
	v_lshl_add_u64 v[158:159], s[8:9], 0, v[136:137]
	s_add_i32 m0, s29, 0xc000
	ds_read_b128 v[190:193], v145
	ds_read_b128 v[194:197], v145 offset:1024
	ds_read_b128 v[198:201], v145 offset:2048
	ds_read_b128 v[202:205], v145 offset:3072
	ds_read_b128 v[206:209], v145 offset:4096
	ds_read_b128 v[210:213], v145 offset:5120
	ds_read_b128 v[214:217], v145 offset:6144
	ds_read_b128 v[238:241], v145 offset:7168
	global_load_lds_dwordx4 v[158:159], off
	v_lshl_add_u64 v[158:159], s[8:9], 0, v[134:135]
	s_add_i32 m0, s29, 0xe000
	s_nop 0
	global_load_lds_dwordx4 v[158:159], off
	s_waitcnt vmcnt(8)
	s_waitcnt lgkmcnt(0)
	s_barrier
	s_waitcnt lgkmcnt(0)
	v_mfma_f32_16x16x32_bf16 v[124:127], v[138:141], v[190:193], v[124:127]
	v_mfma_f32_16x16x32_bf16 v[120:123], v[150:153], v[190:193], v[120:123]
	v_mfma_f32_16x16x32_bf16 v[108:111], v[138:141], v[198:201], v[108:111]
	v_mfma_f32_16x16x32_bf16 v[104:107], v[150:153], v[198:201], v[104:107]
	v_mfma_f32_16x16x32_bf16 v[92:95], v[138:141], v[206:209], v[92:95]
	v_mfma_f32_16x16x32_bf16 v[88:91], v[150:153], v[206:209], v[88:91]
	v_mfma_f32_16x16x32_bf16 v[76:79], v[138:141], v[214:217], v[76:79]
	v_mfma_f32_16x16x32_bf16 v[72:75], v[150:153], v[214:217], v[72:75]
	v_mfma_f32_16x16x32_bf16 v[124:127], v[146:149], v[194:197], v[124:127]
	v_mfma_f32_16x16x32_bf16 v[120:123], v[154:157], v[194:197], v[120:123]
	v_mfma_f32_16x16x32_bf16 v[108:111], v[146:149], v[202:205], v[108:111]
	v_mfma_f32_16x16x32_bf16 v[104:107], v[154:157], v[202:205], v[104:107]
	v_mfma_f32_16x16x32_bf16 v[92:95], v[146:149], v[210:213], v[92:95]
	v_mfma_f32_16x16x32_bf16 v[88:91], v[154:157], v[210:213], v[88:91]
	v_mfma_f32_16x16x32_bf16 v[76:79], v[146:149], v[238:241], v[76:79]
	v_mfma_f32_16x16x32_bf16 v[72:75], v[154:157], v[238:241], v[72:75]
	v_mfma_f32_16x16x32_bf16 v[116:119], v[174:177], v[190:193], v[116:119]
	v_mfma_f32_16x16x32_bf16 v[112:115], v[182:185], v[190:193], v[112:115]
	v_mfma_f32_16x16x32_bf16 v[100:103], v[174:177], v[198:201], v[100:103]
	v_mfma_f32_16x16x32_bf16 v[96:99], v[182:185], v[198:201], v[96:99]
	v_mfma_f32_16x16x32_bf16 v[84:87], v[174:177], v[206:209], v[84:87]
	v_mfma_f32_16x16x32_bf16 v[80:83], v[182:185], v[206:209], v[80:83]
	v_mfma_f32_16x16x32_bf16 v[68:71], v[174:177], v[214:217], v[68:71]
	v_mfma_f32_16x16x32_bf16 v[64:67], v[182:185], v[214:217], v[64:67]
	v_mfma_f32_16x16x32_bf16 v[116:119], v[178:181], v[194:197], v[116:119]
	v_mfma_f32_16x16x32_bf16 v[112:115], v[186:189], v[194:197], v[112:115]
	v_mfma_f32_16x16x32_bf16 v[100:103], v[178:181], v[202:205], v[100:103]
	v_mfma_f32_16x16x32_bf16 v[96:99], v[186:189], v[202:205], v[96:99]
	v_mfma_f32_16x16x32_bf16 v[84:87], v[178:181], v[210:213], v[84:87]
	v_mfma_f32_16x16x32_bf16 v[80:83], v[186:189], v[210:213], v[80:83]
	v_mfma_f32_16x16x32_bf16 v[68:71], v[178:181], v[238:241], v[68:71]
	v_mfma_f32_16x16x32_bf16 v[64:67], v[186:189], v[238:241], v[64:67]
	s_barrier
	s_add_i32 s8, s48, s28
	v_lshl_add_u64 v[158:159], s[12:13], 0, v[160:161]
	s_mov_b32 m0, s8
	ds_read_b128 v[190:193], v145 offset:16384
	ds_read_b128 v[194:197], v145 offset:17408
	ds_read_b128 v[198:201], v145 offset:18432
	ds_read_b128 v[202:205], v145 offset:19456
	ds_read_b128 v[206:209], v145 offset:20480
	ds_read_b128 v[210:213], v145 offset:21504
	ds_read_b128 v[214:217], v145 offset:22528
	ds_read_b128 v[238:241], v145 offset:23552
	global_load_lds_dwordx4 v[158:159], off
	s_add_i32 m0, s8, 0x2000
	s_add_u32 s8, s12, 0xb0000
	v_lshl_add_u64 v[162:163], s[12:13], 0, v[132:133]
	s_addc_u32 s9, s13, 0
	s_add_i32 s48, s49, s28
	global_load_lds_dwordx4 v[162:163], off
	v_lshl_add_u64 v[164:165], s[8:9], 0, v[160:161]
	s_mov_b32 m0, s48
	v_lshl_add_u64 v[166:167], s[14:15], 0, v[130:131]
	global_load_lds_dwordx4 v[164:165], off
	v_lshl_add_u64 v[164:165], s[8:9], 0, v[132:133]
	s_add_i32 m0, s48, 0x2000
	s_nop 0
	global_load_lds_dwordx4 v[164:165], off
	v_lshl_add_u64 v[164:165], s[14:15], 0, v[128:129]
	s_mov_b32 m0, s29
	s_nop 0
	global_load_lds_dwordx4 v[164:165], off
	s_mov_b32 m0, s30
	s_nop 0
	global_load_lds_dwordx4 v[166:167], off
	s_waitcnt vmcnt(8)
	s_waitcnt lgkmcnt(0)
	s_barrier
	s_waitcnt lgkmcnt(0)
	v_mfma_f32_16x16x32_bf16 v[60:63], v[138:141], v[190:193], v[60:63]
	v_mfma_f32_16x16x32_bf16 v[56:59], v[150:153], v[190:193], v[56:59]
	v_mfma_f32_16x16x32_bf16 v[44:47], v[138:141], v[198:201], v[44:47]
	v_mfma_f32_16x16x32_bf16 v[40:43], v[150:153], v[198:201], v[40:43]
	v_mfma_f32_16x16x32_bf16 v[28:31], v[138:141], v[206:209], v[28:31]
	v_mfma_f32_16x16x32_bf16 v[24:27], v[150:153], v[206:209], v[24:27]
	v_mfma_f32_16x16x32_bf16 v[12:15], v[138:141], v[214:217], v[12:15]
	v_mfma_f32_16x16x32_bf16 v[8:11], v[150:153], v[214:217], v[8:11]
	v_mfma_f32_16x16x32_bf16 v[60:63], v[146:149], v[194:197], v[60:63]
	v_mfma_f32_16x16x32_bf16 v[56:59], v[154:157], v[194:197], v[56:59]
	v_mfma_f32_16x16x32_bf16 v[44:47], v[146:149], v[202:205], v[44:47]
	v_mfma_f32_16x16x32_bf16 v[40:43], v[154:157], v[202:205], v[40:43]
	v_mfma_f32_16x16x32_bf16 v[28:31], v[146:149], v[210:213], v[28:31]
	v_mfma_f32_16x16x32_bf16 v[24:27], v[154:157], v[210:213], v[24:27]
	v_mfma_f32_16x16x32_bf16 v[12:15], v[146:149], v[238:241], v[12:15]
	v_mfma_f32_16x16x32_bf16 v[8:11], v[154:157], v[238:241], v[8:11]
	v_mfma_f32_16x16x32_bf16 v[52:55], v[174:177], v[190:193], v[52:55]
	v_mfma_f32_16x16x32_bf16 v[48:51], v[182:185], v[190:193], v[48:51]
	v_mfma_f32_16x16x32_bf16 v[36:39], v[174:177], v[198:201], v[36:39]
	v_mfma_f32_16x16x32_bf16 v[32:35], v[182:185], v[198:201], v[32:35]
	v_mfma_f32_16x16x32_bf16 v[20:23], v[174:177], v[206:209], v[20:23]
	v_mfma_f32_16x16x32_bf16 v[16:19], v[182:185], v[206:209], v[16:19]
	v_mfma_f32_16x16x32_bf16 v[4:7], v[174:177], v[214:217], v[4:7]
	v_mfma_f32_16x16x32_bf16 v[0:3], v[182:185], v[214:217], v[0:3]
	v_mfma_f32_16x16x32_bf16 v[52:55], v[178:181], v[194:197], v[52:55]
	v_mfma_f32_16x16x32_bf16 v[48:51], v[186:189], v[194:197], v[48:51]
	v_mfma_f32_16x16x32_bf16 v[36:39], v[178:181], v[202:205], v[36:39]
	v_mfma_f32_16x16x32_bf16 v[32:35], v[186:189], v[202:205], v[32:35]
	v_mfma_f32_16x16x32_bf16 v[20:23], v[178:181], v[210:213], v[20:23]
	v_mfma_f32_16x16x32_bf16 v[16:19], v[186:189], v[210:213], v[16:19]
	v_mfma_f32_16x16x32_bf16 v[4:7], v[178:181], v[238:241], v[4:7]
	v_mfma_f32_16x16x32_bf16 v[0:3], v[186:189], v[238:241], v[0:3]
	s_barrier
	s_add_i32 s48, 0, 0x18000
	s_add_i32 s49, 0, 0x1c000
	v_add_u32_e32 v154, s48, v143
	v_add_u32_e32 v168, s49, v143
	ds_read_b128 v[138:141], v154
	ds_read_b128 v[146:149], v154 offset:1024
	ds_read_b128 v[150:153], v154 offset:2048
	ds_read_b128 v[154:157], v154 offset:3072
	ds_read_b128 v[174:177], v168
	ds_read_b128 v[178:181], v168 offset:1024
	ds_read_b128 v[182:185], v168 offset:2048
	ds_read_b128 v[186:189], v168 offset:3072
	s_add_u32 s8, s14, 0xb0000
	s_addc_u32 s9, s15, 0
	s_mov_b32 m0, s31
	v_lshl_add_u64 v[168:169], s[8:9], 0, v[128:129]
	ds_read_b128 v[190:193], v145 offset:32768
	ds_read_b128 v[194:197], v145 offset:33792
	ds_read_b128 v[198:201], v145 offset:34816
	ds_read_b128 v[202:205], v145 offset:35840
	ds_read_b128 v[206:209], v145 offset:36864
	ds_read_b128 v[210:213], v145 offset:37888
	ds_read_b128 v[214:217], v145 offset:38912
	ds_read_b128 v[238:241], v145 offset:39936
	global_load_lds_dwordx4 v[168:169], off
	v_lshl_add_u64 v[168:169], s[8:9], 0, v[130:131]
	s_mov_b32 m0, s33
	s_nop 0
	global_load_lds_dwordx4 v[168:169], off
	s_waitcnt vmcnt(8)
	s_waitcnt lgkmcnt(0)
	s_barrier
	s_waitcnt lgkmcnt(0)
	v_mfma_f32_16x16x32_bf16 v[124:127], v[138:141], v[190:193], v[124:127]
	v_mfma_f32_16x16x32_bf16 v[120:123], v[150:153], v[190:193], v[120:123]
	v_mfma_f32_16x16x32_bf16 v[108:111], v[138:141], v[198:201], v[108:111]
	v_mfma_f32_16x16x32_bf16 v[104:107], v[150:153], v[198:201], v[104:107]
	v_mfma_f32_16x16x32_bf16 v[92:95], v[138:141], v[206:209], v[92:95]
	v_mfma_f32_16x16x32_bf16 v[88:91], v[150:153], v[206:209], v[88:91]
	v_mfma_f32_16x16x32_bf16 v[76:79], v[138:141], v[214:217], v[76:79]
	v_mfma_f32_16x16x32_bf16 v[72:75], v[150:153], v[214:217], v[72:75]
	v_mfma_f32_16x16x32_bf16 v[124:127], v[146:149], v[194:197], v[124:127]
	v_mfma_f32_16x16x32_bf16 v[120:123], v[154:157], v[194:197], v[120:123]
	v_mfma_f32_16x16x32_bf16 v[108:111], v[146:149], v[202:205], v[108:111]
	v_mfma_f32_16x16x32_bf16 v[104:107], v[154:157], v[202:205], v[104:107]
	v_mfma_f32_16x16x32_bf16 v[92:95], v[146:149], v[210:213], v[92:95]
	v_mfma_f32_16x16x32_bf16 v[88:91], v[154:157], v[210:213], v[88:91]
	v_mfma_f32_16x16x32_bf16 v[76:79], v[146:149], v[238:241], v[76:79]
	v_mfma_f32_16x16x32_bf16 v[72:75], v[154:157], v[238:241], v[72:75]
	v_mfma_f32_16x16x32_bf16 v[116:119], v[174:177], v[190:193], v[116:119]
	v_mfma_f32_16x16x32_bf16 v[112:115], v[182:185], v[190:193], v[112:115]
	v_mfma_f32_16x16x32_bf16 v[100:103], v[174:177], v[198:201], v[100:103]
	v_mfma_f32_16x16x32_bf16 v[96:99], v[182:185], v[198:201], v[96:99]
	v_mfma_f32_16x16x32_bf16 v[84:87], v[174:177], v[206:209], v[84:87]
	v_mfma_f32_16x16x32_bf16 v[80:83], v[182:185], v[206:209], v[80:83]
	v_mfma_f32_16x16x32_bf16 v[68:71], v[174:177], v[214:217], v[68:71]
	v_mfma_f32_16x16x32_bf16 v[64:67], v[182:185], v[214:217], v[64:67]
	v_mfma_f32_16x16x32_bf16 v[116:119], v[178:181], v[194:197], v[116:119]
	v_mfma_f32_16x16x32_bf16 v[112:115], v[186:189], v[194:197], v[112:115]
	v_mfma_f32_16x16x32_bf16 v[100:103], v[178:181], v[202:205], v[100:103]
	v_mfma_f32_16x16x32_bf16 v[96:99], v[186:189], v[202:205], v[96:99]
	v_mfma_f32_16x16x32_bf16 v[84:87], v[178:181], v[210:213], v[84:87]
	v_mfma_f32_16x16x32_bf16 v[80:83], v[186:189], v[210:213], v[80:83]
	v_mfma_f32_16x16x32_bf16 v[68:71], v[178:181], v[238:241], v[68:71]
	v_mfma_f32_16x16x32_bf16 v[64:67], v[186:189], v[238:241], v[64:67]
	s_barrier
	s_add_i32 s8, s48, s28
	v_lshl_add_u64 v[158:159], v[158:159], 0, s[88:89]
	s_mov_b32 m0, s8
	ds_read_b128 v[190:193], v145 offset:49152
	ds_read_b128 v[194:197], v145 offset:50176
	ds_read_b128 v[198:201], v145 offset:51200
	ds_read_b128 v[202:205], v145 offset:52224
	ds_read_b128 v[206:209], v145 offset:53248
	ds_read_b128 v[210:213], v145 offset:54272
	ds_read_b128 v[214:217], v145 offset:55296
	ds_read_b128 v[238:241], v145 offset:56320
	global_load_lds_dwordx4 v[158:159], off
	s_add_i32 m0, s8, 0x2000
	s_add_u32 s8, s12, 0xb0080
	v_lshl_add_u64 v[158:159], v[162:163], 0, s[88:89]
	s_addc_u32 s9, s13, 0
	s_add_i32 s12, s49, s28
	global_load_lds_dwordx4 v[158:159], off
	v_lshl_add_u64 v[158:159], s[8:9], 0, v[160:161]
	s_mov_b32 m0, s12
	s_nop 0
	global_load_lds_dwordx4 v[158:159], off
	v_lshl_add_u64 v[158:159], s[8:9], 0, v[132:133]
	s_add_i32 m0, s12, 0x2000
	s_nop 0
	global_load_lds_dwordx4 v[158:159], off
	v_lshl_add_u64 v[158:159], v[164:165], 0, s[88:89]
	s_mov_b32 m0, s34
	s_nop 0
	global_load_lds_dwordx4 v[158:159], off
	v_lshl_add_u64 v[158:159], v[166:167], 0, s[88:89]
	s_mov_b32 m0, s35
	s_nop 0
	global_load_lds_dwordx4 v[158:159], off
	s_waitcnt vmcnt(8)
	s_waitcnt lgkmcnt(0)
	s_barrier
	s_waitcnt lgkmcnt(0)
	v_mfma_f32_16x16x32_bf16 v[60:63], v[138:141], v[190:193], v[60:63]
	v_mfma_f32_16x16x32_bf16 v[56:59], v[150:153], v[190:193], v[56:59]
	v_mfma_f32_16x16x32_bf16 v[44:47], v[138:141], v[198:201], v[44:47]
	v_mfma_f32_16x16x32_bf16 v[40:43], v[150:153], v[198:201], v[40:43]
	v_mfma_f32_16x16x32_bf16 v[28:31], v[138:141], v[206:209], v[28:31]
	v_mfma_f32_16x16x32_bf16 v[24:27], v[150:153], v[206:209], v[24:27]
	v_mfma_f32_16x16x32_bf16 v[12:15], v[138:141], v[214:217], v[12:15]
	v_mfma_f32_16x16x32_bf16 v[8:11], v[150:153], v[214:217], v[8:11]
	v_mfma_f32_16x16x32_bf16 v[60:63], v[146:149], v[194:197], v[60:63]
	v_mfma_f32_16x16x32_bf16 v[56:59], v[154:157], v[194:197], v[56:59]
	v_mfma_f32_16x16x32_bf16 v[44:47], v[146:149], v[202:205], v[44:47]
	v_mfma_f32_16x16x32_bf16 v[40:43], v[154:157], v[202:205], v[40:43]
	v_mfma_f32_16x16x32_bf16 v[28:31], v[146:149], v[210:213], v[28:31]
	v_mfma_f32_16x16x32_bf16 v[24:27], v[154:157], v[210:213], v[24:27]
	v_mfma_f32_16x16x32_bf16 v[12:15], v[146:149], v[238:241], v[12:15]
	v_mfma_f32_16x16x32_bf16 v[8:11], v[154:157], v[238:241], v[8:11]
	v_mfma_f32_16x16x32_bf16 v[52:55], v[174:177], v[190:193], v[52:55]
	v_mfma_f32_16x16x32_bf16 v[48:51], v[182:185], v[190:193], v[48:51]
	v_mfma_f32_16x16x32_bf16 v[36:39], v[174:177], v[198:201], v[36:39]
	v_mfma_f32_16x16x32_bf16 v[32:35], v[182:185], v[198:201], v[32:35]
	v_mfma_f32_16x16x32_bf16 v[20:23], v[174:177], v[206:209], v[20:23]
	v_mfma_f32_16x16x32_bf16 v[16:19], v[182:185], v[206:209], v[16:19]
	v_mfma_f32_16x16x32_bf16 v[4:7], v[174:177], v[214:217], v[4:7]
	v_mfma_f32_16x16x32_bf16 v[0:3], v[182:185], v[214:217], v[0:3]
	v_mfma_f32_16x16x32_bf16 v[52:55], v[178:181], v[194:197], v[52:55]
	v_mfma_f32_16x16x32_bf16 v[48:51], v[186:189], v[194:197], v[48:51]
	v_mfma_f32_16x16x32_bf16 v[36:39], v[178:181], v[202:205], v[36:39]
	v_mfma_f32_16x16x32_bf16 v[32:35], v[186:189], v[202:205], v[32:35]
	v_mfma_f32_16x16x32_bf16 v[20:23], v[178:181], v[210:213], v[20:23]
	v_mfma_f32_16x16x32_bf16 v[16:19], v[186:189], v[210:213], v[16:19]
	v_mfma_f32_16x16x32_bf16 v[4:7], v[178:181], v[238:241], v[4:7]
	v_mfma_f32_16x16x32_bf16 v[0:3], v[186:189], v[238:241], v[0:3]
	s_barrier
	s_add_i32 s22, s22, 2
	s_add_u32 s21, s21, 0x100
	s_addc_u32 s92, s92, 0
	s_cmp_gt_u32 s22, 41
	s_mov_b64 s[8:9], s[10:11]
	s_cbranch_scc0 .LBB0_439
	v_lshl_add_u32 v140, s20, 8, v142
	v_lshl_or_b32 v138, s91, 8, v144
	v_lshlrev_b32_e32 v141, 11, v140
	v_lshl_add_u32 v138, v138, 1, v141
	v_lshlrev_b32_e32 v139, 3, v140
	s_mov_b64 s[8:9], s[4:5]
	global_load_dwordx4 v[146:149], v138, s[8:9]
	global_load_dwordx4 v[150:153], v138, s[8:9] offset:256
	s_add_u32 s8, s8, 0x8000
	s_addc_u32 s9, s9, 0
	global_load_dwordx4 v[154:157], v138, s[8:9]
	global_load_dwordx4 v[162:165], v138, s[8:9] offset:256
	s_add_u32 s8, s8, 0x8000
	s_addc_u32 s9, s9, 0
	global_load_dwordx4 v[166:169], v138, s[8:9]
	global_load_dwordx4 v[174:177], v138, s[8:9] offset:256
	s_add_u32 s8, s8, 0x8000
	s_addc_u32 s9, s9, 0
	global_load_dwordx4 v[178:181], v138, s[8:9]
	global_load_dwordx4 v[182:185], v138, s[8:9] offset:256
	s_add_u32 s8, s8, 0x28000
	s_addc_u32 s9, s9, 0
	global_load_dwordx4 v[186:189], v138, s[8:9]
	global_load_dwordx4 v[190:193], v138, s[8:9] offset:256
	s_add_u32 s8, s8, 0x8000
	s_addc_u32 s9, s9, 0
	global_load_dwordx4 v[194:197], v138, s[8:9]
	global_load_dwordx4 v[198:201], v138, s[8:9] offset:256
	s_add_u32 s8, s8, 0x8000
	s_addc_u32 s9, s9, 0
	global_load_dwordx4 v[202:205], v138, s[8:9]
	global_load_dwordx4 v[206:209], v138, s[8:9] offset:256
	s_add_u32 s8, s8, 0x8000
	s_addc_u32 s9, s9, 0
	global_load_dwordx4 v[210:213], v138, s[8:9]
	global_load_dwordx4 v[214:217], v138, s[8:9] offset:256
	s_and_b64 vcc, exec, s[36:37]
	s_cbranch_vccz .LBB0_442
	s_barrier

.LBB0_474:
	s_add_u32 s12, s10, 0xfffc0080
	s_addc_u32 s13, s11, -1
	s_add_i32 s22, 0, 0x10000
	s_cmp_eq_u32 s21, 12
	s_cselect_b32 s15, s20, s13
	s_cselect_b32 s14, s37, s12
	s_cselect_b32 s13, s41, s93
	s_cselect_b32 s12, s91, s92
	s_add_i32 s48, 0, 0x14000
	v_add_u32_e32 v154, s22, v147
	v_add_u32_e32 v158, s48, v147
	ds_read_b128 v[138:141], v154
	ds_read_b128 v[142:145], v154 offset:1024
	ds_read_b128 v[150:153], v154 offset:2048
	ds_read_b128 v[154:157], v154 offset:3072
	ds_read_b128 v[174:177], v158
	ds_read_b128 v[178:181], v158 offset:1024
	ds_read_b128 v[182:185], v158 offset:2048
	ds_read_b128 v[186:189], v158 offset:3072
	v_lshl_add_u64 v[158:159], s[10:11], 0, v[136:137]
	s_add_i32 m0, s30, 0xc000
	ds_read_b128 v[190:193], v149
	ds_read_b128 v[194:197], v149 offset:1024
	ds_read_b128 v[198:201], v149 offset:2048
	ds_read_b128 v[202:205], v149 offset:3072
	ds_read_b128 v[206:209], v149 offset:4096
	ds_read_b128 v[210:213], v149 offset:5120
	ds_read_b128 v[214:217], v149 offset:6144
	ds_read_b128 v[238:241], v149 offset:7168
	global_load_lds_dwordx4 v[158:159], off
	v_lshl_add_u64 v[158:159], s[10:11], 0, v[134:135]
	s_add_i32 m0, s30, 0xe000
	s_nop 0
	global_load_lds_dwordx4 v[158:159], off
	s_waitcnt vmcnt(8)
	s_waitcnt lgkmcnt(0)
	s_barrier
	s_waitcnt lgkmcnt(0)
	v_mfma_f32_16x16x32_bf16 v[124:127], v[138:141], v[190:193], v[124:127]
	v_mfma_f32_16x16x32_bf16 v[116:119], v[150:153], v[190:193], v[116:119]
	v_mfma_f32_16x16x32_bf16 v[108:111], v[138:141], v[198:201], v[108:111]
	v_mfma_f32_16x16x32_bf16 v[100:103], v[150:153], v[198:201], v[100:103]
	v_mfma_f32_16x16x32_bf16 v[92:95], v[138:141], v[206:209], v[92:95]
	v_mfma_f32_16x16x32_bf16 v[84:87], v[150:153], v[206:209], v[84:87]
	v_mfma_f32_16x16x32_bf16 v[76:79], v[138:141], v[214:217], v[76:79]
	v_mfma_f32_16x16x32_bf16 v[64:67], v[150:153], v[214:217], v[64:67]
	v_mfma_f32_16x16x32_bf16 v[124:127], v[142:145], v[194:197], v[124:127]
	v_mfma_f32_16x16x32_bf16 v[116:119], v[154:157], v[194:197], v[116:119]
	v_mfma_f32_16x16x32_bf16 v[108:111], v[142:145], v[202:205], v[108:111]
	v_mfma_f32_16x16x32_bf16 v[100:103], v[154:157], v[202:205], v[100:103]
	v_mfma_f32_16x16x32_bf16 v[92:95], v[142:145], v[210:213], v[92:95]
	v_mfma_f32_16x16x32_bf16 v[84:87], v[154:157], v[210:213], v[84:87]
	v_mfma_f32_16x16x32_bf16 v[76:79], v[142:145], v[238:241], v[76:79]
	v_mfma_f32_16x16x32_bf16 v[64:67], v[154:157], v[238:241], v[64:67]
	v_mfma_f32_16x16x32_bf16 v[120:123], v[174:177], v[190:193], v[120:123]
	v_mfma_f32_16x16x32_bf16 v[112:115], v[182:185], v[190:193], v[112:115]
	v_mfma_f32_16x16x32_bf16 v[104:107], v[174:177], v[198:201], v[104:107]
	v_mfma_f32_16x16x32_bf16 v[96:99], v[182:185], v[198:201], v[96:99]
	v_mfma_f32_16x16x32_bf16 v[88:91], v[174:177], v[206:209], v[88:91]
	v_mfma_f32_16x16x32_bf16 v[80:83], v[182:185], v[206:209], v[80:83]
	v_mfma_f32_16x16x32_bf16 v[72:75], v[174:177], v[214:217], v[72:75]
	v_mfma_f32_16x16x32_bf16 v[68:71], v[182:185], v[214:217], v[68:71]
	v_mfma_f32_16x16x32_bf16 v[120:123], v[178:181], v[194:197], v[120:123]
	v_mfma_f32_16x16x32_bf16 v[112:115], v[186:189], v[194:197], v[112:115]
	v_mfma_f32_16x16x32_bf16 v[104:107], v[178:181], v[202:205], v[104:107]
	v_mfma_f32_16x16x32_bf16 v[96:99], v[186:189], v[202:205], v[96:99]
	v_mfma_f32_16x16x32_bf16 v[88:91], v[178:181], v[210:213], v[88:91]
	v_mfma_f32_16x16x32_bf16 v[80:83], v[186:189], v[210:213], v[80:83]
	v_mfma_f32_16x16x32_bf16 v[72:75], v[178:181], v[238:241], v[72:75]
	v_mfma_f32_16x16x32_bf16 v[68:71], v[186:189], v[238:241], v[68:71]
	s_barrier
	s_add_i32 s22, s22, s28
	v_lshl_add_u64 v[158:159], s[12:13], 0, v[160:161]
	s_mov_b32 m0, s22
	ds_read_b128 v[190:193], v149 offset:16384
	ds_read_b128 v[194:197], v149 offset:17408
	ds_read_b128 v[198:201], v149 offset:18432
	ds_read_b128 v[202:205], v149 offset:19456
	ds_read_b128 v[206:209], v149 offset:20480
	ds_read_b128 v[210:213], v149 offset:21504
	ds_read_b128 v[214:217], v149 offset:22528
	ds_read_b128 v[238:241], v149 offset:23552
	global_load_lds_dwordx4 v[158:159], off
	s_add_i32 m0, s22, 0x2000
	s_add_u32 s96, s12, 0x40000
	v_lshl_add_u64 v[162:163], s[12:13], 0, v[128:129]
	s_addc_u32 s97, s13, 0
	s_add_i32 s22, s48, s28
	global_load_lds_dwordx4 v[162:163], off
	v_lshl_add_u64 v[164:165], s[96:97], 0, v[160:161]
	s_mov_b32 m0, s22
	v_lshl_add_u64 v[166:167], s[14:15], 0, v[130:131]
	global_load_lds_dwordx4 v[164:165], off
	v_lshl_add_u64 v[164:165], s[96:97], 0, v[128:129]
	s_add_i32 m0, s22, 0x2000
	s_nop 0
	global_load_lds_dwordx4 v[164:165], off
	v_lshl_add_u64 v[164:165], s[14:15], 0, v[132:133]
	s_mov_b32 m0, s30
	s_nop 0
	global_load_lds_dwordx4 v[164:165], off
	s_mov_b32 m0, s31
	s_nop 0
	global_load_lds_dwordx4 v[166:167], off
	s_waitcnt vmcnt(8)
	s_waitcnt lgkmcnt(0)
	s_barrier
	s_waitcnt lgkmcnt(0)
	v_mfma_f32_16x16x32_bf16 v[60:63], v[138:141], v[190:193], v[60:63]
	v_mfma_f32_16x16x32_bf16 v[48:51], v[150:153], v[190:193], v[48:51]
	v_mfma_f32_16x16x32_bf16 v[44:47], v[138:141], v[198:201], v[44:47]
	v_mfma_f32_16x16x32_bf16 v[32:35], v[150:153], v[198:201], v[32:35]
	v_mfma_f32_16x16x32_bf16 v[28:31], v[138:141], v[206:209], v[28:31]
	v_mfma_f32_16x16x32_bf16 v[16:19], v[150:153], v[206:209], v[16:19]
	v_mfma_f32_16x16x32_bf16 v[12:15], v[138:141], v[214:217], v[12:15]
	v_mfma_f32_16x16x32_bf16 v[0:3], v[150:153], v[214:217], v[0:3]
	v_mfma_f32_16x16x32_bf16 v[60:63], v[142:145], v[194:197], v[60:63]
	v_mfma_f32_16x16x32_bf16 v[48:51], v[154:157], v[194:197], v[48:51]
	v_mfma_f32_16x16x32_bf16 v[44:47], v[142:145], v[202:205], v[44:47]
	v_mfma_f32_16x16x32_bf16 v[32:35], v[154:157], v[202:205], v[32:35]
	v_mfma_f32_16x16x32_bf16 v[28:31], v[142:145], v[210:213], v[28:31]
	v_mfma_f32_16x16x32_bf16 v[16:19], v[154:157], v[210:213], v[16:19]
	v_mfma_f32_16x16x32_bf16 v[12:15], v[142:145], v[238:241], v[12:15]
	v_mfma_f32_16x16x32_bf16 v[0:3], v[154:157], v[238:241], v[0:3]
	v_mfma_f32_16x16x32_bf16 v[56:59], v[174:177], v[190:193], v[56:59]
	v_mfma_f32_16x16x32_bf16 v[52:55], v[182:185], v[190:193], v[52:55]
	v_mfma_f32_16x16x32_bf16 v[40:43], v[174:177], v[198:201], v[40:43]
	v_mfma_f32_16x16x32_bf16 v[36:39], v[182:185], v[198:201], v[36:39]
	v_mfma_f32_16x16x32_bf16 v[24:27], v[174:177], v[206:209], v[24:27]
	v_mfma_f32_16x16x32_bf16 v[20:23], v[182:185], v[206:209], v[20:23]
	v_mfma_f32_16x16x32_bf16 v[8:11], v[174:177], v[214:217], v[8:11]
	v_mfma_f32_16x16x32_bf16 v[4:7], v[182:185], v[214:217], v[4:7]
	v_mfma_f32_16x16x32_bf16 v[56:59], v[178:181], v[194:197], v[56:59]
	v_mfma_f32_16x16x32_bf16 v[52:55], v[186:189], v[194:197], v[52:55]
	v_mfma_f32_16x16x32_bf16 v[40:43], v[178:181], v[202:205], v[40:43]
	v_mfma_f32_16x16x32_bf16 v[36:39], v[186:189], v[202:205], v[36:39]
	v_mfma_f32_16x16x32_bf16 v[24:27], v[178:181], v[210:213], v[24:27]
	v_mfma_f32_16x16x32_bf16 v[20:23], v[186:189], v[210:213], v[20:23]
	v_mfma_f32_16x16x32_bf16 v[8:11], v[178:181], v[238:241], v[8:11]
	v_mfma_f32_16x16x32_bf16 v[4:7], v[186:189], v[238:241], v[4:7]
	s_barrier
	s_add_i32 s22, 0, 0x18000
	s_add_i32 s48, 0, 0x1c000
	v_add_u32_e32 v154, s22, v147
	v_add_u32_e32 v168, s48, v147
	ds_read_b128 v[138:141], v154
	ds_read_b128 v[142:145], v154 offset:1024
	ds_read_b128 v[150:153], v154 offset:2048
	ds_read_b128 v[154:157], v154 offset:3072
	ds_read_b128 v[174:177], v168
	ds_read_b128 v[178:181], v168 offset:1024
	ds_read_b128 v[182:185], v168 offset:2048
	ds_read_b128 v[186:189], v168 offset:3072
	s_add_u32 s14, s14, 0x40000
	s_addc_u32 s15, s15, 0
	s_mov_b32 m0, s33
	v_lshl_add_u64 v[168:169], s[14:15], 0, v[132:133]
	ds_read_b128 v[190:193], v149 offset:32768
	ds_read_b128 v[194:197], v149 offset:33792
	ds_read_b128 v[198:201], v149 offset:34816
	ds_read_b128 v[202:205], v149 offset:35840
	ds_read_b128 v[206:209], v149 offset:36864
	ds_read_b128 v[210:213], v149 offset:37888
	ds_read_b128 v[214:217], v149 offset:38912
	ds_read_b128 v[238:241], v149 offset:39936
	global_load_lds_dwordx4 v[168:169], off
	v_lshl_add_u64 v[168:169], s[14:15], 0, v[130:131]
	s_mov_b32 m0, s34
	s_nop 0
	global_load_lds_dwordx4 v[168:169], off
	s_waitcnt vmcnt(8)
	s_waitcnt lgkmcnt(0)
	s_barrier
	s_waitcnt lgkmcnt(0)
	v_mfma_f32_16x16x32_bf16 v[124:127], v[138:141], v[190:193], v[124:127]
	v_mfma_f32_16x16x32_bf16 v[116:119], v[150:153], v[190:193], v[116:119]
	v_mfma_f32_16x16x32_bf16 v[108:111], v[138:141], v[198:201], v[108:111]
	v_mfma_f32_16x16x32_bf16 v[100:103], v[150:153], v[198:201], v[100:103]
	v_mfma_f32_16x16x32_bf16 v[92:95], v[138:141], v[206:209], v[92:95]
	v_mfma_f32_16x16x32_bf16 v[84:87], v[150:153], v[206:209], v[84:87]
	v_mfma_f32_16x16x32_bf16 v[76:79], v[138:141], v[214:217], v[76:79]
	v_mfma_f32_16x16x32_bf16 v[64:67], v[150:153], v[214:217], v[64:67]
	v_mfma_f32_16x16x32_bf16 v[124:127], v[142:145], v[194:197], v[124:127]
	v_mfma_f32_16x16x32_bf16 v[116:119], v[154:157], v[194:197], v[116:119]
	v_mfma_f32_16x16x32_bf16 v[108:111], v[142:145], v[202:205], v[108:111]
	v_mfma_f32_16x16x32_bf16 v[100:103], v[154:157], v[202:205], v[100:103]
	v_mfma_f32_16x16x32_bf16 v[92:95], v[142:145], v[210:213], v[92:95]
	v_mfma_f32_16x16x32_bf16 v[84:87], v[154:157], v[210:213], v[84:87]
	v_mfma_f32_16x16x32_bf16 v[76:79], v[142:145], v[238:241], v[76:79]
	v_mfma_f32_16x16x32_bf16 v[64:67], v[154:157], v[238:241], v[64:67]
	v_mfma_f32_16x16x32_bf16 v[120:123], v[174:177], v[190:193], v[120:123]
	v_mfma_f32_16x16x32_bf16 v[112:115], v[182:185], v[190:193], v[112:115]
	v_mfma_f32_16x16x32_bf16 v[104:107], v[174:177], v[198:201], v[104:107]
	v_mfma_f32_16x16x32_bf16 v[96:99], v[182:185], v[198:201], v[96:99]
	v_mfma_f32_16x16x32_bf16 v[88:91], v[174:177], v[206:209], v[88:91]
	v_mfma_f32_16x16x32_bf16 v[80:83], v[182:185], v[206:209], v[80:83]
	v_mfma_f32_16x16x32_bf16 v[72:75], v[174:177], v[214:217], v[72:75]
	v_mfma_f32_16x16x32_bf16 v[68:71], v[182:185], v[214:217], v[68:71]
	v_mfma_f32_16x16x32_bf16 v[120:123], v[178:181], v[194:197], v[120:123]
	v_mfma_f32_16x16x32_bf16 v[112:115], v[186:189], v[194:197], v[112:115]
	v_mfma_f32_16x16x32_bf16 v[104:107], v[178:181], v[202:205], v[104:107]
	v_mfma_f32_16x16x32_bf16 v[96:99], v[186:189], v[202:205], v[96:99]
	v_mfma_f32_16x16x32_bf16 v[88:91], v[178:181], v[210:213], v[88:91]
	v_mfma_f32_16x16x32_bf16 v[80:83], v[186:189], v[210:213], v[80:83]
	v_mfma_f32_16x16x32_bf16 v[72:75], v[178:181], v[238:241], v[72:75]
	v_mfma_f32_16x16x32_bf16 v[68:71], v[186:189], v[238:241], v[68:71]
	s_barrier
	s_add_i32 s14, s22, s28
	v_lshl_add_u64 v[158:159], v[158:159], 0, s[88:89]
	s_mov_b32 m0, s14
	ds_read_b128 v[190:193], v149 offset:49152
	ds_read_b128 v[194:197], v149 offset:50176
	ds_read_b128 v[198:201], v149 offset:51200
	ds_read_b128 v[202:205], v149 offset:52224
	ds_read_b128 v[206:209], v149 offset:53248
	ds_read_b128 v[210:213], v149 offset:54272
	ds_read_b128 v[214:217], v149 offset:55296
	ds_read_b128 v[238:241], v149 offset:56320
	global_load_lds_dwordx4 v[158:159], off
	s_add_i32 m0, s14, 0x2000
	s_add_u32 s12, s12, 0x40080
	v_lshl_add_u64 v[158:159], v[162:163], 0, s[88:89]
	s_addc_u32 s13, s13, 0
	s_add_i32 s14, s48, s28
	global_load_lds_dwordx4 v[158:159], off
	v_lshl_add_u64 v[158:159], s[12:13], 0, v[160:161]
	s_mov_b32 m0, s14
	s_nop 0
	global_load_lds_dwordx4 v[158:159], off
	v_lshl_add_u64 v[158:159], s[12:13], 0, v[128:129]
	s_add_i32 m0, s14, 0x2000
	s_nop 0
	global_load_lds_dwordx4 v[158:159], off
	v_lshl_add_u64 v[158:159], v[164:165], 0, s[88:89]
	s_mov_b32 m0, s35
	s_nop 0
	global_load_lds_dwordx4 v[158:159], off
	v_lshl_add_u64 v[158:159], v[166:167], 0, s[88:89]
	s_mov_b32 m0, s90
	s_nop 0
	global_load_lds_dwordx4 v[158:159], off
	s_waitcnt vmcnt(8)
	s_waitcnt lgkmcnt(0)
	s_barrier
	s_waitcnt lgkmcnt(0)
	v_mfma_f32_16x16x32_bf16 v[60:63], v[138:141], v[190:193], v[60:63]
	v_mfma_f32_16x16x32_bf16 v[48:51], v[150:153], v[190:193], v[48:51]
	v_mfma_f32_16x16x32_bf16 v[44:47], v[138:141], v[198:201], v[44:47]
	v_mfma_f32_16x16x32_bf16 v[32:35], v[150:153], v[198:201], v[32:35]
	v_mfma_f32_16x16x32_bf16 v[28:31], v[138:141], v[206:209], v[28:31]
	v_mfma_f32_16x16x32_bf16 v[16:19], v[150:153], v[206:209], v[16:19]
	v_mfma_f32_16x16x32_bf16 v[12:15], v[138:141], v[214:217], v[12:15]
	v_mfma_f32_16x16x32_bf16 v[0:3], v[150:153], v[214:217], v[0:3]
	v_mfma_f32_16x16x32_bf16 v[60:63], v[142:145], v[194:197], v[60:63]
	v_mfma_f32_16x16x32_bf16 v[48:51], v[154:157], v[194:197], v[48:51]
	v_mfma_f32_16x16x32_bf16 v[44:47], v[142:145], v[202:205], v[44:47]
	v_mfma_f32_16x16x32_bf16 v[32:35], v[154:157], v[202:205], v[32:35]
	v_mfma_f32_16x16x32_bf16 v[28:31], v[142:145], v[210:213], v[28:31]
	v_mfma_f32_16x16x32_bf16 v[16:19], v[154:157], v[210:213], v[16:19]
	v_mfma_f32_16x16x32_bf16 v[12:15], v[142:145], v[238:241], v[12:15]
	v_mfma_f32_16x16x32_bf16 v[0:3], v[154:157], v[238:241], v[0:3]
	v_mfma_f32_16x16x32_bf16 v[56:59], v[174:177], v[190:193], v[56:59]
	v_mfma_f32_16x16x32_bf16 v[52:55], v[182:185], v[190:193], v[52:55]
	v_mfma_f32_16x16x32_bf16 v[40:43], v[174:177], v[198:201], v[40:43]
	v_mfma_f32_16x16x32_bf16 v[36:39], v[182:185], v[198:201], v[36:39]
	v_mfma_f32_16x16x32_bf16 v[24:27], v[174:177], v[206:209], v[24:27]
	v_mfma_f32_16x16x32_bf16 v[20:23], v[182:185], v[206:209], v[20:23]
	v_mfma_f32_16x16x32_bf16 v[8:11], v[174:177], v[214:217], v[8:11]
	v_mfma_f32_16x16x32_bf16 v[4:7], v[182:185], v[214:217], v[4:7]
	v_mfma_f32_16x16x32_bf16 v[56:59], v[178:181], v[194:197], v[56:59]
	v_mfma_f32_16x16x32_bf16 v[52:55], v[186:189], v[194:197], v[52:55]
	v_mfma_f32_16x16x32_bf16 v[40:43], v[178:181], v[202:205], v[40:43]
	v_mfma_f32_16x16x32_bf16 v[36:39], v[186:189], v[202:205], v[36:39]
	v_mfma_f32_16x16x32_bf16 v[24:27], v[178:181], v[210:213], v[24:27]
	v_mfma_f32_16x16x32_bf16 v[20:23], v[186:189], v[210:213], v[20:23]
	v_mfma_f32_16x16x32_bf16 v[8:11], v[178:181], v[238:241], v[8:11]
	v_mfma_f32_16x16x32_bf16 v[4:7], v[186:189], v[238:241], v[4:7]
	s_barrier
	s_add_i32 s21, s21, 2
	s_add_u32 s92, s92, 0x100
	s_addc_u32 s93, s93, 0
	s_add_u32 s10, s10, 0x100
	s_addc_u32 s11, s11, 0
	s_cmp_gt_u32 s21, 13
	s_cbranch_scc0 .LBB0_474
	v_lshl_add_u32 v192, s8, 8, v146
	v_lshlrev_b32_e32 v192, 3, v192
	global_load_dwordx2 v[176:177], v192, s[4:5]
	global_load_dwordx2 v[178:179], v192, s[4:5] offset:128
	global_load_dwordx2 v[180:181], v192, s[4:5] offset:256
	global_load_dwordx2 v[182:183], v192, s[4:5] offset:384
	global_load_dwordx2 v[184:185], v192, s[4:5] offset:1024
	global_load_dwordx2 v[186:187], v192, s[4:5] offset:1152
	global_load_dwordx2 v[188:189], v192, s[4:5] offset:1280
	global_load_dwordx2 v[190:191], v192, s[4:5] offset:1408
	s_and_b64 vcc, exec, s[6:7]
	s_cbranch_vccz .LBB0_477
	s_barrier
